# GEMM loop edges: pointer bumps and loop test moved before the closing barrier, LDS fragment reads issued first at the loop head ahead of the scalar address selects
# speedup vs baseline: 1.0063x; 1.0063x over previous
; #define PG8_STAGE(bufoff, gbase, voff) do { _Pragma("unroll") for (int _i = 0; _i < 2; ++_i) \
;         __builtin_amdgcn_global_load_lds((const unsigned*)((const char*)(gbase) + (voff)[_i]), (PG8_LAS unsigned*)(lds + (bufoff) + ldsw + _i * 8192), 16, 0, 0); } while (0)
; #define PG8_LDA(dst, b, h) do { _Pragma("unroll") for (int m = 0; m < 4; ++m) _Pragma("unroll") for (int k = 0; k < 2; ++k) dst[m][k] = *(const PG8_LAS bf16x8*)(lds + PG8_SA(b, h) + aoff + m * 2048 + k * 1024); } while (0)
; #define PG8_LDB(dst, b, h) do { _Pragma("unroll") for (int n = 0; n < 2; ++n) _Pragma("unroll") for (int k = 0; k < 2; ++k) dst[n][k] = *(const PG8_LAS bf16x8*)(lds + PG8_SB(b, h) + boff + n * 2048 + k * 1024); } while (0)
; #define PG8_MMA(ai, bj, At, Bt) do { __builtin_amdgcn_s_setprio(1); _Pragma("unroll") for (int m = 0; m < 4; ++m) _Pragma("unroll") for (int n = 0; n < 2; ++n) _Pragma("unroll") for (int k = 0; k < 2; ++k) \
;         acc[ai][bj][m][n] = __builtin_amdgcn_mfma_f32_16x16x32_bf16(Bt[n][k], At[m][k], acc[ai][bj][m][n], 0, 0, 0); __builtin_amdgcn_s_setprio(0); } while (0)
; #define PG8_WAIT_V(n) asm volatile("s_waitcnt vmcnt(" #n ")" ::: "memory")
; #define PG8_BAR __builtin_amdgcn_s_barrier()
; template <class Epi, class Sched, bool ALIGN_EPI = false, bool SP2 = false>
; __device__ __forceinline__ void gemm_phase(PG8_LAS unsigned char* lds, const Gemm g, const Sched& S, const Epi& E) {
;     ...
;         for (int t = 0; t < nt; t += 2) {
;             const bool last = (t == nt - 2);
;             const char* a1 = cA + (size_t)(t + 1) * kstep;
;             const char* a2 = last ? nA : cA + (size_t)(t + 2) * kstep; const char* b2 = last ? nB : cB + (size_t)(t + 2) * kstep;
;             const char* a3 = a2 + kstep; const char* b3 = b2 + kstep;
;             if (last && has_next) S.a_ready(nxt);
;             if constexpr (SP2) {
;             PG8_LDB(B0, 0, 0); PG8_LDB(B1, 0, 1); PG8_SCHED; PG8_LDA(At, 0, 0); PG8_STAGE(PG8_SA(1, 1), a1 + hstep, voffA);
;             PG8_WAIT_V(8); PG8_WAIT_L(0); PG8_BAR; PG8_MMA(0, 0, At, B0); PG8_MMA(0, 1, At, B1); PG8_BAR; PG8_SCHED;
;             PG8_LDA(At, 0, 1); PG8_STAGE(PG8_SB(0, 0), b2, voffB); PG8_STAGE(PG8_SB(0, 1), b2 + hstep, voffB); PG8_STAGE(PG8_SA(0, 0), a2, voffA);
;             PG8_WAIT_V(8); PG8_WAIT_L(0); PG8_BAR; PG8_MMA(1, 0, At, B0); PG8_MMA(1, 1, At, B1); PG8_BAR; PG8_SCHED;
.LBB0_38:
	ds_read_b128 v[176:179], v143
	ds_read_b128 v[180:183], v143 offset:1024
	ds_read_b128 v[194:197], v143 offset:2048
	ds_read_b128 v[198:201], v143 offset:3072
	ds_read_b128 v[202:205], v143 offset:4096
	ds_read_b128 v[206:209], v143 offset:5120
	ds_read_b128 v[220:223], v143 offset:6144
	ds_read_b128 v[224:227], v143 offset:7168
	s_add_i32 s25, s33, 0x100
	v_add_u32_e32 v2, s25, v142
	ds_read_b128 v[144:147], v2
	ds_read_b128 v[148:151], v2 offset:1024
	ds_read_b128 v[152:155], v2 offset:2048
	ds_read_b128 v[156:159], v2 offset:3072
	s_add_i32 s19, s18, 2
	s_add_u32 s20, s38, 0x80
	s_addc_u32 s23, s39, 0
	s_cmp_eq_u32 s97, s18
	s_cselect_b32 s51, s43, s23
	s_cselect_b32 s50, s42, s20
	s_cselect_b32 s27, s61, s15
	s_cselect_b32 s26, s60, s12
	s_add_i32 s18, s21, 0x100
	v_add_u32_e32 v2, s18, v142
	ds_read_b128 v[160:163], v2
	ds_read_b128 v[164:167], v2 offset:1024
	ds_read_b128 v[168:171], v2 offset:2048
	ds_read_b128 v[172:175], v2 offset:3072
	v_lshl_add_u64 v[210:211], s[38:39], 0, v[140:141]
	s_add_i32 m0, s70, 0xc000
	global_load_lds_dwordx4 v[210:211], off
	v_lshl_add_u64 v[210:211], s[38:39], 0, v[138:139]
	s_add_i32 m0, s70, 0xe000
	s_nop 0
	global_load_lds_dwordx4 v[210:211], off
	s_waitcnt vmcnt(8)
	s_waitcnt lgkmcnt(0)
	s_barrier
	s_setprio 1
	s_waitcnt lgkmcnt(0)
	v_mfma_f32_16x16x32_bf16 v[128:131], v[144:147], v[176:179], v[128:131]
	v_mfma_f32_16x16x32_bf16 v[120:123], v[152:155], v[176:179], v[120:123]
	v_mfma_f32_16x16x32_bf16 v[112:115], v[144:147], v[194:197], v[112:115]
	v_mfma_f32_16x16x32_bf16 v[104:107], v[152:155], v[194:197], v[104:107]
	v_mfma_f32_16x16x32_bf16 v[96:99], v[144:147], v[202:205], v[96:99]
	v_mfma_f32_16x16x32_bf16 v[88:91], v[152:155], v[202:205], v[88:91]
	v_mfma_f32_16x16x32_bf16 v[80:83], v[144:147], v[220:223], v[80:83]
	v_mfma_f32_16x16x32_bf16 v[72:75], v[152:155], v[220:223], v[72:75]
	v_mfma_f32_16x16x32_bf16 v[128:131], v[148:151], v[180:183], v[128:131]
	v_mfma_f32_16x16x32_bf16 v[120:123], v[156:159], v[180:183], v[120:123]
	v_mfma_f32_16x16x32_bf16 v[112:115], v[148:151], v[198:201], v[112:115]
	v_mfma_f32_16x16x32_bf16 v[104:107], v[156:159], v[198:201], v[104:107]
	v_mfma_f32_16x16x32_bf16 v[96:99], v[148:151], v[206:209], v[96:99]
	v_mfma_f32_16x16x32_bf16 v[88:91], v[156:159], v[206:209], v[88:91]
	v_mfma_f32_16x16x32_bf16 v[80:83], v[148:151], v[224:227], v[80:83]
	v_mfma_f32_16x16x32_bf16 v[72:75], v[156:159], v[224:227], v[72:75]
	s_setprio 0
	s_setprio 1
	v_mfma_f32_16x16x32_bf16 v[124:127], v[160:163], v[176:179], v[124:127]
	v_mfma_f32_16x16x32_bf16 v[116:119], v[168:171], v[176:179], v[116:119]
	v_mfma_f32_16x16x32_bf16 v[108:111], v[160:163], v[194:197], v[108:111]
	v_mfma_f32_16x16x32_bf16 v[100:103], v[168:171], v[194:197], v[100:103]
	v_mfma_f32_16x16x32_bf16 v[92:95], v[160:163], v[202:205], v[92:95]
	v_mfma_f32_16x16x32_bf16 v[84:87], v[168:171], v[202:205], v[84:87]
	v_mfma_f32_16x16x32_bf16 v[76:79], v[160:163], v[220:223], v[76:79]
	v_mfma_f32_16x16x32_bf16 v[68:71], v[168:171], v[220:223], v[68:71]
	v_mfma_f32_16x16x32_bf16 v[124:127], v[164:167], v[180:183], v[124:127]
	v_mfma_f32_16x16x32_bf16 v[116:119], v[172:175], v[180:183], v[116:119]
	v_mfma_f32_16x16x32_bf16 v[108:111], v[164:167], v[198:201], v[108:111]
	v_mfma_f32_16x16x32_bf16 v[100:103], v[172:175], v[198:201], v[100:103]
	v_mfma_f32_16x16x32_bf16 v[92:95], v[164:167], v[206:209], v[92:95]
	v_mfma_f32_16x16x32_bf16 v[84:87], v[172:175], v[206:209], v[84:87]
	v_mfma_f32_16x16x32_bf16 v[76:79], v[164:167], v[224:227], v[76:79]
	v_mfma_f32_16x16x32_bf16 v[68:71], v[172:175], v[224:227], v[68:71]
	s_setprio 0
	s_barrier
	s_add_i32 s20, s25, s67
	v_lshl_add_u64 v[210:211], s[26:27], 0, v[134:135]
	s_mov_b32 m0, s20
	ds_read_b128 v[176:179], v143 offset:16384
	ds_read_b128 v[180:183], v143 offset:17408
	ds_read_b128 v[194:197], v143 offset:18432
	ds_read_b128 v[198:201], v143 offset:19456
	ds_read_b128 v[202:205], v143 offset:20480
	ds_read_b128 v[206:209], v143 offset:21504
	ds_read_b128 v[220:223], v143 offset:22528
	ds_read_b128 v[224:227], v143 offset:23552
	global_load_lds_dwordx4 v[210:211], off
	s_add_i32 m0, s20, 0x2000
	v_lshl_add_u64 v[228:229], s[26:27], 0, v[0:1]
	s_add_u32 s26, s26, s44
	s_addc_u32 s27, s27, s45
	s_add_i32 s18, s18, s67
	global_load_lds_dwordx4 v[228:229], off
	v_lshl_add_u64 v[230:231], s[26:27], 0, v[134:135]
	s_mov_b32 m0, s18
	v_lshl_add_u64 v[232:233], s[26:27], 0, v[0:1]
	global_load_lds_dwordx4 v[230:231], off
	s_add_i32 m0, s18, 0x2000
	v_lshl_add_u64 v[234:235], s[50:51], 0, v[136:137]
	global_load_lds_dwordx4 v[232:233], off
	s_mov_b32 m0, s70
	v_lshl_add_u64 v[236:237], s[50:51], 0, v[132:133]
	global_load_lds_dwordx4 v[234:235], off
	s_mov_b32 m0, s71
	s_nop 0
	global_load_lds_dwordx4 v[236:237], off
	s_waitcnt vmcnt(8)
	s_waitcnt lgkmcnt(0)
	s_barrier
; #define PG8_STAGE(bufoff, gbase, voff) do { _Pragma("unroll") for (int _i = 0; _i < 2; ++_i) \
;         __builtin_amdgcn_global_load_lds((const unsigned*)((const char*)(gbase) + (voff)[_i]), (PG8_LAS unsigned*)(lds + (bufoff) + ldsw + _i * 8192), 16, 0, 0); } while (0)
; #define PG8_LDA(dst, b, h) do { _Pragma("unroll") for (int m = 0; m < 4; ++m) _Pragma("unroll") for (int k = 0; k < 2; ++k) dst[m][k] = *(const PG8_LAS bf16x8*)(lds + PG8_SA(b, h) + aoff + m * 2048 + k * 1024); } while (0)
; #define PG8_LDB(dst, b, h) do { _Pragma("unroll") for (int n = 0; n < 2; ++n) _Pragma("unroll") for (int k = 0; k < 2; ++k) dst[n][k] = *(const PG8_LAS bf16x8*)(lds + PG8_SB(b, h) + boff + n * 2048 + k * 1024); } while (0)
; #define PG8_MMA(ai, bj, At, Bt) do { __builtin_amdgcn_s_setprio(1); _Pragma("unroll") for (int m = 0; m < 4; ++m) _Pragma("unroll") for (int n = 0; n < 2; ++n) _Pragma("unroll") for (int k = 0; k < 2; ++k) \
;         acc[ai][bj][m][n] = __builtin_amdgcn_mfma_f32_16x16x32_bf16(Bt[n][k], At[m][k], acc[ai][bj][m][n], 0, 0, 0); __builtin_amdgcn_s_setprio(0); } while (0)
; #define PG8_WAIT_V(n) asm volatile("s_waitcnt vmcnt(" #n ")" ::: "memory")
; #define PG8_WAIT_L(n) asm volatile("s_waitcnt lgkmcnt(" #n ")" ::: "memory")
; #define PG8_BAR __builtin_amdgcn_s_barrier()
; #define PG8_SCHED __builtin_amdgcn_sched_barrier(0)
; template <class Epi, class Sched, bool ALIGN_EPI = false, bool SP2 = false>
; __device__ __forceinline__ void gemm_phase(PG8_LAS unsigned char* lds, const Gemm g, const Sched& S, const Epi& E) {
;     ...
;             PG8_WAIT_V(8); PG8_WAIT_L(0); PG8_BAR; PG8_MMA(1, 0, At, B0); PG8_MMA(1, 1, At, B1); PG8_BAR; PG8_SCHED;
;             PG8_LDB(B0, 1, 0); PG8_LDB(B1, 1, 1); PG8_SCHED; PG8_LDA(At, 1, 0); PG8_STAGE(PG8_SA(0, 1), a2 + hstep, voffA);
;             PG8_WAIT_V(8); PG8_WAIT_L(0); PG8_BAR; PG8_MMA(0, 0, At, B0); PG8_MMA(0, 1, At, B1); PG8_BAR; PG8_SCHED;
	s_setprio 1
	s_waitcnt lgkmcnt(0)
	v_mfma_f32_16x16x32_bf16 v[64:67], v[144:147], v[176:179], v[64:67]
	v_mfma_f32_16x16x32_bf16 v[56:59], v[152:155], v[176:179], v[56:59]
	v_mfma_f32_16x16x32_bf16 v[48:51], v[144:147], v[194:197], v[48:51]
	v_mfma_f32_16x16x32_bf16 v[40:43], v[152:155], v[194:197], v[40:43]
	v_mfma_f32_16x16x32_bf16 v[32:35], v[144:147], v[202:205], v[32:35]
	v_mfma_f32_16x16x32_bf16 v[24:27], v[152:155], v[202:205], v[24:27]
	v_mfma_f32_16x16x32_bf16 v[16:19], v[144:147], v[220:223], v[16:19]
	v_mfma_f32_16x16x32_bf16 v[8:11], v[152:155], v[220:223], v[8:11]
	v_mfma_f32_16x16x32_bf16 v[64:67], v[148:151], v[180:183], v[64:67]
	v_mfma_f32_16x16x32_bf16 v[56:59], v[156:159], v[180:183], v[56:59]
	v_mfma_f32_16x16x32_bf16 v[48:51], v[148:151], v[198:201], v[48:51]
	v_mfma_f32_16x16x32_bf16 v[40:43], v[156:159], v[198:201], v[40:43]
	v_mfma_f32_16x16x32_bf16 v[32:35], v[148:151], v[206:209], v[32:35]
	v_mfma_f32_16x16x32_bf16 v[24:27], v[156:159], v[206:209], v[24:27]
	v_mfma_f32_16x16x32_bf16 v[16:19], v[148:151], v[224:227], v[16:19]
	v_mfma_f32_16x16x32_bf16 v[8:11], v[156:159], v[224:227], v[8:11]
	s_setprio 0
	s_setprio 1
	v_mfma_f32_16x16x32_bf16 v[60:63], v[160:163], v[176:179], v[60:63]
	v_mfma_f32_16x16x32_bf16 v[52:55], v[168:171], v[176:179], v[52:55]
	v_mfma_f32_16x16x32_bf16 v[44:47], v[160:163], v[194:197], v[44:47]
	v_mfma_f32_16x16x32_bf16 v[36:39], v[168:171], v[194:197], v[36:39]
	v_mfma_f32_16x16x32_bf16 v[28:31], v[160:163], v[202:205], v[28:31]
	v_mfma_f32_16x16x32_bf16 v[20:23], v[168:171], v[202:205], v[20:23]
	v_mfma_f32_16x16x32_bf16 v[12:15], v[160:163], v[220:223], v[12:15]
	v_mfma_f32_16x16x32_bf16 v[4:7], v[168:171], v[220:223], v[4:7]
	v_mfma_f32_16x16x32_bf16 v[60:63], v[164:167], v[180:183], v[60:63]
	v_mfma_f32_16x16x32_bf16 v[52:55], v[172:175], v[180:183], v[52:55]
	v_mfma_f32_16x16x32_bf16 v[44:47], v[164:167], v[198:201], v[44:47]
	v_mfma_f32_16x16x32_bf16 v[36:39], v[172:175], v[198:201], v[36:39]
	v_mfma_f32_16x16x32_bf16 v[28:31], v[164:167], v[206:209], v[28:31]
	v_mfma_f32_16x16x32_bf16 v[20:23], v[172:175], v[206:209], v[20:23]
	v_mfma_f32_16x16x32_bf16 v[12:15], v[164:167], v[224:227], v[12:15]
	v_mfma_f32_16x16x32_bf16 v[4:7], v[172:175], v[224:227], v[4:7]
	s_setprio 0
	s_barrier
	s_add_i32 s18, s82, 0x100
	v_add_u32_e32 v2, s18, v142
	s_add_i32 s20, s78, 0x100
	ds_read_b128 v[144:147], v2
	ds_read_b128 v[148:151], v2 offset:1024
	ds_read_b128 v[152:155], v2 offset:2048
	ds_read_b128 v[156:159], v2 offset:3072
	v_add_u32_e32 v2, s20, v142
	ds_read_b128 v[160:163], v2
	ds_read_b128 v[164:167], v2 offset:1024
	ds_read_b128 v[168:171], v2 offset:2048
	ds_read_b128 v[172:175], v2 offset:3072
	s_add_u32 s26, s50, s44
	s_addc_u32 s27, s51, s45
	s_mov_b32 m0, s80
	v_lshl_add_u64 v[238:239], s[26:27], 0, v[136:137]
	ds_read_b128 v[176:179], v143 offset:32768
	ds_read_b128 v[180:183], v143 offset:33792
	ds_read_b128 v[194:197], v143 offset:34816
	ds_read_b128 v[198:201], v143 offset:35840
	ds_read_b128 v[202:205], v143 offset:36864
	ds_read_b128 v[206:209], v143 offset:37888
	ds_read_b128 v[220:223], v143 offset:38912
	ds_read_b128 v[224:227], v143 offset:39936
	global_load_lds_dwordx4 v[238:239], off
	v_lshl_add_u64 v[238:239], s[26:27], 0, v[132:133]
	s_mov_b32 m0, s81
	s_nop 0
	global_load_lds_dwordx4 v[238:239], off
	s_waitcnt vmcnt(8)
	s_waitcnt lgkmcnt(0)
	s_barrier
	s_setprio 1
	s_waitcnt lgkmcnt(0)
	v_mfma_f32_16x16x32_bf16 v[128:131], v[144:147], v[176:179], v[128:131]
	v_mfma_f32_16x16x32_bf16 v[120:123], v[152:155], v[176:179], v[120:123]
	v_mfma_f32_16x16x32_bf16 v[112:115], v[144:147], v[194:197], v[112:115]
	v_mfma_f32_16x16x32_bf16 v[104:107], v[152:155], v[194:197], v[104:107]
	v_mfma_f32_16x16x32_bf16 v[96:99], v[144:147], v[202:205], v[96:99]
	v_mfma_f32_16x16x32_bf16 v[88:91], v[152:155], v[202:205], v[88:91]
	v_mfma_f32_16x16x32_bf16 v[80:83], v[144:147], v[220:223], v[80:83]
	v_mfma_f32_16x16x32_bf16 v[72:75], v[152:155], v[220:223], v[72:75]
	v_mfma_f32_16x16x32_bf16 v[128:131], v[148:151], v[180:183], v[128:131]
	v_mfma_f32_16x16x32_bf16 v[120:123], v[156:159], v[180:183], v[120:123]
	v_mfma_f32_16x16x32_bf16 v[112:115], v[148:151], v[198:201], v[112:115]
	v_mfma_f32_16x16x32_bf16 v[104:107], v[156:159], v[198:201], v[104:107]
	v_mfma_f32_16x16x32_bf16 v[96:99], v[148:151], v[206:209], v[96:99]
	v_mfma_f32_16x16x32_bf16 v[88:91], v[156:159], v[206:209], v[88:91]
	v_mfma_f32_16x16x32_bf16 v[80:83], v[148:151], v[224:227], v[80:83]
	v_mfma_f32_16x16x32_bf16 v[72:75], v[156:159], v[224:227], v[72:75]
	s_setprio 0
	s_setprio 1
	v_mfma_f32_16x16x32_bf16 v[124:127], v[160:163], v[176:179], v[124:127]
	v_mfma_f32_16x16x32_bf16 v[116:119], v[168:171], v[176:179], v[116:119]
	v_mfma_f32_16x16x32_bf16 v[108:111], v[160:163], v[194:197], v[108:111]
	v_mfma_f32_16x16x32_bf16 v[100:103], v[168:171], v[194:197], v[100:103]
	v_mfma_f32_16x16x32_bf16 v[92:95], v[160:163], v[202:205], v[92:95]
	v_mfma_f32_16x16x32_bf16 v[84:87], v[168:171], v[202:205], v[84:87]
	v_mfma_f32_16x16x32_bf16 v[76:79], v[160:163], v[220:223], v[76:79]
	v_mfma_f32_16x16x32_bf16 v[68:71], v[168:171], v[220:223], v[68:71]
	v_mfma_f32_16x16x32_bf16 v[124:127], v[164:167], v[180:183], v[124:127]
	v_mfma_f32_16x16x32_bf16 v[116:119], v[172:175], v[180:183], v[116:119]
	v_mfma_f32_16x16x32_bf16 v[108:111], v[164:167], v[198:201], v[108:111]
	v_mfma_f32_16x16x32_bf16 v[100:103], v[172:175], v[198:201], v[100:103]
	v_mfma_f32_16x16x32_bf16 v[92:95], v[164:167], v[206:209], v[92:95]
	v_mfma_f32_16x16x32_bf16 v[84:87], v[172:175], v[206:209], v[84:87]
	v_mfma_f32_16x16x32_bf16 v[76:79], v[164:167], v[224:227], v[76:79]
	v_mfma_f32_16x16x32_bf16 v[68:71], v[172:175], v[224:227], v[68:71]
	s_setprio 0
	s_barrier
; #define PG8_STAGE(bufoff, gbase, voff) do { _Pragma("unroll") for (int _i = 0; _i < 2; ++_i) \
;         __builtin_amdgcn_global_load_lds((const unsigned*)((const char*)(gbase) + (voff)[_i]), (PG8_LAS unsigned*)(lds + (bufoff) + ldsw + _i * 8192), 16, 0, 0); } while (0)
; #define PG8_LDA(dst, b, h) do { _Pragma("unroll") for (int m = 0; m < 4; ++m) _Pragma("unroll") for (int k = 0; k < 2; ++k) dst[m][k] = *(const PG8_LAS bf16x8*)(lds + PG8_SA(b, h) + aoff + m * 2048 + k * 1024); } while (0)
; #define PG8_MMA(ai, bj, At, Bt) do { __builtin_amdgcn_s_setprio(1); _Pragma("unroll") for (int m = 0; m < 4; ++m) _Pragma("unroll") for (int n = 0; n < 2; ++n) _Pragma("unroll") for (int k = 0; k < 2; ++k) \
;         acc[ai][bj][m][n] = __builtin_amdgcn_mfma_f32_16x16x32_bf16(Bt[n][k], At[m][k], acc[ai][bj][m][n], 0, 0, 0); __builtin_amdgcn_s_setprio(0); } while (0)
; #define PG8_WAIT_V(n) asm volatile("s_waitcnt vmcnt(" #n ")" ::: "memory")
; #define PG8_WAIT_L(n) asm volatile("s_waitcnt lgkmcnt(" #n ")" ::: "memory")
; #define PG8_BAR __builtin_amdgcn_s_barrier()
; #define PG8_SCHED __builtin_amdgcn_sched_barrier(0)
; template <class Epi, class Sched, bool ALIGN_EPI = false, bool SP2 = false>
; __device__ __forceinline__ void gemm_phase(PG8_LAS unsigned char* lds, const Gemm g, const Sched& S, const Epi& E) {
;     ...
;         for (int t = 0; t < nt; t += 2) {
;     ...
;             PG8_LDA(At, 1, 1); PG8_STAGE(PG8_SB(1, 0), b3, voffB); PG8_STAGE(PG8_SB(1, 1), b3 + hstep, voffB); PG8_STAGE(PG8_SA(1, 0), a3, voffA);
;             PG8_WAIT_V(8); PG8_WAIT_L(0); PG8_BAR; PG8_MMA(1, 0, At, B0); PG8_MMA(1, 1, At, B1); PG8_BAR; PG8_SCHED;
	s_add_i32 s18, s18, s67
	v_lshl_add_u64 v[210:211], v[210:211], 0, s[8:9]
	s_mov_b32 m0, s18
	ds_read_b128 v[176:179], v143 offset:49152
	ds_read_b128 v[180:183], v143 offset:50176
	ds_read_b128 v[194:197], v143 offset:51200
	ds_read_b128 v[198:201], v143 offset:52224
	ds_read_b128 v[202:205], v143 offset:53248
	ds_read_b128 v[206:209], v143 offset:54272
	ds_read_b128 v[220:223], v143 offset:55296
	ds_read_b128 v[224:227], v143 offset:56320
	global_load_lds_dwordx4 v[210:211], off
	v_lshl_add_u64 v[210:211], v[228:229], 0, s[8:9]
	s_add_i32 m0, s18, 0x2000
	s_add_i32 s18, s20, s67
	global_load_lds_dwordx4 v[210:211], off
	v_lshl_add_u64 v[210:211], v[230:231], 0, s[8:9]
	s_mov_b32 m0, s18
	s_nop 0
	global_load_lds_dwordx4 v[210:211], off
	v_lshl_add_u64 v[210:211], v[232:233], 0, s[8:9]
	s_add_i32 m0, s18, 0x2000
	s_nop 0
	global_load_lds_dwordx4 v[210:211], off
	v_lshl_add_u64 v[210:211], v[234:235], 0, s[8:9]
	s_mov_b32 m0, s87
	s_nop 0
	global_load_lds_dwordx4 v[210:211], off
	v_lshl_add_u64 v[210:211], v[236:237], 0, s[8:9]
	s_mov_b32 m0, s92
	s_nop 0
	global_load_lds_dwordx4 v[210:211], off
	s_waitcnt vmcnt(8)
	s_waitcnt lgkmcnt(0)
	s_barrier
	s_setprio 1
	s_waitcnt lgkmcnt(0)
	v_mfma_f32_16x16x32_bf16 v[64:67], v[144:147], v[176:179], v[64:67]
	v_mfma_f32_16x16x32_bf16 v[56:59], v[152:155], v[176:179], v[56:59]
	v_mfma_f32_16x16x32_bf16 v[48:51], v[144:147], v[194:197], v[48:51]
	v_mfma_f32_16x16x32_bf16 v[40:43], v[152:155], v[194:197], v[40:43]
	v_mfma_f32_16x16x32_bf16 v[32:35], v[144:147], v[202:205], v[32:35]
	v_mfma_f32_16x16x32_bf16 v[24:27], v[152:155], v[202:205], v[24:27]
	v_mfma_f32_16x16x32_bf16 v[16:19], v[144:147], v[220:223], v[16:19]
	v_mfma_f32_16x16x32_bf16 v[8:11], v[152:155], v[220:223], v[8:11]
	v_mfma_f32_16x16x32_bf16 v[64:67], v[148:151], v[180:183], v[64:67]
	v_mfma_f32_16x16x32_bf16 v[56:59], v[156:159], v[180:183], v[56:59]
	v_mfma_f32_16x16x32_bf16 v[48:51], v[148:151], v[198:201], v[48:51]
	v_mfma_f32_16x16x32_bf16 v[40:43], v[156:159], v[198:201], v[40:43]
	v_mfma_f32_16x16x32_bf16 v[32:35], v[148:151], v[206:209], v[32:35]
	v_mfma_f32_16x16x32_bf16 v[24:27], v[156:159], v[206:209], v[24:27]
	v_mfma_f32_16x16x32_bf16 v[16:19], v[148:151], v[224:227], v[16:19]
	v_mfma_f32_16x16x32_bf16 v[8:11], v[156:159], v[224:227], v[8:11]
	s_setprio 0
	s_setprio 1
	v_mfma_f32_16x16x32_bf16 v[60:63], v[160:163], v[176:179], v[60:63]
	v_mfma_f32_16x16x32_bf16 v[52:55], v[168:171], v[176:179], v[52:55]
	v_mfma_f32_16x16x32_bf16 v[44:47], v[160:163], v[194:197], v[44:47]
	v_mfma_f32_16x16x32_bf16 v[36:39], v[168:171], v[194:197], v[36:39]
	v_mfma_f32_16x16x32_bf16 v[28:31], v[160:163], v[202:205], v[28:31]
	v_mfma_f32_16x16x32_bf16 v[20:23], v[168:171], v[202:205], v[20:23]
	v_mfma_f32_16x16x32_bf16 v[12:15], v[160:163], v[220:223], v[12:15]
	v_mfma_f32_16x16x32_bf16 v[4:7], v[168:171], v[220:223], v[4:7]
	v_mfma_f32_16x16x32_bf16 v[60:63], v[164:167], v[180:183], v[60:63]
	v_mfma_f32_16x16x32_bf16 v[52:55], v[172:175], v[180:183], v[52:55]
	v_mfma_f32_16x16x32_bf16 v[44:47], v[164:167], v[198:201], v[44:47]
	v_mfma_f32_16x16x32_bf16 v[36:39], v[172:175], v[198:201], v[36:39]
	v_mfma_f32_16x16x32_bf16 v[28:31], v[164:167], v[206:209], v[28:31]
	v_mfma_f32_16x16x32_bf16 v[20:23], v[172:175], v[206:209], v[20:23]
	v_mfma_f32_16x16x32_bf16 v[12:15], v[164:167], v[224:227], v[12:15]
	v_mfma_f32_16x16x32_bf16 v[4:7], v[172:175], v[224:227], v[4:7]
	s_add_u32 s12, s12, 0x100
	s_addc_u32 s15, s15, 0
	s_add_u32 s38, s38, 0x100
	s_addc_u32 s39, s39, 0
	s_cmp_ge_i32 s19, s93
	s_mov_b32 s18, s19
	s_setprio 0
	s_barrier
	s_cbranch_scc0 .LBB0_38

; #define PG8_STAGE(bufoff, gbase, voff) do { _Pragma("unroll") for (int _i = 0; _i < 2; ++_i) \
;         __builtin_amdgcn_global_load_lds((const unsigned*)((const char*)(gbase) + (voff)[_i]), (PG8_LAS unsigned*)(lds + (bufoff) + ldsw + _i * 8192), 16, 0, 0); } while (0)
; #define PG8_LDA(dst, b, h) do { _Pragma("unroll") for (int m = 0; m < 4; ++m) _Pragma("unroll") for (int k = 0; k < 2; ++k) dst[m][k] = *(const PG8_LAS bf16x8*)(lds + PG8_SA(b, h) + aoff + m * 2048 + k * 1024); } while (0)
; #define PG8_LDB(dst, b, h) do { _Pragma("unroll") for (int n = 0; n < 2; ++n) _Pragma("unroll") for (int k = 0; k < 2; ++k) dst[n][k] = *(const PG8_LAS bf16x8*)(lds + PG8_SB(b, h) + boff + n * 2048 + k * 1024); } while (0)
; #define PG8_MMA(ai, bj, At, Bt) do { __builtin_amdgcn_s_setprio(1); _Pragma("unroll") for (int m = 0; m < 4; ++m) _Pragma("unroll") for (int n = 0; n < 2; ++n) _Pragma("unroll") for (int k = 0; k < 2; ++k) \
;         acc[ai][bj][m][n] = __builtin_amdgcn_mfma_f32_16x16x32_bf16(Bt[n][k], At[m][k], acc[ai][bj][m][n], 0, 0, 0); __builtin_amdgcn_s_setprio(0); } while (0)
; #define PG8_WAIT_V(n) asm volatile("s_waitcnt vmcnt(" #n ")" ::: "memory")
; #define PG8_BAR __builtin_amdgcn_s_barrier()
; template <class Epi, class Sched, bool ALIGN_EPI = false, bool SP2 = false>
; __device__ __forceinline__ void gemm_phase(PG8_LAS unsigned char* lds, const Gemm g, const Sched& S, const Epi& E) {
;     ...
;         for (int t = 0; t < nt; t += 2) {
;             const bool last = (t == nt - 2);
;             const char* a1 = cA + (size_t)(t + 1) * kstep;
;             const char* a2 = last ? nA : cA + (size_t)(t + 2) * kstep; const char* b2 = last ? nB : cB + (size_t)(t + 2) * kstep;
;             const char* a3 = a2 + kstep; const char* b3 = b2 + kstep;
;             if (last && has_next) S.a_ready(nxt);
;             if constexpr (SP2) {
;             PG8_LDB(B0, 0, 0); PG8_LDB(B1, 0, 1); PG8_SCHED; PG8_LDA(At, 0, 0); PG8_STAGE(PG8_SA(1, 1), a1 + hstep, voffA);
;             PG8_WAIT_V(8); PG8_WAIT_L(0); PG8_BAR; PG8_MMA(0, 0, At, B0); PG8_MMA(0, 1, At, B1); PG8_BAR; PG8_SCHED;
;             PG8_LDA(At, 0, 1); PG8_STAGE(PG8_SB(0, 0), b2, voffB); PG8_STAGE(PG8_SB(0, 1), b2 + hstep, voffB); PG8_STAGE(PG8_SA(0, 0), a2, voffA);
;             PG8_WAIT_V(8); PG8_WAIT_L(0); PG8_BAR; PG8_MMA(1, 0, At, B0); PG8_MMA(1, 1, At, B1); PG8_BAR; PG8_SCHED;
.LBB0_80:
	ds_read_b128 v[176:179], v143
	ds_read_b128 v[180:183], v143 offset:1024
	ds_read_b128 v[194:197], v143 offset:2048
	ds_read_b128 v[198:201], v143 offset:3072
	ds_read_b128 v[202:205], v143 offset:4096
	ds_read_b128 v[206:209], v143 offset:5120
	ds_read_b128 v[220:223], v143 offset:6144
	ds_read_b128 v[224:227], v143 offset:7168
	s_add_i32 s74, s33, 0x100
	v_add_u32_e32 v2, s74, v142
	ds_read_b128 v[144:147], v2
	ds_read_b128 v[148:151], v2 offset:1024
	ds_read_b128 v[152:155], v2 offset:2048
	ds_read_b128 v[156:159], v2 offset:3072
	s_add_i32 s93, s50, 2
	s_add_u32 s28, s46, 0x80
	s_addc_u32 s29, s47, 0
	s_cmp_eq_u32 s4, s50
	s_cselect_b32 s51, s45, s29
	s_cselect_b32 s50, s44, s28
	s_cselect_b32 vcc_hi, s71, s92
	s_cselect_b32 vcc_lo, s70, s25
	s_add_i32 s28, s21, 0x100
	v_add_u32_e32 v2, s28, v142
	ds_read_b128 v[160:163], v2
	ds_read_b128 v[164:167], v2 offset:1024
	ds_read_b128 v[168:171], v2 offset:2048
	ds_read_b128 v[172:175], v2 offset:3072
	v_lshl_add_u64 v[210:211], s[46:47], 0, v[140:141]
	s_add_i32 m0, s19, 0xc000
	global_load_lds_dwordx4 v[210:211], off
	v_lshl_add_u64 v[210:211], s[46:47], 0, v[138:139]
	s_add_i32 m0, s19, 0xe000
	s_nop 0
	global_load_lds_dwordx4 v[210:211], off
	s_waitcnt vmcnt(8)
	s_waitcnt lgkmcnt(0)
	s_barrier
	s_setprio 1
	s_waitcnt lgkmcnt(0)
	v_mfma_f32_16x16x32_bf16 v[128:131], v[144:147], v[176:179], v[128:131]
	v_mfma_f32_16x16x32_bf16 v[124:127], v[152:155], v[176:179], v[124:127]
	v_mfma_f32_16x16x32_bf16 v[112:115], v[144:147], v[194:197], v[112:115]
	v_mfma_f32_16x16x32_bf16 v[108:111], v[152:155], v[194:197], v[108:111]
	v_mfma_f32_16x16x32_bf16 v[96:99], v[144:147], v[202:205], v[96:99]
	v_mfma_f32_16x16x32_bf16 v[92:95], v[152:155], v[202:205], v[92:95]
	v_mfma_f32_16x16x32_bf16 v[80:83], v[144:147], v[220:223], v[80:83]
	v_mfma_f32_16x16x32_bf16 v[76:79], v[152:155], v[220:223], v[76:79]
	v_mfma_f32_16x16x32_bf16 v[128:131], v[148:151], v[180:183], v[128:131]
	v_mfma_f32_16x16x32_bf16 v[124:127], v[156:159], v[180:183], v[124:127]
	v_mfma_f32_16x16x32_bf16 v[112:115], v[148:151], v[198:201], v[112:115]
	v_mfma_f32_16x16x32_bf16 v[108:111], v[156:159], v[198:201], v[108:111]
	v_mfma_f32_16x16x32_bf16 v[96:99], v[148:151], v[206:209], v[96:99]
	v_mfma_f32_16x16x32_bf16 v[92:95], v[156:159], v[206:209], v[92:95]
	v_mfma_f32_16x16x32_bf16 v[80:83], v[148:151], v[224:227], v[80:83]
	v_mfma_f32_16x16x32_bf16 v[76:79], v[156:159], v[224:227], v[76:79]
	s_setprio 0
	s_setprio 1
	v_mfma_f32_16x16x32_bf16 v[120:123], v[160:163], v[176:179], v[120:123]
	v_mfma_f32_16x16x32_bf16 v[116:119], v[168:171], v[176:179], v[116:119]
	v_mfma_f32_16x16x32_bf16 v[104:107], v[160:163], v[194:197], v[104:107]
	v_mfma_f32_16x16x32_bf16 v[100:103], v[168:171], v[194:197], v[100:103]
	v_mfma_f32_16x16x32_bf16 v[88:91], v[160:163], v[202:205], v[88:91]
	v_mfma_f32_16x16x32_bf16 v[84:87], v[168:171], v[202:205], v[84:87]
	v_mfma_f32_16x16x32_bf16 v[72:75], v[160:163], v[220:223], v[72:75]
	v_mfma_f32_16x16x32_bf16 v[68:71], v[168:171], v[220:223], v[68:71]
	v_mfma_f32_16x16x32_bf16 v[120:123], v[164:167], v[180:183], v[120:123]
	v_mfma_f32_16x16x32_bf16 v[116:119], v[172:175], v[180:183], v[116:119]
	v_mfma_f32_16x16x32_bf16 v[104:107], v[164:167], v[198:201], v[104:107]
	v_mfma_f32_16x16x32_bf16 v[100:103], v[172:175], v[198:201], v[100:103]
	v_mfma_f32_16x16x32_bf16 v[88:91], v[164:167], v[206:209], v[88:91]
	v_mfma_f32_16x16x32_bf16 v[84:87], v[172:175], v[206:209], v[84:87]
	v_mfma_f32_16x16x32_bf16 v[72:75], v[164:167], v[224:227], v[72:75]
	v_mfma_f32_16x16x32_bf16 v[68:71], v[172:175], v[224:227], v[68:71]
	s_setprio 0
	s_barrier
	s_add_i32 s29, s74, s18
	v_lshl_add_u64 v[210:211], vcc, 0, v[134:135]
	s_mov_b32 m0, s29
	ds_read_b128 v[176:179], v143 offset:16384
	ds_read_b128 v[180:183], v143 offset:17408
	ds_read_b128 v[194:197], v143 offset:18432
	ds_read_b128 v[198:201], v143 offset:19456
	ds_read_b128 v[202:205], v143 offset:20480
	ds_read_b128 v[206:209], v143 offset:21504
	ds_read_b128 v[220:223], v143 offset:22528
	ds_read_b128 v[224:227], v143 offset:23552
	global_load_lds_dwordx4 v[210:211], off
	s_add_i32 m0, s29, 0x2000
	v_lshl_add_u64 v[214:215], vcc, 0, v[0:1]
	s_add_u32 vcc_lo, vcc_lo, s58
	s_addc_u32 vcc_hi, vcc_hi, s59
	s_add_i32 s28, s28, s18
	global_load_lds_dwordx4 v[214:215], off
	v_lshl_add_u64 v[218:219], vcc, 0, v[134:135]
	s_mov_b32 m0, s28
	v_lshl_add_u64 v[228:229], vcc, 0, v[0:1]
	global_load_lds_dwordx4 v[218:219], off
	s_add_i32 m0, s28, 0x2000
	v_lshl_add_u64 v[230:231], s[50:51], 0, v[136:137]
	global_load_lds_dwordx4 v[228:229], off
	s_mov_b32 m0, s19
	v_lshl_add_u64 v[232:233], s[50:51], 0, v[132:133]
	global_load_lds_dwordx4 v[230:231], off
	s_mov_b32 m0, s30
	s_nop 0
	global_load_lds_dwordx4 v[232:233], off
	s_waitcnt vmcnt(8)
	s_waitcnt lgkmcnt(0)
	s_barrier
; #define PG8_STAGE(bufoff, gbase, voff) do { _Pragma("unroll") for (int _i = 0; _i < 2; ++_i) \
;         __builtin_amdgcn_global_load_lds((const unsigned*)((const char*)(gbase) + (voff)[_i]), (PG8_LAS unsigned*)(lds + (bufoff) + ldsw + _i * 8192), 16, 0, 0); } while (0)
; #define PG8_LDA(dst, b, h) do { _Pragma("unroll") for (int m = 0; m < 4; ++m) _Pragma("unroll") for (int k = 0; k < 2; ++k) dst[m][k] = *(const PG8_LAS bf16x8*)(lds + PG8_SA(b, h) + aoff + m * 2048 + k * 1024); } while (0)
; #define PG8_LDB(dst, b, h) do { _Pragma("unroll") for (int n = 0; n < 2; ++n) _Pragma("unroll") for (int k = 0; k < 2; ++k) dst[n][k] = *(const PG8_LAS bf16x8*)(lds + PG8_SB(b, h) + boff + n * 2048 + k * 1024); } while (0)
; #define PG8_MMA(ai, bj, At, Bt) do { __builtin_amdgcn_s_setprio(1); _Pragma("unroll") for (int m = 0; m < 4; ++m) _Pragma("unroll") for (int n = 0; n < 2; ++n) _Pragma("unroll") for (int k = 0; k < 2; ++k) \
;         acc[ai][bj][m][n] = __builtin_amdgcn_mfma_f32_16x16x32_bf16(Bt[n][k], At[m][k], acc[ai][bj][m][n], 0, 0, 0); __builtin_amdgcn_s_setprio(0); } while (0)
; #define PG8_WAIT_V(n) asm volatile("s_waitcnt vmcnt(" #n ")" ::: "memory")
; #define PG8_WAIT_L(n) asm volatile("s_waitcnt lgkmcnt(" #n ")" ::: "memory")
; #define PG8_BAR __builtin_amdgcn_s_barrier()
; #define PG8_SCHED __builtin_amdgcn_sched_barrier(0)
; template <class Epi, class Sched, bool ALIGN_EPI = false, bool SP2 = false>
; __device__ __forceinline__ void gemm_phase(PG8_LAS unsigned char* lds, const Gemm g, const Sched& S, const Epi& E) {
;     ...
;             PG8_WAIT_V(8); PG8_WAIT_L(0); PG8_BAR; PG8_MMA(1, 0, At, B0); PG8_MMA(1, 1, At, B1); PG8_BAR; PG8_SCHED;
;             PG8_LDB(B0, 1, 0); PG8_LDB(B1, 1, 1); PG8_SCHED; PG8_LDA(At, 1, 0); PG8_STAGE(PG8_SA(0, 1), a2 + hstep, voffA);
;             PG8_WAIT_V(8); PG8_WAIT_L(0); PG8_BAR; PG8_MMA(0, 0, At, B0); PG8_MMA(0, 1, At, B1); PG8_BAR; PG8_SCHED;
	s_setprio 1
	s_waitcnt lgkmcnt(0)
	v_mfma_f32_16x16x32_bf16 v[64:67], v[144:147], v[176:179], v[64:67]
	v_mfma_f32_16x16x32_bf16 v[60:63], v[152:155], v[176:179], v[60:63]
	v_mfma_f32_16x16x32_bf16 v[48:51], v[144:147], v[194:197], v[48:51]
	v_mfma_f32_16x16x32_bf16 v[44:47], v[152:155], v[194:197], v[44:47]
	v_mfma_f32_16x16x32_bf16 v[32:35], v[144:147], v[202:205], v[32:35]
	v_mfma_f32_16x16x32_bf16 v[28:31], v[152:155], v[202:205], v[28:31]
	v_mfma_f32_16x16x32_bf16 v[16:19], v[144:147], v[220:223], v[16:19]
	v_mfma_f32_16x16x32_bf16 v[12:15], v[152:155], v[220:223], v[12:15]
	v_mfma_f32_16x16x32_bf16 v[64:67], v[148:151], v[180:183], v[64:67]
	v_mfma_f32_16x16x32_bf16 v[60:63], v[156:159], v[180:183], v[60:63]
	v_mfma_f32_16x16x32_bf16 v[48:51], v[148:151], v[198:201], v[48:51]
	v_mfma_f32_16x16x32_bf16 v[44:47], v[156:159], v[198:201], v[44:47]
	v_mfma_f32_16x16x32_bf16 v[32:35], v[148:151], v[206:209], v[32:35]
	v_mfma_f32_16x16x32_bf16 v[28:31], v[156:159], v[206:209], v[28:31]
	v_mfma_f32_16x16x32_bf16 v[16:19], v[148:151], v[224:227], v[16:19]
	v_mfma_f32_16x16x32_bf16 v[12:15], v[156:159], v[224:227], v[12:15]
	s_setprio 0
	s_setprio 1
	v_mfma_f32_16x16x32_bf16 v[56:59], v[160:163], v[176:179], v[56:59]
	v_mfma_f32_16x16x32_bf16 v[52:55], v[168:171], v[176:179], v[52:55]
	v_mfma_f32_16x16x32_bf16 v[40:43], v[160:163], v[194:197], v[40:43]
	v_mfma_f32_16x16x32_bf16 v[36:39], v[168:171], v[194:197], v[36:39]
	v_mfma_f32_16x16x32_bf16 v[24:27], v[160:163], v[202:205], v[24:27]
	v_mfma_f32_16x16x32_bf16 v[20:23], v[168:171], v[202:205], v[20:23]
	v_mfma_f32_16x16x32_bf16 v[8:11], v[160:163], v[220:223], v[8:11]
	v_mfma_f32_16x16x32_bf16 v[4:7], v[168:171], v[220:223], v[4:7]
	v_mfma_f32_16x16x32_bf16 v[56:59], v[164:167], v[180:183], v[56:59]
	v_mfma_f32_16x16x32_bf16 v[52:55], v[172:175], v[180:183], v[52:55]
	v_mfma_f32_16x16x32_bf16 v[40:43], v[164:167], v[198:201], v[40:43]
	v_mfma_f32_16x16x32_bf16 v[36:39], v[172:175], v[198:201], v[36:39]
	v_mfma_f32_16x16x32_bf16 v[24:27], v[164:167], v[206:209], v[24:27]
	v_mfma_f32_16x16x32_bf16 v[20:23], v[172:175], v[206:209], v[20:23]
	v_mfma_f32_16x16x32_bf16 v[8:11], v[164:167], v[224:227], v[8:11]
	v_mfma_f32_16x16x32_bf16 v[4:7], v[172:175], v[224:227], v[4:7]
	s_setprio 0
	s_barrier
	s_add_i32 s28, s82, 0x100
	v_add_u32_e32 v2, s28, v142
	s_add_i32 s29, s78, 0x100
	ds_read_b128 v[144:147], v2
	ds_read_b128 v[148:151], v2 offset:1024
	ds_read_b128 v[152:155], v2 offset:2048
	ds_read_b128 v[156:159], v2 offset:3072
	v_add_u32_e32 v2, s29, v142
	ds_read_b128 v[160:163], v2
	ds_read_b128 v[164:167], v2 offset:1024
	ds_read_b128 v[168:171], v2 offset:2048
	ds_read_b128 v[172:175], v2 offset:3072
	s_add_u32 s50, s50, s58
	s_addc_u32 s51, s51, s59
	s_mov_b32 m0, s88
	v_lshl_add_u64 v[234:235], s[50:51], 0, v[136:137]
	ds_read_b128 v[176:179], v143 offset:32768
	ds_read_b128 v[180:183], v143 offset:33792
	ds_read_b128 v[194:197], v143 offset:34816
	ds_read_b128 v[198:201], v143 offset:35840
	ds_read_b128 v[202:205], v143 offset:36864
	ds_read_b128 v[206:209], v143 offset:37888
	ds_read_b128 v[220:223], v143 offset:38912
	ds_read_b128 v[224:227], v143 offset:39936
	global_load_lds_dwordx4 v[234:235], off
	v_lshl_add_u64 v[234:235], s[50:51], 0, v[132:133]
	s_mov_b32 m0, s89
	s_nop 0
	global_load_lds_dwordx4 v[234:235], off
	s_waitcnt vmcnt(8)
	s_waitcnt lgkmcnt(0)
	s_barrier
	s_setprio 1
	s_waitcnt lgkmcnt(0)
	v_mfma_f32_16x16x32_bf16 v[128:131], v[144:147], v[176:179], v[128:131]
	v_mfma_f32_16x16x32_bf16 v[124:127], v[152:155], v[176:179], v[124:127]
	v_mfma_f32_16x16x32_bf16 v[112:115], v[144:147], v[194:197], v[112:115]
	v_mfma_f32_16x16x32_bf16 v[108:111], v[152:155], v[194:197], v[108:111]
	v_mfma_f32_16x16x32_bf16 v[96:99], v[144:147], v[202:205], v[96:99]
	v_mfma_f32_16x16x32_bf16 v[92:95], v[152:155], v[202:205], v[92:95]
	v_mfma_f32_16x16x32_bf16 v[80:83], v[144:147], v[220:223], v[80:83]
	v_mfma_f32_16x16x32_bf16 v[76:79], v[152:155], v[220:223], v[76:79]
	v_mfma_f32_16x16x32_bf16 v[128:131], v[148:151], v[180:183], v[128:131]
	v_mfma_f32_16x16x32_bf16 v[124:127], v[156:159], v[180:183], v[124:127]
	v_mfma_f32_16x16x32_bf16 v[112:115], v[148:151], v[198:201], v[112:115]
	v_mfma_f32_16x16x32_bf16 v[108:111], v[156:159], v[198:201], v[108:111]
	v_mfma_f32_16x16x32_bf16 v[96:99], v[148:151], v[206:209], v[96:99]
	v_mfma_f32_16x16x32_bf16 v[92:95], v[156:159], v[206:209], v[92:95]
	v_mfma_f32_16x16x32_bf16 v[80:83], v[148:151], v[224:227], v[80:83]
	v_mfma_f32_16x16x32_bf16 v[76:79], v[156:159], v[224:227], v[76:79]
	s_setprio 0
	s_setprio 1
	v_mfma_f32_16x16x32_bf16 v[120:123], v[160:163], v[176:179], v[120:123]
	v_mfma_f32_16x16x32_bf16 v[116:119], v[168:171], v[176:179], v[116:119]
	v_mfma_f32_16x16x32_bf16 v[104:107], v[160:163], v[194:197], v[104:107]
	v_mfma_f32_16x16x32_bf16 v[100:103], v[168:171], v[194:197], v[100:103]
	v_mfma_f32_16x16x32_bf16 v[88:91], v[160:163], v[202:205], v[88:91]
	v_mfma_f32_16x16x32_bf16 v[84:87], v[168:171], v[202:205], v[84:87]
	v_mfma_f32_16x16x32_bf16 v[72:75], v[160:163], v[220:223], v[72:75]
	v_mfma_f32_16x16x32_bf16 v[68:71], v[168:171], v[220:223], v[68:71]
	v_mfma_f32_16x16x32_bf16 v[120:123], v[164:167], v[180:183], v[120:123]
	v_mfma_f32_16x16x32_bf16 v[116:119], v[172:175], v[180:183], v[116:119]
	v_mfma_f32_16x16x32_bf16 v[104:107], v[164:167], v[198:201], v[104:107]
	v_mfma_f32_16x16x32_bf16 v[100:103], v[172:175], v[198:201], v[100:103]
	v_mfma_f32_16x16x32_bf16 v[88:91], v[164:167], v[206:209], v[88:91]
	v_mfma_f32_16x16x32_bf16 v[84:87], v[172:175], v[206:209], v[84:87]
	v_mfma_f32_16x16x32_bf16 v[72:75], v[164:167], v[224:227], v[72:75]
	v_mfma_f32_16x16x32_bf16 v[68:71], v[172:175], v[224:227], v[68:71]
	s_setprio 0
	s_barrier
; #define PG8_STAGE(bufoff, gbase, voff) do { _Pragma("unroll") for (int _i = 0; _i < 2; ++_i) \
;         __builtin_amdgcn_global_load_lds((const unsigned*)((const char*)(gbase) + (voff)[_i]), (PG8_LAS unsigned*)(lds + (bufoff) + ldsw + _i * 8192), 16, 0, 0); } while (0)
; #define PG8_LDA(dst, b, h) do { _Pragma("unroll") for (int m = 0; m < 4; ++m) _Pragma("unroll") for (int k = 0; k < 2; ++k) dst[m][k] = *(const PG8_LAS bf16x8*)(lds + PG8_SA(b, h) + aoff + m * 2048 + k * 1024); } while (0)
; #define PG8_MMA(ai, bj, At, Bt) do { __builtin_amdgcn_s_setprio(1); _Pragma("unroll") for (int m = 0; m < 4; ++m) _Pragma("unroll") for (int n = 0; n < 2; ++n) _Pragma("unroll") for (int k = 0; k < 2; ++k) \
;         acc[ai][bj][m][n] = __builtin_amdgcn_mfma_f32_16x16x32_bf16(Bt[n][k], At[m][k], acc[ai][bj][m][n], 0, 0, 0); __builtin_amdgcn_s_setprio(0); } while (0)
; #define PG8_WAIT_V(n) asm volatile("s_waitcnt vmcnt(" #n ")" ::: "memory")
; #define PG8_WAIT_L(n) asm volatile("s_waitcnt lgkmcnt(" #n ")" ::: "memory")
; #define PG8_BAR __builtin_amdgcn_s_barrier()
; #define PG8_SCHED __builtin_amdgcn_sched_barrier(0)
; template <class Epi, class Sched, bool ALIGN_EPI = false, bool SP2 = false>
; __device__ __forceinline__ void gemm_phase(PG8_LAS unsigned char* lds, const Gemm g, const Sched& S, const Epi& E) {
;     ...
;         for (int t = 0; t < nt; t += 2) {
;     ...
;             PG8_LDA(At, 1, 1); PG8_STAGE(PG8_SB(1, 0), b3, voffB); PG8_STAGE(PG8_SB(1, 1), b3 + hstep, voffB); PG8_STAGE(PG8_SA(1, 0), a3, voffA);
;             PG8_WAIT_V(8); PG8_WAIT_L(0); PG8_BAR; PG8_MMA(1, 0, At, B0); PG8_MMA(1, 1, At, B1); PG8_BAR; PG8_SCHED;
	s_add_i32 s28, s28, s18
	v_lshl_add_u64 v[210:211], v[210:211], 0, s[8:9]
	s_mov_b32 m0, s28
	ds_read_b128 v[176:179], v143 offset:49152
	ds_read_b128 v[180:183], v143 offset:50176
	ds_read_b128 v[194:197], v143 offset:51200
	ds_read_b128 v[198:201], v143 offset:52224
	ds_read_b128 v[202:205], v143 offset:53248
	ds_read_b128 v[206:209], v143 offset:54272
	ds_read_b128 v[220:223], v143 offset:55296
	ds_read_b128 v[224:227], v143 offset:56320
	global_load_lds_dwordx4 v[210:211], off
	v_lshl_add_u64 v[210:211], v[214:215], 0, s[8:9]
	s_add_i32 m0, s28, 0x2000
	s_add_i32 s28, s29, s18
	global_load_lds_dwordx4 v[210:211], off
	v_lshl_add_u64 v[210:211], v[218:219], 0, s[8:9]
	s_mov_b32 m0, s28
	s_nop 0
	global_load_lds_dwordx4 v[210:211], off
	v_lshl_add_u64 v[210:211], v[228:229], 0, s[8:9]
	s_add_i32 m0, s28, 0x2000
	s_nop 0
	global_load_lds_dwordx4 v[210:211], off
	v_lshl_add_u64 v[210:211], v[230:231], 0, s[8:9]
	s_mov_b32 m0, s90
	s_nop 0
	global_load_lds_dwordx4 v[210:211], off
	v_lshl_add_u64 v[210:211], v[232:233], 0, s[8:9]
	s_mov_b32 m0, s91
	s_nop 0
	global_load_lds_dwordx4 v[210:211], off
	s_waitcnt vmcnt(8)
	s_waitcnt lgkmcnt(0)
	s_barrier
	s_setprio 1
	s_waitcnt lgkmcnt(0)
	v_mfma_f32_16x16x32_bf16 v[64:67], v[144:147], v[176:179], v[64:67]
	v_mfma_f32_16x16x32_bf16 v[60:63], v[152:155], v[176:179], v[60:63]
	v_mfma_f32_16x16x32_bf16 v[48:51], v[144:147], v[194:197], v[48:51]
	v_mfma_f32_16x16x32_bf16 v[44:47], v[152:155], v[194:197], v[44:47]
	v_mfma_f32_16x16x32_bf16 v[32:35], v[144:147], v[202:205], v[32:35]
	v_mfma_f32_16x16x32_bf16 v[28:31], v[152:155], v[202:205], v[28:31]
	v_mfma_f32_16x16x32_bf16 v[16:19], v[144:147], v[220:223], v[16:19]
	v_mfma_f32_16x16x32_bf16 v[12:15], v[152:155], v[220:223], v[12:15]
	v_mfma_f32_16x16x32_bf16 v[64:67], v[148:151], v[180:183], v[64:67]
	v_mfma_f32_16x16x32_bf16 v[60:63], v[156:159], v[180:183], v[60:63]
	v_mfma_f32_16x16x32_bf16 v[48:51], v[148:151], v[198:201], v[48:51]
	v_mfma_f32_16x16x32_bf16 v[44:47], v[156:159], v[198:201], v[44:47]
	v_mfma_f32_16x16x32_bf16 v[32:35], v[148:151], v[206:209], v[32:35]
	v_mfma_f32_16x16x32_bf16 v[28:31], v[156:159], v[206:209], v[28:31]
	v_mfma_f32_16x16x32_bf16 v[16:19], v[148:151], v[224:227], v[16:19]
	v_mfma_f32_16x16x32_bf16 v[12:15], v[156:159], v[224:227], v[12:15]
	s_setprio 0
	s_setprio 1
	v_mfma_f32_16x16x32_bf16 v[56:59], v[160:163], v[176:179], v[56:59]
	v_mfma_f32_16x16x32_bf16 v[52:55], v[168:171], v[176:179], v[52:55]
	v_mfma_f32_16x16x32_bf16 v[40:43], v[160:163], v[194:197], v[40:43]
	v_mfma_f32_16x16x32_bf16 v[36:39], v[168:171], v[194:197], v[36:39]
	v_mfma_f32_16x16x32_bf16 v[24:27], v[160:163], v[202:205], v[24:27]
	v_mfma_f32_16x16x32_bf16 v[20:23], v[168:171], v[202:205], v[20:23]
	v_mfma_f32_16x16x32_bf16 v[8:11], v[160:163], v[220:223], v[8:11]
	v_mfma_f32_16x16x32_bf16 v[4:7], v[168:171], v[220:223], v[4:7]
	v_mfma_f32_16x16x32_bf16 v[56:59], v[164:167], v[180:183], v[56:59]
	v_mfma_f32_16x16x32_bf16 v[52:55], v[172:175], v[180:183], v[52:55]
	v_mfma_f32_16x16x32_bf16 v[40:43], v[164:167], v[198:201], v[40:43]
	v_mfma_f32_16x16x32_bf16 v[36:39], v[172:175], v[198:201], v[36:39]
	v_mfma_f32_16x16x32_bf16 v[24:27], v[164:167], v[206:209], v[24:27]
	v_mfma_f32_16x16x32_bf16 v[20:23], v[172:175], v[206:209], v[20:23]
	v_mfma_f32_16x16x32_bf16 v[8:11], v[164:167], v[224:227], v[8:11]
	v_mfma_f32_16x16x32_bf16 v[4:7], v[172:175], v[224:227], v[4:7]
	s_add_u32 s25, s25, 0x100
	s_addc_u32 s92, s92, 0
	s_add_u32 s46, s46, 0x100
	s_addc_u32 s47, s47, 0
	s_cmp_ge_i32 s93, s26
	s_mov_b32 s50, s93
	s_setprio 0
	s_barrier
	s_cbranch_scc0 .LBB0_80

; #define PG8_STAGE(bufoff, gbase, voff) do { _Pragma("unroll") for (int _i = 0; _i < 2; ++_i) \
;         __builtin_amdgcn_global_load_lds((const unsigned*)((const char*)(gbase) + (voff)[_i]), (PG8_LAS unsigned*)(lds + (bufoff) + ldsw + _i * 8192), 16, 0, 0); } while (0)
; #define PG8_LDA(dst, b, h) do { _Pragma("unroll") for (int m = 0; m < 4; ++m) _Pragma("unroll") for (int k = 0; k < 2; ++k) dst[m][k] = *(const PG8_LAS bf16x8*)(lds + PG8_SA(b, h) + aoff + m * 2048 + k * 1024); } while (0)
; #define PG8_LDB(dst, b, h) do { _Pragma("unroll") for (int n = 0; n < 2; ++n) _Pragma("unroll") for (int k = 0; k < 2; ++k) dst[n][k] = *(const PG8_LAS bf16x8*)(lds + PG8_SB(b, h) + boff + n * 2048 + k * 1024); } while (0)
; #define PG8_MMA(ai, bj, At, Bt) do { __builtin_amdgcn_s_setprio(1); _Pragma("unroll") for (int m = 0; m < 4; ++m) _Pragma("unroll") for (int n = 0; n < 2; ++n) _Pragma("unroll") for (int k = 0; k < 2; ++k) \
;         acc[ai][bj][m][n] = __builtin_amdgcn_mfma_f32_16x16x32_bf16(Bt[n][k], At[m][k], acc[ai][bj][m][n], 0, 0, 0); __builtin_amdgcn_s_setprio(0); } while (0)
; #define PG8_WAIT_V(n) asm volatile("s_waitcnt vmcnt(" #n ")" ::: "memory")
; #define PG8_BAR __builtin_amdgcn_s_barrier()
; template <class Epi, class Sched, bool ALIGN_EPI = false, bool SP2 = false>
; __device__ __forceinline__ void gemm_phase(PG8_LAS unsigned char* lds, const Gemm g, const Sched& S, const Epi& E) {
;     ...
;         for (int t = 0; t < nt; t += 2) {
;             const bool last = (t == nt - 2);
;             const char* a1 = cA + (size_t)(t + 1) * kstep;
;             const char* a2 = last ? nA : cA + (size_t)(t + 2) * kstep; const char* b2 = last ? nB : cB + (size_t)(t + 2) * kstep;
;             const char* a3 = a2 + kstep; const char* b3 = b2 + kstep;
;             if (last && has_next) S.a_ready(nxt);
;             if constexpr (SP2) {
;             PG8_LDB(B0, 0, 0); PG8_LDB(B1, 0, 1); PG8_SCHED; PG8_LDA(At, 0, 0); PG8_STAGE(PG8_SA(1, 1), a1 + hstep, voffA);
;             PG8_WAIT_V(8); PG8_WAIT_L(0); PG8_BAR; PG8_MMA(0, 0, At, B0); PG8_MMA(0, 1, At, B1); PG8_BAR; PG8_SCHED;
;             PG8_LDA(At, 0, 1); PG8_STAGE(PG8_SB(0, 0), b2, voffB); PG8_STAGE(PG8_SB(0, 1), b2 + hstep, voffB); PG8_STAGE(PG8_SA(0, 0), a2, voffA);
;             PG8_WAIT_V(8); PG8_WAIT_L(0); PG8_BAR; PG8_MMA(1, 0, At, B0); PG8_MMA(1, 1, At, B1); PG8_BAR; PG8_SCHED;
.LBB0_105:
	ds_read_b128 v[176:179], v147
	ds_read_b128 v[180:183], v147 offset:1024
	ds_read_b128 v[194:197], v147 offset:2048
	ds_read_b128 v[198:201], v147 offset:3072
	ds_read_b128 v[202:205], v147 offset:4096
	ds_read_b128 v[206:209], v147 offset:5120
	ds_read_b128 v[220:223], v147 offset:6144
	ds_read_b128 v[224:227], v147 offset:7168
	s_add_i32 s51, s33, 0x100
	v_add_u32_e32 v2, s51, v146
	ds_read_b128 v[142:145], v2
	ds_read_b128 v[148:151], v2 offset:1024
	ds_read_b128 v[152:155], v2 offset:2048
	ds_read_b128 v[156:159], v2 offset:3072
	s_add_i32 s50, s46, 2
	s_add_u32 s28, s42, 0x80
	s_addc_u32 s29, s43, 0
	s_cmp_eq_u32 s89, s46
	s_cselect_b32 s47, s71, s29
	s_cselect_b32 s46, s70, s28
	s_cselect_b32 s29, s93, vcc_hi
	s_cselect_b32 s28, s92, vcc_lo
	s_add_i32 s74, s21, 0x100
	v_add_u32_e32 v2, s74, v146
	ds_read_b128 v[160:163], v2
	ds_read_b128 v[164:167], v2 offset:1024
	ds_read_b128 v[168:171], v2 offset:2048
	ds_read_b128 v[172:175], v2 offset:3072
	v_lshl_add_u64 v[210:211], s[42:43], 0, v[140:141]
	s_add_i32 m0, s18, 0xc000
	global_load_lds_dwordx4 v[210:211], off
	v_lshl_add_u64 v[210:211], s[42:43], 0, v[138:139]
	s_add_i32 m0, s18, 0xe000
	s_nop 0
	global_load_lds_dwordx4 v[210:211], off
	s_waitcnt vmcnt(8)
	s_waitcnt lgkmcnt(0)
	s_barrier
	s_setprio 1
	s_waitcnt lgkmcnt(0)
	v_mfma_f32_16x16x32_bf16 v[128:131], v[142:145], v[176:179], v[128:131]
	v_mfma_f32_16x16x32_bf16 v[124:127], v[152:155], v[176:179], v[124:127]
	v_mfma_f32_16x16x32_bf16 v[112:115], v[142:145], v[194:197], v[112:115]
	v_mfma_f32_16x16x32_bf16 v[108:111], v[152:155], v[194:197], v[108:111]
	v_mfma_f32_16x16x32_bf16 v[96:99], v[142:145], v[202:205], v[96:99]
	v_mfma_f32_16x16x32_bf16 v[92:95], v[152:155], v[202:205], v[92:95]
	v_mfma_f32_16x16x32_bf16 v[80:83], v[142:145], v[220:223], v[80:83]
	v_mfma_f32_16x16x32_bf16 v[76:79], v[152:155], v[220:223], v[76:79]
	v_mfma_f32_16x16x32_bf16 v[128:131], v[148:151], v[180:183], v[128:131]
	v_mfma_f32_16x16x32_bf16 v[124:127], v[156:159], v[180:183], v[124:127]
	v_mfma_f32_16x16x32_bf16 v[112:115], v[148:151], v[198:201], v[112:115]
	v_mfma_f32_16x16x32_bf16 v[108:111], v[156:159], v[198:201], v[108:111]
	v_mfma_f32_16x16x32_bf16 v[96:99], v[148:151], v[206:209], v[96:99]
	v_mfma_f32_16x16x32_bf16 v[92:95], v[156:159], v[206:209], v[92:95]
	v_mfma_f32_16x16x32_bf16 v[80:83], v[148:151], v[224:227], v[80:83]
	v_mfma_f32_16x16x32_bf16 v[76:79], v[156:159], v[224:227], v[76:79]
	s_setprio 0
	s_setprio 1
	v_mfma_f32_16x16x32_bf16 v[120:123], v[160:163], v[176:179], v[120:123]
	v_mfma_f32_16x16x32_bf16 v[116:119], v[168:171], v[176:179], v[116:119]
	v_mfma_f32_16x16x32_bf16 v[104:107], v[160:163], v[194:197], v[104:107]
	v_mfma_f32_16x16x32_bf16 v[100:103], v[168:171], v[194:197], v[100:103]
	v_mfma_f32_16x16x32_bf16 v[88:91], v[160:163], v[202:205], v[88:91]
	v_mfma_f32_16x16x32_bf16 v[84:87], v[168:171], v[202:205], v[84:87]
	v_mfma_f32_16x16x32_bf16 v[72:75], v[160:163], v[220:223], v[72:75]
	v_mfma_f32_16x16x32_bf16 v[68:71], v[168:171], v[220:223], v[68:71]
	v_mfma_f32_16x16x32_bf16 v[120:123], v[164:167], v[180:183], v[120:123]
	v_mfma_f32_16x16x32_bf16 v[116:119], v[172:175], v[180:183], v[116:119]
	v_mfma_f32_16x16x32_bf16 v[104:107], v[164:167], v[198:201], v[104:107]
	v_mfma_f32_16x16x32_bf16 v[100:103], v[172:175], v[198:201], v[100:103]
	v_mfma_f32_16x16x32_bf16 v[88:91], v[164:167], v[206:209], v[88:91]
	v_mfma_f32_16x16x32_bf16 v[84:87], v[172:175], v[206:209], v[84:87]
	v_mfma_f32_16x16x32_bf16 v[72:75], v[164:167], v[224:227], v[72:75]
	v_mfma_f32_16x16x32_bf16 v[68:71], v[172:175], v[224:227], v[68:71]
	s_setprio 0
	s_barrier
	s_add_i32 s51, s51, s15
	v_lshl_add_u64 v[210:211], s[28:29], 0, v[134:135]
	s_mov_b32 m0, s51
	ds_read_b128 v[176:179], v147 offset:16384
	ds_read_b128 v[180:183], v147 offset:17408
	ds_read_b128 v[194:197], v147 offset:18432
	ds_read_b128 v[198:201], v147 offset:19456
	ds_read_b128 v[202:205], v147 offset:20480
	ds_read_b128 v[206:209], v147 offset:21504
	ds_read_b128 v[220:223], v147 offset:22528
	ds_read_b128 v[224:227], v147 offset:23552
	global_load_lds_dwordx4 v[210:211], off
	s_add_i32 m0, s51, 0x2000
	v_lshl_add_u64 v[214:215], s[28:29], 0, v[0:1]
	s_add_u32 s28, s28, s58
	s_addc_u32 s29, s29, s59
	s_add_i32 s51, s74, s15
	global_load_lds_dwordx4 v[214:215], off
	v_lshl_add_u64 v[218:219], s[28:29], 0, v[134:135]
	s_mov_b32 m0, s51
	v_lshl_add_u64 v[228:229], s[28:29], 0, v[0:1]
	global_load_lds_dwordx4 v[218:219], off
	s_add_i32 m0, s51, 0x2000
	v_lshl_add_u64 v[230:231], s[46:47], 0, v[136:137]
	global_load_lds_dwordx4 v[228:229], off
	s_mov_b32 m0, s18
	v_lshl_add_u64 v[232:233], s[46:47], 0, v[132:133]
	global_load_lds_dwordx4 v[230:231], off
	s_mov_b32 m0, s19
	s_nop 0
	global_load_lds_dwordx4 v[232:233], off
	s_waitcnt vmcnt(8)
	s_waitcnt lgkmcnt(0)
	s_barrier
; #define PG8_STAGE(bufoff, gbase, voff) do { _Pragma("unroll") for (int _i = 0; _i < 2; ++_i) \
;         __builtin_amdgcn_global_load_lds((const unsigned*)((const char*)(gbase) + (voff)[_i]), (PG8_LAS unsigned*)(lds + (bufoff) + ldsw + _i * 8192), 16, 0, 0); } while (0)
; #define PG8_LDA(dst, b, h) do { _Pragma("unroll") for (int m = 0; m < 4; ++m) _Pragma("unroll") for (int k = 0; k < 2; ++k) dst[m][k] = *(const PG8_LAS bf16x8*)(lds + PG8_SA(b, h) + aoff + m * 2048 + k * 1024); } while (0)
; #define PG8_LDB(dst, b, h) do { _Pragma("unroll") for (int n = 0; n < 2; ++n) _Pragma("unroll") for (int k = 0; k < 2; ++k) dst[n][k] = *(const PG8_LAS bf16x8*)(lds + PG8_SB(b, h) + boff + n * 2048 + k * 1024); } while (0)
; #define PG8_MMA(ai, bj, At, Bt) do { __builtin_amdgcn_s_setprio(1); _Pragma("unroll") for (int m = 0; m < 4; ++m) _Pragma("unroll") for (int n = 0; n < 2; ++n) _Pragma("unroll") for (int k = 0; k < 2; ++k) \
;         acc[ai][bj][m][n] = __builtin_amdgcn_mfma_f32_16x16x32_bf16(Bt[n][k], At[m][k], acc[ai][bj][m][n], 0, 0, 0); __builtin_amdgcn_s_setprio(0); } while (0)
; #define PG8_WAIT_V(n) asm volatile("s_waitcnt vmcnt(" #n ")" ::: "memory")
; #define PG8_WAIT_L(n) asm volatile("s_waitcnt lgkmcnt(" #n ")" ::: "memory")
; #define PG8_BAR __builtin_amdgcn_s_barrier()
; #define PG8_SCHED __builtin_amdgcn_sched_barrier(0)
; template <class Epi, class Sched, bool ALIGN_EPI = false, bool SP2 = false>
; __device__ __forceinline__ void gemm_phase(PG8_LAS unsigned char* lds, const Gemm g, const Sched& S, const Epi& E) {
;     ...
;             PG8_WAIT_V(8); PG8_WAIT_L(0); PG8_BAR; PG8_MMA(1, 0, At, B0); PG8_MMA(1, 1, At, B1); PG8_BAR; PG8_SCHED;
;             PG8_LDB(B0, 1, 0); PG8_LDB(B1, 1, 1); PG8_SCHED; PG8_LDA(At, 1, 0); PG8_STAGE(PG8_SA(0, 1), a2 + hstep, voffA);
;             PG8_WAIT_V(8); PG8_WAIT_L(0); PG8_BAR; PG8_MMA(0, 0, At, B0); PG8_MMA(0, 1, At, B1); PG8_BAR; PG8_SCHED;
	s_setprio 1
	s_waitcnt lgkmcnt(0)
	v_mfma_f32_16x16x32_bf16 v[64:67], v[142:145], v[176:179], v[64:67]
	v_mfma_f32_16x16x32_bf16 v[60:63], v[152:155], v[176:179], v[60:63]
	v_mfma_f32_16x16x32_bf16 v[48:51], v[142:145], v[194:197], v[48:51]
	v_mfma_f32_16x16x32_bf16 v[44:47], v[152:155], v[194:197], v[44:47]
	v_mfma_f32_16x16x32_bf16 v[32:35], v[142:145], v[202:205], v[32:35]
	v_mfma_f32_16x16x32_bf16 v[28:31], v[152:155], v[202:205], v[28:31]
	v_mfma_f32_16x16x32_bf16 v[16:19], v[142:145], v[220:223], v[16:19]
	v_mfma_f32_16x16x32_bf16 v[12:15], v[152:155], v[220:223], v[12:15]
	v_mfma_f32_16x16x32_bf16 v[64:67], v[148:151], v[180:183], v[64:67]
	v_mfma_f32_16x16x32_bf16 v[60:63], v[156:159], v[180:183], v[60:63]
	v_mfma_f32_16x16x32_bf16 v[48:51], v[148:151], v[198:201], v[48:51]
	v_mfma_f32_16x16x32_bf16 v[44:47], v[156:159], v[198:201], v[44:47]
	v_mfma_f32_16x16x32_bf16 v[32:35], v[148:151], v[206:209], v[32:35]
	v_mfma_f32_16x16x32_bf16 v[28:31], v[156:159], v[206:209], v[28:31]
	v_mfma_f32_16x16x32_bf16 v[16:19], v[148:151], v[224:227], v[16:19]
	v_mfma_f32_16x16x32_bf16 v[12:15], v[156:159], v[224:227], v[12:15]
	s_setprio 0
	s_setprio 1
	v_mfma_f32_16x16x32_bf16 v[56:59], v[160:163], v[176:179], v[56:59]
	v_mfma_f32_16x16x32_bf16 v[52:55], v[168:171], v[176:179], v[52:55]
	v_mfma_f32_16x16x32_bf16 v[40:43], v[160:163], v[194:197], v[40:43]
	v_mfma_f32_16x16x32_bf16 v[36:39], v[168:171], v[194:197], v[36:39]
	v_mfma_f32_16x16x32_bf16 v[24:27], v[160:163], v[202:205], v[24:27]
	v_mfma_f32_16x16x32_bf16 v[20:23], v[168:171], v[202:205], v[20:23]
	v_mfma_f32_16x16x32_bf16 v[8:11], v[160:163], v[220:223], v[8:11]
	v_mfma_f32_16x16x32_bf16 v[4:7], v[168:171], v[220:223], v[4:7]
	v_mfma_f32_16x16x32_bf16 v[56:59], v[164:167], v[180:183], v[56:59]
	v_mfma_f32_16x16x32_bf16 v[52:55], v[172:175], v[180:183], v[52:55]
	v_mfma_f32_16x16x32_bf16 v[40:43], v[164:167], v[198:201], v[40:43]
	v_mfma_f32_16x16x32_bf16 v[36:39], v[172:175], v[198:201], v[36:39]
	v_mfma_f32_16x16x32_bf16 v[24:27], v[164:167], v[206:209], v[24:27]
	v_mfma_f32_16x16x32_bf16 v[20:23], v[172:175], v[206:209], v[20:23]
	v_mfma_f32_16x16x32_bf16 v[8:11], v[164:167], v[224:227], v[8:11]
	v_mfma_f32_16x16x32_bf16 v[4:7], v[172:175], v[224:227], v[4:7]
	s_setprio 0
	s_barrier
	s_add_i32 s51, s82, 0x100
	v_add_u32_e32 v2, s51, v146
	s_add_i32 s74, s78, 0x100
	ds_read_b128 v[142:145], v2
	ds_read_b128 v[148:151], v2 offset:1024
	ds_read_b128 v[152:155], v2 offset:2048
	ds_read_b128 v[156:159], v2 offset:3072
	v_add_u32_e32 v2, s74, v146
	ds_read_b128 v[160:163], v2
	ds_read_b128 v[164:167], v2 offset:1024
	ds_read_b128 v[168:171], v2 offset:2048
	ds_read_b128 v[172:175], v2 offset:3072
	s_add_u32 s28, s46, s58
	s_addc_u32 s29, s47, s59
	s_mov_b32 m0, s23
	v_lshl_add_u64 v[234:235], s[28:29], 0, v[136:137]
	ds_read_b128 v[176:179], v147 offset:32768
	ds_read_b128 v[180:183], v147 offset:33792
	ds_read_b128 v[194:197], v147 offset:34816
	ds_read_b128 v[198:201], v147 offset:35840
	ds_read_b128 v[202:205], v147 offset:36864
	ds_read_b128 v[206:209], v147 offset:37888
	ds_read_b128 v[220:223], v147 offset:38912
	ds_read_b128 v[224:227], v147 offset:39936
	global_load_lds_dwordx4 v[234:235], off
	v_lshl_add_u64 v[234:235], s[28:29], 0, v[132:133]
	s_mov_b32 m0, s26
	s_nop 0
	global_load_lds_dwordx4 v[234:235], off
	s_waitcnt vmcnt(8)
	s_waitcnt lgkmcnt(0)
	s_barrier
	s_setprio 1
	s_waitcnt lgkmcnt(0)
	v_mfma_f32_16x16x32_bf16 v[128:131], v[142:145], v[176:179], v[128:131]
	v_mfma_f32_16x16x32_bf16 v[124:127], v[152:155], v[176:179], v[124:127]
	v_mfma_f32_16x16x32_bf16 v[112:115], v[142:145], v[194:197], v[112:115]
	v_mfma_f32_16x16x32_bf16 v[108:111], v[152:155], v[194:197], v[108:111]
	v_mfma_f32_16x16x32_bf16 v[96:99], v[142:145], v[202:205], v[96:99]
	v_mfma_f32_16x16x32_bf16 v[92:95], v[152:155], v[202:205], v[92:95]
	v_mfma_f32_16x16x32_bf16 v[80:83], v[142:145], v[220:223], v[80:83]
	v_mfma_f32_16x16x32_bf16 v[76:79], v[152:155], v[220:223], v[76:79]
	v_mfma_f32_16x16x32_bf16 v[128:131], v[148:151], v[180:183], v[128:131]
	v_mfma_f32_16x16x32_bf16 v[124:127], v[156:159], v[180:183], v[124:127]
	v_mfma_f32_16x16x32_bf16 v[112:115], v[148:151], v[198:201], v[112:115]
	v_mfma_f32_16x16x32_bf16 v[108:111], v[156:159], v[198:201], v[108:111]
	v_mfma_f32_16x16x32_bf16 v[96:99], v[148:151], v[206:209], v[96:99]
	v_mfma_f32_16x16x32_bf16 v[92:95], v[156:159], v[206:209], v[92:95]
	v_mfma_f32_16x16x32_bf16 v[80:83], v[148:151], v[224:227], v[80:83]
	v_mfma_f32_16x16x32_bf16 v[76:79], v[156:159], v[224:227], v[76:79]
	s_setprio 0
	s_setprio 1
	v_mfma_f32_16x16x32_bf16 v[120:123], v[160:163], v[176:179], v[120:123]
	v_mfma_f32_16x16x32_bf16 v[116:119], v[168:171], v[176:179], v[116:119]
	v_mfma_f32_16x16x32_bf16 v[104:107], v[160:163], v[194:197], v[104:107]
	v_mfma_f32_16x16x32_bf16 v[100:103], v[168:171], v[194:197], v[100:103]
	v_mfma_f32_16x16x32_bf16 v[88:91], v[160:163], v[202:205], v[88:91]
	v_mfma_f32_16x16x32_bf16 v[84:87], v[168:171], v[202:205], v[84:87]
	v_mfma_f32_16x16x32_bf16 v[72:75], v[160:163], v[220:223], v[72:75]
	v_mfma_f32_16x16x32_bf16 v[68:71], v[168:171], v[220:223], v[68:71]
	v_mfma_f32_16x16x32_bf16 v[120:123], v[164:167], v[180:183], v[120:123]
	v_mfma_f32_16x16x32_bf16 v[116:119], v[172:175], v[180:183], v[116:119]
	v_mfma_f32_16x16x32_bf16 v[104:107], v[164:167], v[198:201], v[104:107]
	v_mfma_f32_16x16x32_bf16 v[100:103], v[172:175], v[198:201], v[100:103]
	v_mfma_f32_16x16x32_bf16 v[88:91], v[164:167], v[206:209], v[88:91]
	v_mfma_f32_16x16x32_bf16 v[84:87], v[172:175], v[206:209], v[84:87]
	v_mfma_f32_16x16x32_bf16 v[72:75], v[164:167], v[224:227], v[72:75]
	v_mfma_f32_16x16x32_bf16 v[68:71], v[172:175], v[224:227], v[68:71]
	s_setprio 0
	s_barrier
; #define PG8_STAGE(bufoff, gbase, voff) do { _Pragma("unroll") for (int _i = 0; _i < 2; ++_i) \
;         __builtin_amdgcn_global_load_lds((const unsigned*)((const char*)(gbase) + (voff)[_i]), (PG8_LAS unsigned*)(lds + (bufoff) + ldsw + _i * 8192), 16, 0, 0); } while (0)
; #define PG8_LDA(dst, b, h) do { _Pragma("unroll") for (int m = 0; m < 4; ++m) _Pragma("unroll") for (int k = 0; k < 2; ++k) dst[m][k] = *(const PG8_LAS bf16x8*)(lds + PG8_SA(b, h) + aoff + m * 2048 + k * 1024); } while (0)
; #define PG8_MMA(ai, bj, At, Bt) do { __builtin_amdgcn_s_setprio(1); _Pragma("unroll") for (int m = 0; m < 4; ++m) _Pragma("unroll") for (int n = 0; n < 2; ++n) _Pragma("unroll") for (int k = 0; k < 2; ++k) \
;         acc[ai][bj][m][n] = __builtin_amdgcn_mfma_f32_16x16x32_bf16(Bt[n][k], At[m][k], acc[ai][bj][m][n], 0, 0, 0); __builtin_amdgcn_s_setprio(0); } while (0)
; #define PG8_WAIT_V(n) asm volatile("s_waitcnt vmcnt(" #n ")" ::: "memory")
; #define PG8_WAIT_L(n) asm volatile("s_waitcnt lgkmcnt(" #n ")" ::: "memory")
; #define PG8_BAR __builtin_amdgcn_s_barrier()
; #define PG8_SCHED __builtin_amdgcn_sched_barrier(0)
; template <class Epi, class Sched, bool ALIGN_EPI = false, bool SP2 = false>
; __device__ __forceinline__ void gemm_phase(PG8_LAS unsigned char* lds, const Gemm g, const Sched& S, const Epi& E) {
;     ...
;         for (int t = 0; t < nt; t += 2) {
;     ...
;             PG8_LDA(At, 1, 1); PG8_STAGE(PG8_SB(1, 0), b3, voffB); PG8_STAGE(PG8_SB(1, 1), b3 + hstep, voffB); PG8_STAGE(PG8_SA(1, 0), a3, voffA);
;             PG8_WAIT_V(8); PG8_WAIT_L(0); PG8_BAR; PG8_MMA(1, 0, At, B0); PG8_MMA(1, 1, At, B1); PG8_BAR; PG8_SCHED;
	s_add_i32 s28, s51, s15
	v_lshl_add_u64 v[210:211], v[210:211], 0, s[8:9]
	s_mov_b32 m0, s28
	ds_read_b128 v[176:179], v147 offset:49152
	ds_read_b128 v[180:183], v147 offset:50176
	ds_read_b128 v[194:197], v147 offset:51200
	ds_read_b128 v[198:201], v147 offset:52224
	ds_read_b128 v[202:205], v147 offset:53248
	ds_read_b128 v[206:209], v147 offset:54272
	ds_read_b128 v[220:223], v147 offset:55296
	ds_read_b128 v[224:227], v147 offset:56320
	global_load_lds_dwordx4 v[210:211], off
	v_lshl_add_u64 v[210:211], v[214:215], 0, s[8:9]
	s_add_i32 m0, s28, 0x2000
	s_add_i32 s28, s74, s15
	global_load_lds_dwordx4 v[210:211], off
	v_lshl_add_u64 v[210:211], v[218:219], 0, s[8:9]
	s_mov_b32 m0, s28
	s_nop 0
	global_load_lds_dwordx4 v[210:211], off
	v_lshl_add_u64 v[210:211], v[228:229], 0, s[8:9]
	s_add_i32 m0, s28, 0x2000
	s_nop 0
	global_load_lds_dwordx4 v[210:211], off
	v_lshl_add_u64 v[210:211], v[230:231], 0, s[8:9]
	s_mov_b32 m0, s27
	s_nop 0
	global_load_lds_dwordx4 v[210:211], off
	v_lshl_add_u64 v[210:211], v[232:233], 0, s[8:9]
	s_mov_b32 m0, s30
	s_nop 0
	global_load_lds_dwordx4 v[210:211], off
	s_waitcnt vmcnt(8)
	s_waitcnt lgkmcnt(0)
	s_barrier
	s_setprio 1
	s_waitcnt lgkmcnt(0)
	v_mfma_f32_16x16x32_bf16 v[64:67], v[142:145], v[176:179], v[64:67]
	v_mfma_f32_16x16x32_bf16 v[60:63], v[152:155], v[176:179], v[60:63]
	v_mfma_f32_16x16x32_bf16 v[48:51], v[142:145], v[194:197], v[48:51]
	v_mfma_f32_16x16x32_bf16 v[44:47], v[152:155], v[194:197], v[44:47]
	v_mfma_f32_16x16x32_bf16 v[32:35], v[142:145], v[202:205], v[32:35]
	v_mfma_f32_16x16x32_bf16 v[28:31], v[152:155], v[202:205], v[28:31]
	v_mfma_f32_16x16x32_bf16 v[16:19], v[142:145], v[220:223], v[16:19]
	v_mfma_f32_16x16x32_bf16 v[12:15], v[152:155], v[220:223], v[12:15]
	v_mfma_f32_16x16x32_bf16 v[64:67], v[148:151], v[180:183], v[64:67]
	v_mfma_f32_16x16x32_bf16 v[60:63], v[156:159], v[180:183], v[60:63]
	v_mfma_f32_16x16x32_bf16 v[48:51], v[148:151], v[198:201], v[48:51]
	v_mfma_f32_16x16x32_bf16 v[44:47], v[156:159], v[198:201], v[44:47]
	v_mfma_f32_16x16x32_bf16 v[32:35], v[148:151], v[206:209], v[32:35]
	v_mfma_f32_16x16x32_bf16 v[28:31], v[156:159], v[206:209], v[28:31]
	v_mfma_f32_16x16x32_bf16 v[16:19], v[148:151], v[224:227], v[16:19]
	v_mfma_f32_16x16x32_bf16 v[12:15], v[156:159], v[224:227], v[12:15]
	s_setprio 0
	s_setprio 1
	v_mfma_f32_16x16x32_bf16 v[56:59], v[160:163], v[176:179], v[56:59]
	v_mfma_f32_16x16x32_bf16 v[52:55], v[168:171], v[176:179], v[52:55]
	v_mfma_f32_16x16x32_bf16 v[40:43], v[160:163], v[194:197], v[40:43]
	v_mfma_f32_16x16x32_bf16 v[36:39], v[168:171], v[194:197], v[36:39]
	v_mfma_f32_16x16x32_bf16 v[24:27], v[160:163], v[202:205], v[24:27]
	v_mfma_f32_16x16x32_bf16 v[20:23], v[168:171], v[202:205], v[20:23]
	v_mfma_f32_16x16x32_bf16 v[8:11], v[160:163], v[220:223], v[8:11]
	v_mfma_f32_16x16x32_bf16 v[4:7], v[168:171], v[220:223], v[4:7]
	v_mfma_f32_16x16x32_bf16 v[56:59], v[164:167], v[180:183], v[56:59]
	v_mfma_f32_16x16x32_bf16 v[52:55], v[172:175], v[180:183], v[52:55]
	v_mfma_f32_16x16x32_bf16 v[40:43], v[164:167], v[198:201], v[40:43]
	v_mfma_f32_16x16x32_bf16 v[36:39], v[172:175], v[198:201], v[36:39]
	v_mfma_f32_16x16x32_bf16 v[24:27], v[164:167], v[206:209], v[24:27]
	v_mfma_f32_16x16x32_bf16 v[20:23], v[172:175], v[206:209], v[20:23]
	v_mfma_f32_16x16x32_bf16 v[8:11], v[164:167], v[224:227], v[8:11]
	v_mfma_f32_16x16x32_bf16 v[4:7], v[172:175], v[224:227], v[4:7]
	s_add_u32 vcc_lo, vcc_lo, 0x100
	s_addc_u32 vcc_hi, vcc_hi, 0
	s_add_u32 s42, s42, 0x100
	s_addc_u32 s43, s43, 0
	s_cmp_ge_i32 s50, s76
	s_mov_b32 s46, s50
	s_setprio 0
	s_barrier
	s_cbranch_scc0 .LBB0_105

; #define PG8_STAGE(bufoff, gbase, voff) do { _Pragma("unroll") for (int _i = 0; _i < 2; ++_i) \
;         __builtin_amdgcn_global_load_lds((const unsigned*)((const char*)(gbase) + (voff)[_i]), (PG8_LAS unsigned*)(lds + (bufoff) + ldsw + _i * 8192), 16, 0, 0); } while (0)
; #define PG8_LDA(dst, b, h) do { _Pragma("unroll") for (int m = 0; m < 4; ++m) _Pragma("unroll") for (int k = 0; k < 2; ++k) dst[m][k] = *(const PG8_LAS bf16x8*)(lds + PG8_SA(b, h) + aoff + m * 2048 + k * 1024); } while (0)
; #define PG8_LDB(dst, b, h) do { _Pragma("unroll") for (int n = 0; n < 2; ++n) _Pragma("unroll") for (int k = 0; k < 2; ++k) dst[n][k] = *(const PG8_LAS bf16x8*)(lds + PG8_SB(b, h) + boff + n * 2048 + k * 1024); } while (0)
; #define PG8_MMA(ai, bj, At, Bt) do { __builtin_amdgcn_s_setprio(1); _Pragma("unroll") for (int m = 0; m < 4; ++m) _Pragma("unroll") for (int n = 0; n < 2; ++n) _Pragma("unroll") for (int k = 0; k < 2; ++k) \
;         acc[ai][bj][m][n] = __builtin_amdgcn_mfma_f32_16x16x32_bf16(Bt[n][k], At[m][k], acc[ai][bj][m][n], 0, 0, 0); __builtin_amdgcn_s_setprio(0); } while (0)
; #define PG8_WAIT_V(n) asm volatile("s_waitcnt vmcnt(" #n ")" ::: "memory")
; #define PG8_BAR __builtin_amdgcn_s_barrier()
; template <class Epi, class Sched, bool ALIGN_EPI = false, bool SP2 = false>
; __device__ __forceinline__ void gemm_phase(PG8_LAS unsigned char* lds, const Gemm g, const Sched& S, const Epi& E) {
;     ...
;         for (int t = 0; t < nt; t += 2) {
;             const bool last = (t == nt - 2);
;             const char* a1 = cA + (size_t)(t + 1) * kstep;
;             const char* a2 = last ? nA : cA + (size_t)(t + 2) * kstep; const char* b2 = last ? nB : cB + (size_t)(t + 2) * kstep;
;             const char* a3 = a2 + kstep; const char* b3 = b2 + kstep;
;             if (last && has_next) S.a_ready(nxt);
;             if constexpr (SP2) {
;             PG8_LDB(B0, 0, 0); PG8_LDB(B1, 0, 1); PG8_SCHED; PG8_LDA(At, 0, 0); PG8_STAGE(PG8_SA(1, 1), a1 + hstep, voffA);
;             PG8_WAIT_V(8); PG8_WAIT_L(0); PG8_BAR; PG8_MMA(0, 0, At, B0); PG8_MMA(0, 1, At, B1); PG8_BAR; PG8_SCHED;
;             PG8_LDA(At, 0, 1); PG8_STAGE(PG8_SB(0, 0), b2, voffB); PG8_STAGE(PG8_SB(0, 1), b2 + hstep, voffB); PG8_STAGE(PG8_SA(0, 0), a2, voffA);
;             PG8_WAIT_V(8); PG8_WAIT_L(0); PG8_BAR; PG8_MMA(1, 0, At, B0); PG8_MMA(1, 1, At, B1); PG8_BAR; PG8_SCHED;
.LBB0_324:
	ds_read_b128 v[176:179], v143
	ds_read_b128 v[180:183], v143 offset:1024
	ds_read_b128 v[194:197], v143 offset:2048
	ds_read_b128 v[198:201], v143 offset:3072
	ds_read_b128 v[202:205], v143 offset:4096
	ds_read_b128 v[206:209], v143 offset:5120
	ds_read_b128 v[220:223], v143 offset:6144
	ds_read_b128 v[224:227], v143 offset:7168
	s_add_i32 s59, s33, 0x100
	v_add_u32_e32 v2, s59, v142
	ds_read_b128 v[144:147], v2
	ds_read_b128 v[148:151], v2 offset:1024
	ds_read_b128 v[152:155], v2 offset:2048
	ds_read_b128 v[156:159], v2 offset:3072
	s_add_i32 s58, s52, 2
	s_add_u32 s28, s56, 0x80
	s_addc_u32 s29, s57, 0
	s_cmp_eq_u32 s62, s52
	s_cselect_b32 s53, s43, s29
	s_cselect_b32 s52, s42, s28
	s_cselect_b32 s77, s55, s70
	s_cselect_b32 s76, s54, s69
	s_add_i32 s28, s21, 0x100
	v_add_u32_e32 v2, s28, v142
	ds_read_b128 v[160:163], v2
	ds_read_b128 v[164:167], v2 offset:1024
	ds_read_b128 v[168:171], v2 offset:2048
	ds_read_b128 v[172:175], v2 offset:3072
	v_lshl_add_u64 v[210:211], s[56:57], 0, v[140:141]
	s_add_i32 m0, s19, 0xc000
	global_load_lds_dwordx4 v[210:211], off
	v_lshl_add_u64 v[210:211], s[56:57], 0, v[138:139]
	s_add_i32 m0, s19, 0xe000
	s_nop 0
	global_load_lds_dwordx4 v[210:211], off
	s_waitcnt vmcnt(8)
	s_waitcnt lgkmcnt(0)
	s_barrier
	s_setprio 1
	s_waitcnt lgkmcnt(0)
	v_mfma_f32_16x16x32_bf16 v[124:127], v[144:147], v[176:179], v[124:127]
	v_mfma_f32_16x16x32_bf16 v[128:131], v[152:155], v[176:179], v[128:131]
	v_mfma_f32_16x16x32_bf16 v[112:115], v[144:147], v[194:197], v[112:115]
	v_mfma_f32_16x16x32_bf16 v[108:111], v[152:155], v[194:197], v[108:111]
	v_mfma_f32_16x16x32_bf16 v[96:99], v[144:147], v[202:205], v[96:99]
	v_mfma_f32_16x16x32_bf16 v[92:95], v[152:155], v[202:205], v[92:95]
	v_mfma_f32_16x16x32_bf16 v[80:83], v[144:147], v[220:223], v[80:83]
	v_mfma_f32_16x16x32_bf16 v[76:79], v[152:155], v[220:223], v[76:79]
	v_mfma_f32_16x16x32_bf16 v[124:127], v[148:151], v[180:183], v[124:127]
	v_mfma_f32_16x16x32_bf16 v[128:131], v[156:159], v[180:183], v[128:131]
	v_mfma_f32_16x16x32_bf16 v[112:115], v[148:151], v[198:201], v[112:115]
	v_mfma_f32_16x16x32_bf16 v[108:111], v[156:159], v[198:201], v[108:111]
	v_mfma_f32_16x16x32_bf16 v[96:99], v[148:151], v[206:209], v[96:99]
	v_mfma_f32_16x16x32_bf16 v[92:95], v[156:159], v[206:209], v[92:95]
	v_mfma_f32_16x16x32_bf16 v[80:83], v[148:151], v[224:227], v[80:83]
	v_mfma_f32_16x16x32_bf16 v[76:79], v[156:159], v[224:227], v[76:79]
	s_setprio 0
	s_setprio 1
	v_mfma_f32_16x16x32_bf16 v[120:123], v[160:163], v[176:179], v[120:123]
	v_mfma_f32_16x16x32_bf16 v[116:119], v[168:171], v[176:179], v[116:119]
	v_mfma_f32_16x16x32_bf16 v[104:107], v[160:163], v[194:197], v[104:107]
	v_mfma_f32_16x16x32_bf16 v[100:103], v[168:171], v[194:197], v[100:103]
	v_mfma_f32_16x16x32_bf16 v[88:91], v[160:163], v[202:205], v[88:91]
	v_mfma_f32_16x16x32_bf16 v[84:87], v[168:171], v[202:205], v[84:87]
	v_mfma_f32_16x16x32_bf16 v[72:75], v[160:163], v[220:223], v[72:75]
	v_mfma_f32_16x16x32_bf16 v[68:71], v[168:171], v[220:223], v[68:71]
	v_mfma_f32_16x16x32_bf16 v[120:123], v[164:167], v[180:183], v[120:123]
	v_mfma_f32_16x16x32_bf16 v[116:119], v[172:175], v[180:183], v[116:119]
	v_mfma_f32_16x16x32_bf16 v[104:107], v[164:167], v[198:201], v[104:107]
	v_mfma_f32_16x16x32_bf16 v[100:103], v[172:175], v[198:201], v[100:103]
	v_mfma_f32_16x16x32_bf16 v[88:91], v[164:167], v[206:209], v[88:91]
	v_mfma_f32_16x16x32_bf16 v[84:87], v[172:175], v[206:209], v[84:87]
	v_mfma_f32_16x16x32_bf16 v[72:75], v[164:167], v[224:227], v[72:75]
	v_mfma_f32_16x16x32_bf16 v[68:71], v[172:175], v[224:227], v[68:71]
	s_setprio 0
	s_barrier
	s_add_i32 s29, s59, s15
	v_lshl_add_u64 v[210:211], s[76:77], 0, v[134:135]
	s_mov_b32 m0, s29
	ds_read_b128 v[176:179], v143 offset:16384
	ds_read_b128 v[180:183], v143 offset:17408
	ds_read_b128 v[194:197], v143 offset:18432
	ds_read_b128 v[198:201], v143 offset:19456
	ds_read_b128 v[202:205], v143 offset:20480
	ds_read_b128 v[206:209], v143 offset:21504
	ds_read_b128 v[220:223], v143 offset:22528
	ds_read_b128 v[224:227], v143 offset:23552
	global_load_lds_dwordx4 v[210:211], off
	s_add_i32 m0, s29, 0x2000
	v_lshl_add_u64 v[228:229], s[76:77], 0, v[0:1]
	s_add_u32 s76, s76, s36
	s_addc_u32 s77, s77, s37
	s_add_i32 s28, s28, s15
	global_load_lds_dwordx4 v[228:229], off
	v_lshl_add_u64 v[230:231], s[76:77], 0, v[134:135]
	s_mov_b32 m0, s28
	v_lshl_add_u64 v[232:233], s[76:77], 0, v[0:1]
	global_load_lds_dwordx4 v[230:231], off
	s_add_i32 m0, s28, 0x2000
	v_lshl_add_u64 v[234:235], s[52:53], 0, v[136:137]
	global_load_lds_dwordx4 v[232:233], off
	s_mov_b32 m0, s19
	v_lshl_add_u64 v[236:237], s[52:53], 0, v[132:133]
	global_load_lds_dwordx4 v[234:235], off
	s_mov_b32 m0, s23
	s_nop 0
	global_load_lds_dwordx4 v[236:237], off
	s_waitcnt vmcnt(8)
	s_waitcnt lgkmcnt(0)
	s_barrier
; #define PG8_STAGE(bufoff, gbase, voff) do { _Pragma("unroll") for (int _i = 0; _i < 2; ++_i) \
;         __builtin_amdgcn_global_load_lds((const unsigned*)((const char*)(gbase) + (voff)[_i]), (PG8_LAS unsigned*)(lds + (bufoff) + ldsw + _i * 8192), 16, 0, 0); } while (0)
; #define PG8_LDA(dst, b, h) do { _Pragma("unroll") for (int m = 0; m < 4; ++m) _Pragma("unroll") for (int k = 0; k < 2; ++k) dst[m][k] = *(const PG8_LAS bf16x8*)(lds + PG8_SA(b, h) + aoff + m * 2048 + k * 1024); } while (0)
; #define PG8_LDB(dst, b, h) do { _Pragma("unroll") for (int n = 0; n < 2; ++n) _Pragma("unroll") for (int k = 0; k < 2; ++k) dst[n][k] = *(const PG8_LAS bf16x8*)(lds + PG8_SB(b, h) + boff + n * 2048 + k * 1024); } while (0)
; #define PG8_MMA(ai, bj, At, Bt) do { __builtin_amdgcn_s_setprio(1); _Pragma("unroll") for (int m = 0; m < 4; ++m) _Pragma("unroll") for (int n = 0; n < 2; ++n) _Pragma("unroll") for (int k = 0; k < 2; ++k) \
;         acc[ai][bj][m][n] = __builtin_amdgcn_mfma_f32_16x16x32_bf16(Bt[n][k], At[m][k], acc[ai][bj][m][n], 0, 0, 0); __builtin_amdgcn_s_setprio(0); } while (0)
; #define PG8_WAIT_V(n) asm volatile("s_waitcnt vmcnt(" #n ")" ::: "memory")
; #define PG8_WAIT_L(n) asm volatile("s_waitcnt lgkmcnt(" #n ")" ::: "memory")
; #define PG8_BAR __builtin_amdgcn_s_barrier()
; #define PG8_SCHED __builtin_amdgcn_sched_barrier(0)
; template <class Epi, class Sched, bool ALIGN_EPI = false, bool SP2 = false>
; __device__ __forceinline__ void gemm_phase(PG8_LAS unsigned char* lds, const Gemm g, const Sched& S, const Epi& E) {
;     ...
;             PG8_WAIT_V(8); PG8_WAIT_L(0); PG8_BAR; PG8_MMA(1, 0, At, B0); PG8_MMA(1, 1, At, B1); PG8_BAR; PG8_SCHED;
;             PG8_LDB(B0, 1, 0); PG8_LDB(B1, 1, 1); PG8_SCHED; PG8_LDA(At, 1, 0); PG8_STAGE(PG8_SA(0, 1), a2 + hstep, voffA);
;             PG8_WAIT_V(8); PG8_WAIT_L(0); PG8_BAR; PG8_MMA(0, 0, At, B0); PG8_MMA(0, 1, At, B1); PG8_BAR; PG8_SCHED;
	s_setprio 1
	s_waitcnt lgkmcnt(0)
	v_mfma_f32_16x16x32_bf16 v[64:67], v[144:147], v[176:179], v[64:67]
	v_mfma_f32_16x16x32_bf16 v[60:63], v[152:155], v[176:179], v[60:63]
	v_mfma_f32_16x16x32_bf16 v[48:51], v[144:147], v[194:197], v[48:51]
	v_mfma_f32_16x16x32_bf16 v[44:47], v[152:155], v[194:197], v[44:47]
	v_mfma_f32_16x16x32_bf16 v[32:35], v[144:147], v[202:205], v[32:35]
	v_mfma_f32_16x16x32_bf16 v[28:31], v[152:155], v[202:205], v[28:31]
	v_mfma_f32_16x16x32_bf16 v[16:19], v[144:147], v[220:223], v[16:19]
	v_mfma_f32_16x16x32_bf16 v[12:15], v[152:155], v[220:223], v[12:15]
	v_mfma_f32_16x16x32_bf16 v[64:67], v[148:151], v[180:183], v[64:67]
	v_mfma_f32_16x16x32_bf16 v[60:63], v[156:159], v[180:183], v[60:63]
	v_mfma_f32_16x16x32_bf16 v[48:51], v[148:151], v[198:201], v[48:51]
	v_mfma_f32_16x16x32_bf16 v[44:47], v[156:159], v[198:201], v[44:47]
	v_mfma_f32_16x16x32_bf16 v[32:35], v[148:151], v[206:209], v[32:35]
	v_mfma_f32_16x16x32_bf16 v[28:31], v[156:159], v[206:209], v[28:31]
	v_mfma_f32_16x16x32_bf16 v[16:19], v[148:151], v[224:227], v[16:19]
	v_mfma_f32_16x16x32_bf16 v[12:15], v[156:159], v[224:227], v[12:15]
	s_setprio 0
	s_setprio 1
	v_mfma_f32_16x16x32_bf16 v[56:59], v[160:163], v[176:179], v[56:59]
	v_mfma_f32_16x16x32_bf16 v[52:55], v[168:171], v[176:179], v[52:55]
	v_mfma_f32_16x16x32_bf16 v[40:43], v[160:163], v[194:197], v[40:43]
	v_mfma_f32_16x16x32_bf16 v[36:39], v[168:171], v[194:197], v[36:39]
	v_mfma_f32_16x16x32_bf16 v[24:27], v[160:163], v[202:205], v[24:27]
	v_mfma_f32_16x16x32_bf16 v[20:23], v[168:171], v[202:205], v[20:23]
	v_mfma_f32_16x16x32_bf16 v[8:11], v[160:163], v[220:223], v[8:11]
	v_mfma_f32_16x16x32_bf16 v[4:7], v[168:171], v[220:223], v[4:7]
	v_mfma_f32_16x16x32_bf16 v[56:59], v[164:167], v[180:183], v[56:59]
	v_mfma_f32_16x16x32_bf16 v[52:55], v[172:175], v[180:183], v[52:55]
	v_mfma_f32_16x16x32_bf16 v[40:43], v[164:167], v[198:201], v[40:43]
	v_mfma_f32_16x16x32_bf16 v[36:39], v[172:175], v[198:201], v[36:39]
	v_mfma_f32_16x16x32_bf16 v[24:27], v[164:167], v[206:209], v[24:27]
	v_mfma_f32_16x16x32_bf16 v[20:23], v[172:175], v[206:209], v[20:23]
	v_mfma_f32_16x16x32_bf16 v[8:11], v[164:167], v[224:227], v[8:11]
	v_mfma_f32_16x16x32_bf16 v[4:7], v[172:175], v[224:227], v[4:7]
	s_setprio 0
	s_barrier
	s_add_i32 s28, s82, 0x100
	v_add_u32_e32 v2, s28, v142
	s_add_i32 s29, s78, 0x100
	ds_read_b128 v[144:147], v2
	ds_read_b128 v[148:151], v2 offset:1024
	ds_read_b128 v[152:155], v2 offset:2048
	ds_read_b128 v[156:159], v2 offset:3072
	v_add_u32_e32 v2, s29, v142
	ds_read_b128 v[160:163], v2
	ds_read_b128 v[164:167], v2 offset:1024
	ds_read_b128 v[168:171], v2 offset:2048
	ds_read_b128 v[172:175], v2 offset:3072
	s_add_u32 s52, s52, s36
	s_addc_u32 s53, s53, s37
	s_mov_b32 m0, s25
	v_lshl_add_u64 v[238:239], s[52:53], 0, v[136:137]
	ds_read_b128 v[176:179], v143 offset:32768
	ds_read_b128 v[180:183], v143 offset:33792
	ds_read_b128 v[194:197], v143 offset:34816
	ds_read_b128 v[198:201], v143 offset:35840
	ds_read_b128 v[202:205], v143 offset:36864
	ds_read_b128 v[206:209], v143 offset:37888
	ds_read_b128 v[220:223], v143 offset:38912
	ds_read_b128 v[224:227], v143 offset:39936
	global_load_lds_dwordx4 v[238:239], off
	v_lshl_add_u64 v[238:239], s[52:53], 0, v[132:133]
	s_mov_b32 m0, s26
	s_nop 0
	global_load_lds_dwordx4 v[238:239], off
	s_waitcnt vmcnt(8)
	s_waitcnt lgkmcnt(0)
	s_barrier
	s_setprio 1
	s_waitcnt lgkmcnt(0)
	v_mfma_f32_16x16x32_bf16 v[124:127], v[144:147], v[176:179], v[124:127]
	v_mfma_f32_16x16x32_bf16 v[128:131], v[152:155], v[176:179], v[128:131]
	v_mfma_f32_16x16x32_bf16 v[112:115], v[144:147], v[194:197], v[112:115]
	v_mfma_f32_16x16x32_bf16 v[108:111], v[152:155], v[194:197], v[108:111]
	v_mfma_f32_16x16x32_bf16 v[96:99], v[144:147], v[202:205], v[96:99]
	v_mfma_f32_16x16x32_bf16 v[92:95], v[152:155], v[202:205], v[92:95]
	v_mfma_f32_16x16x32_bf16 v[80:83], v[144:147], v[220:223], v[80:83]
	v_mfma_f32_16x16x32_bf16 v[76:79], v[152:155], v[220:223], v[76:79]
	v_mfma_f32_16x16x32_bf16 v[124:127], v[148:151], v[180:183], v[124:127]
	v_mfma_f32_16x16x32_bf16 v[128:131], v[156:159], v[180:183], v[128:131]
	v_mfma_f32_16x16x32_bf16 v[112:115], v[148:151], v[198:201], v[112:115]
	v_mfma_f32_16x16x32_bf16 v[108:111], v[156:159], v[198:201], v[108:111]
	v_mfma_f32_16x16x32_bf16 v[96:99], v[148:151], v[206:209], v[96:99]
	v_mfma_f32_16x16x32_bf16 v[92:95], v[156:159], v[206:209], v[92:95]
	v_mfma_f32_16x16x32_bf16 v[80:83], v[148:151], v[224:227], v[80:83]
	v_mfma_f32_16x16x32_bf16 v[76:79], v[156:159], v[224:227], v[76:79]
	s_setprio 0
	s_setprio 1
	v_mfma_f32_16x16x32_bf16 v[120:123], v[160:163], v[176:179], v[120:123]
	v_mfma_f32_16x16x32_bf16 v[116:119], v[168:171], v[176:179], v[116:119]
	v_mfma_f32_16x16x32_bf16 v[104:107], v[160:163], v[194:197], v[104:107]
	v_mfma_f32_16x16x32_bf16 v[100:103], v[168:171], v[194:197], v[100:103]
	v_mfma_f32_16x16x32_bf16 v[88:91], v[160:163], v[202:205], v[88:91]
	v_mfma_f32_16x16x32_bf16 v[84:87], v[168:171], v[202:205], v[84:87]
	v_mfma_f32_16x16x32_bf16 v[72:75], v[160:163], v[220:223], v[72:75]
	v_mfma_f32_16x16x32_bf16 v[68:71], v[168:171], v[220:223], v[68:71]
	v_mfma_f32_16x16x32_bf16 v[120:123], v[164:167], v[180:183], v[120:123]
	v_mfma_f32_16x16x32_bf16 v[116:119], v[172:175], v[180:183], v[116:119]
	v_mfma_f32_16x16x32_bf16 v[104:107], v[164:167], v[198:201], v[104:107]
	v_mfma_f32_16x16x32_bf16 v[100:103], v[172:175], v[198:201], v[100:103]
	v_mfma_f32_16x16x32_bf16 v[88:91], v[164:167], v[206:209], v[88:91]
	v_mfma_f32_16x16x32_bf16 v[84:87], v[172:175], v[206:209], v[84:87]
	v_mfma_f32_16x16x32_bf16 v[72:75], v[164:167], v[224:227], v[72:75]
	v_mfma_f32_16x16x32_bf16 v[68:71], v[172:175], v[224:227], v[68:71]
	s_setprio 0
	s_barrier
; #define PG8_STAGE(bufoff, gbase, voff) do { _Pragma("unroll") for (int _i = 0; _i < 2; ++_i) \
;         __builtin_amdgcn_global_load_lds((const unsigned*)((const char*)(gbase) + (voff)[_i]), (PG8_LAS unsigned*)(lds + (bufoff) + ldsw + _i * 8192), 16, 0, 0); } while (0)
; #define PG8_LDA(dst, b, h) do { _Pragma("unroll") for (int m = 0; m < 4; ++m) _Pragma("unroll") for (int k = 0; k < 2; ++k) dst[m][k] = *(const PG8_LAS bf16x8*)(lds + PG8_SA(b, h) + aoff + m * 2048 + k * 1024); } while (0)
; #define PG8_MMA(ai, bj, At, Bt) do { __builtin_amdgcn_s_setprio(1); _Pragma("unroll") for (int m = 0; m < 4; ++m) _Pragma("unroll") for (int n = 0; n < 2; ++n) _Pragma("unroll") for (int k = 0; k < 2; ++k) \
;         acc[ai][bj][m][n] = __builtin_amdgcn_mfma_f32_16x16x32_bf16(Bt[n][k], At[m][k], acc[ai][bj][m][n], 0, 0, 0); __builtin_amdgcn_s_setprio(0); } while (0)
; #define PG8_WAIT_V(n) asm volatile("s_waitcnt vmcnt(" #n ")" ::: "memory")
; #define PG8_WAIT_L(n) asm volatile("s_waitcnt lgkmcnt(" #n ")" ::: "memory")
; #define PG8_BAR __builtin_amdgcn_s_barrier()
; #define PG8_SCHED __builtin_amdgcn_sched_barrier(0)
; template <class Epi, class Sched, bool ALIGN_EPI = false, bool SP2 = false>
; __device__ __forceinline__ void gemm_phase(PG8_LAS unsigned char* lds, const Gemm g, const Sched& S, const Epi& E) {
;     ...
;         for (int t = 0; t < nt; t += 2) {
;     ...
;             PG8_LDA(At, 1, 1); PG8_STAGE(PG8_SB(1, 0), b3, voffB); PG8_STAGE(PG8_SB(1, 1), b3 + hstep, voffB); PG8_STAGE(PG8_SA(1, 0), a3, voffA);
;             PG8_WAIT_V(8); PG8_WAIT_L(0); PG8_BAR; PG8_MMA(1, 0, At, B0); PG8_MMA(1, 1, At, B1); PG8_BAR; PG8_SCHED;
	s_add_i32 s28, s28, s15
	v_lshl_add_u64 v[210:211], v[210:211], 0, s[8:9]
	s_mov_b32 m0, s28
	ds_read_b128 v[176:179], v143 offset:49152
	ds_read_b128 v[180:183], v143 offset:50176
	ds_read_b128 v[194:197], v143 offset:51200
	ds_read_b128 v[198:201], v143 offset:52224
	ds_read_b128 v[202:205], v143 offset:53248
	ds_read_b128 v[206:209], v143 offset:54272
	ds_read_b128 v[220:223], v143 offset:55296
	ds_read_b128 v[224:227], v143 offset:56320
	global_load_lds_dwordx4 v[210:211], off
	v_lshl_add_u64 v[210:211], v[228:229], 0, s[8:9]
	s_add_i32 m0, s28, 0x2000
	s_add_i32 s28, s29, s15
	global_load_lds_dwordx4 v[210:211], off
	v_lshl_add_u64 v[210:211], v[230:231], 0, s[8:9]
	s_mov_b32 m0, s28
	s_nop 0
	global_load_lds_dwordx4 v[210:211], off
	v_lshl_add_u64 v[210:211], v[232:233], 0, s[8:9]
	s_add_i32 m0, s28, 0x2000
	s_nop 0
	global_load_lds_dwordx4 v[210:211], off
	v_lshl_add_u64 v[210:211], v[234:235], 0, s[8:9]
	s_mov_b32 m0, s20
	s_nop 0
	global_load_lds_dwordx4 v[210:211], off
	v_lshl_add_u64 v[210:211], v[236:237], 0, s[8:9]
	s_mov_b32 m0, s27
	s_nop 0
	global_load_lds_dwordx4 v[210:211], off
	s_waitcnt vmcnt(8)
	s_waitcnt lgkmcnt(0)
	s_barrier
	s_setprio 1
	s_waitcnt lgkmcnt(0)
	v_mfma_f32_16x16x32_bf16 v[64:67], v[144:147], v[176:179], v[64:67]
	v_mfma_f32_16x16x32_bf16 v[60:63], v[152:155], v[176:179], v[60:63]
	v_mfma_f32_16x16x32_bf16 v[48:51], v[144:147], v[194:197], v[48:51]
	v_mfma_f32_16x16x32_bf16 v[44:47], v[152:155], v[194:197], v[44:47]
	v_mfma_f32_16x16x32_bf16 v[32:35], v[144:147], v[202:205], v[32:35]
	v_mfma_f32_16x16x32_bf16 v[28:31], v[152:155], v[202:205], v[28:31]
	v_mfma_f32_16x16x32_bf16 v[16:19], v[144:147], v[220:223], v[16:19]
	v_mfma_f32_16x16x32_bf16 v[12:15], v[152:155], v[220:223], v[12:15]
	v_mfma_f32_16x16x32_bf16 v[64:67], v[148:151], v[180:183], v[64:67]
	v_mfma_f32_16x16x32_bf16 v[60:63], v[156:159], v[180:183], v[60:63]
	v_mfma_f32_16x16x32_bf16 v[48:51], v[148:151], v[198:201], v[48:51]
	v_mfma_f32_16x16x32_bf16 v[44:47], v[156:159], v[198:201], v[44:47]
	v_mfma_f32_16x16x32_bf16 v[32:35], v[148:151], v[206:209], v[32:35]
	v_mfma_f32_16x16x32_bf16 v[28:31], v[156:159], v[206:209], v[28:31]
	v_mfma_f32_16x16x32_bf16 v[16:19], v[148:151], v[224:227], v[16:19]
	v_mfma_f32_16x16x32_bf16 v[12:15], v[156:159], v[224:227], v[12:15]
	s_setprio 0
	s_setprio 1
	v_mfma_f32_16x16x32_bf16 v[56:59], v[160:163], v[176:179], v[56:59]
	v_mfma_f32_16x16x32_bf16 v[52:55], v[168:171], v[176:179], v[52:55]
	v_mfma_f32_16x16x32_bf16 v[40:43], v[160:163], v[194:197], v[40:43]
	v_mfma_f32_16x16x32_bf16 v[36:39], v[168:171], v[194:197], v[36:39]
	v_mfma_f32_16x16x32_bf16 v[24:27], v[160:163], v[202:205], v[24:27]
	v_mfma_f32_16x16x32_bf16 v[20:23], v[168:171], v[202:205], v[20:23]
	v_mfma_f32_16x16x32_bf16 v[8:11], v[160:163], v[220:223], v[8:11]
	v_mfma_f32_16x16x32_bf16 v[4:7], v[168:171], v[220:223], v[4:7]
	v_mfma_f32_16x16x32_bf16 v[56:59], v[164:167], v[180:183], v[56:59]
	v_mfma_f32_16x16x32_bf16 v[52:55], v[172:175], v[180:183], v[52:55]
	v_mfma_f32_16x16x32_bf16 v[40:43], v[164:167], v[198:201], v[40:43]
	v_mfma_f32_16x16x32_bf16 v[36:39], v[172:175], v[198:201], v[36:39]
	v_mfma_f32_16x16x32_bf16 v[24:27], v[164:167], v[206:209], v[24:27]
	v_mfma_f32_16x16x32_bf16 v[20:23], v[172:175], v[206:209], v[20:23]
	v_mfma_f32_16x16x32_bf16 v[8:11], v[164:167], v[224:227], v[8:11]
	v_mfma_f32_16x16x32_bf16 v[4:7], v[172:175], v[224:227], v[4:7]
	s_add_u32 s69, s69, 0x100
	s_addc_u32 s70, s70, 0
	s_add_u32 s56, s56, 0x100
	s_addc_u32 s57, s57, 0
	s_cmp_ge_i32 s58, s6
	s_mov_b32 s52, s58
	s_setprio 0
	s_barrier
	s_cbranch_scc0 .LBB0_324

; #define PG8_STAGE(bufoff, gbase, voff) do { _Pragma("unroll") for (int _i = 0; _i < 2; ++_i) \
;         __builtin_amdgcn_global_load_lds((const unsigned*)((const char*)(gbase) + (voff)[_i]), (PG8_LAS unsigned*)(lds + (bufoff) + ldsw + _i * 8192), 16, 0, 0); } while (0)
; #define PG8_LDA(dst, b, h) do { _Pragma("unroll") for (int m = 0; m < 4; ++m) _Pragma("unroll") for (int k = 0; k < 2; ++k) dst[m][k] = *(const PG8_LAS bf16x8*)(lds + PG8_SA(b, h) + aoff + m * 2048 + k * 1024); } while (0)
; #define PG8_LDB(dst, b, h) do { _Pragma("unroll") for (int n = 0; n < 2; ++n) _Pragma("unroll") for (int k = 0; k < 2; ++k) dst[n][k] = *(const PG8_LAS bf16x8*)(lds + PG8_SB(b, h) + boff + n * 2048 + k * 1024); } while (0)
; #define PG8_MMA(ai, bj, At, Bt) do { __builtin_amdgcn_s_setprio(1); _Pragma("unroll") for (int m = 0; m < 4; ++m) _Pragma("unroll") for (int n = 0; n < 2; ++n) _Pragma("unroll") for (int k = 0; k < 2; ++k) \
;         acc[ai][bj][m][n] = __builtin_amdgcn_mfma_f32_16x16x32_bf16(Bt[n][k], At[m][k], acc[ai][bj][m][n], 0, 0, 0); __builtin_amdgcn_s_setprio(0); } while (0)
; #define PG8_WAIT_V(n) asm volatile("s_waitcnt vmcnt(" #n ")" ::: "memory")
; #define PG8_BAR __builtin_amdgcn_s_barrier()
; template <class Epi, class Sched, bool ALIGN_EPI = false, bool SP2 = false>
; __device__ __forceinline__ void gemm_phase(PG8_LAS unsigned char* lds, const Gemm g, const Sched& S, const Epi& E) {
;     ...
;         for (int t = 0; t < nt; t += 2) {
;             const bool last = (t == nt - 2);
;             const char* a1 = cA + (size_t)(t + 1) * kstep;
;             const char* a2 = last ? nA : cA + (size_t)(t + 2) * kstep; const char* b2 = last ? nB : cB + (size_t)(t + 2) * kstep;
;             const char* a3 = a2 + kstep; const char* b3 = b2 + kstep;
;             if (last && has_next) S.a_ready(nxt);
;             if constexpr (SP2) {
;             PG8_LDB(B0, 0, 0); PG8_LDB(B1, 0, 1); PG8_SCHED; PG8_LDA(At, 0, 0); PG8_STAGE(PG8_SA(1, 1), a1 + hstep, voffA);
;             PG8_WAIT_V(8); PG8_WAIT_L(0); PG8_BAR; PG8_MMA(0, 0, At, B0); PG8_MMA(0, 1, At, B1); PG8_BAR; PG8_SCHED;
;             PG8_LDA(At, 0, 1); PG8_STAGE(PG8_SB(0, 0), b2, voffB); PG8_STAGE(PG8_SB(0, 1), b2 + hstep, voffB); PG8_STAGE(PG8_SA(0, 0), a2, voffA);
;             PG8_WAIT_V(8); PG8_WAIT_L(0); PG8_BAR; PG8_MMA(1, 0, At, B0); PG8_MMA(1, 1, At, B1); PG8_BAR; PG8_SCHED;
.LBB0_355:
	ds_read_b128 v[176:179], v143
	ds_read_b128 v[180:183], v143 offset:1024
	ds_read_b128 v[194:197], v143 offset:2048
	ds_read_b128 v[198:201], v143 offset:3072
	ds_read_b128 v[202:205], v143 offset:4096
	ds_read_b128 v[206:209], v143 offset:5120
	ds_read_b128 v[220:223], v143 offset:6144
	ds_read_b128 v[224:227], v143 offset:7168
	s_add_i32 s65, s33, 0x100
	v_add_u32_e32 v2, s65, v142
	ds_read_b128 v[144:147], v2
	ds_read_b128 v[148:151], v2 offset:1024
	ds_read_b128 v[152:155], v2 offset:2048
	ds_read_b128 v[156:159], v2 offset:3072
	s_add_i32 s64, s50, 2
	s_add_u32 s28, s42, 0x80
	s_addc_u32 s29, s43, 0
	s_cmp_eq_u32 s69, s50
	s_cselect_b32 s51, s61, s29
	s_cselect_b32 s50, s60, s28
	s_cselect_b32 s89, s63, s53
	s_cselect_b32 s88, s62, s20
	s_add_i32 s28, s21, 0x100
	v_add_u32_e32 v2, s28, v142
	ds_read_b128 v[160:163], v2
	ds_read_b128 v[164:167], v2 offset:1024
	ds_read_b128 v[168:171], v2 offset:2048
	ds_read_b128 v[172:175], v2 offset:3072
	v_lshl_add_u64 v[210:211], s[42:43], 0, v[140:141]
	s_add_i32 m0, s15, 0xc000
	global_load_lds_dwordx4 v[210:211], off
	v_lshl_add_u64 v[210:211], s[42:43], 0, v[138:139]
	s_add_i32 m0, s15, 0xe000
	s_nop 0
	global_load_lds_dwordx4 v[210:211], off
	s_waitcnt vmcnt(8)
	s_waitcnt lgkmcnt(0)
	s_barrier
	s_setprio 1
	s_waitcnt lgkmcnt(0)
	v_mfma_f32_16x16x32_bf16 v[124:127], v[144:147], v[176:179], v[124:127]
	v_mfma_f32_16x16x32_bf16 v[128:131], v[152:155], v[176:179], v[128:131]
	v_mfma_f32_16x16x32_bf16 v[112:115], v[144:147], v[194:197], v[112:115]
	v_mfma_f32_16x16x32_bf16 v[108:111], v[152:155], v[194:197], v[108:111]
	v_mfma_f32_16x16x32_bf16 v[96:99], v[144:147], v[202:205], v[96:99]
	v_mfma_f32_16x16x32_bf16 v[92:95], v[152:155], v[202:205], v[92:95]
	v_mfma_f32_16x16x32_bf16 v[80:83], v[144:147], v[220:223], v[80:83]
	v_mfma_f32_16x16x32_bf16 v[76:79], v[152:155], v[220:223], v[76:79]
	v_mfma_f32_16x16x32_bf16 v[124:127], v[148:151], v[180:183], v[124:127]
	v_mfma_f32_16x16x32_bf16 v[128:131], v[156:159], v[180:183], v[128:131]
	v_mfma_f32_16x16x32_bf16 v[112:115], v[148:151], v[198:201], v[112:115]
	v_mfma_f32_16x16x32_bf16 v[108:111], v[156:159], v[198:201], v[108:111]
	v_mfma_f32_16x16x32_bf16 v[96:99], v[148:151], v[206:209], v[96:99]
	v_mfma_f32_16x16x32_bf16 v[92:95], v[156:159], v[206:209], v[92:95]
	v_mfma_f32_16x16x32_bf16 v[80:83], v[148:151], v[224:227], v[80:83]
	v_mfma_f32_16x16x32_bf16 v[76:79], v[156:159], v[224:227], v[76:79]
	s_setprio 0
	s_setprio 1
	v_mfma_f32_16x16x32_bf16 v[120:123], v[160:163], v[176:179], v[120:123]
	v_mfma_f32_16x16x32_bf16 v[116:119], v[168:171], v[176:179], v[116:119]
	v_mfma_f32_16x16x32_bf16 v[104:107], v[160:163], v[194:197], v[104:107]
	v_mfma_f32_16x16x32_bf16 v[100:103], v[168:171], v[194:197], v[100:103]
	v_mfma_f32_16x16x32_bf16 v[88:91], v[160:163], v[202:205], v[88:91]
	v_mfma_f32_16x16x32_bf16 v[84:87], v[168:171], v[202:205], v[84:87]
	v_mfma_f32_16x16x32_bf16 v[72:75], v[160:163], v[220:223], v[72:75]
	v_mfma_f32_16x16x32_bf16 v[68:71], v[168:171], v[220:223], v[68:71]
	v_mfma_f32_16x16x32_bf16 v[120:123], v[164:167], v[180:183], v[120:123]
	v_mfma_f32_16x16x32_bf16 v[116:119], v[172:175], v[180:183], v[116:119]
	v_mfma_f32_16x16x32_bf16 v[104:107], v[164:167], v[198:201], v[104:107]
	v_mfma_f32_16x16x32_bf16 v[100:103], v[172:175], v[198:201], v[100:103]
	v_mfma_f32_16x16x32_bf16 v[88:91], v[164:167], v[206:209], v[88:91]
	v_mfma_f32_16x16x32_bf16 v[84:87], v[172:175], v[206:209], v[84:87]
	v_mfma_f32_16x16x32_bf16 v[72:75], v[164:167], v[224:227], v[72:75]
	v_mfma_f32_16x16x32_bf16 v[68:71], v[172:175], v[224:227], v[68:71]
	s_setprio 0
	s_barrier
	s_add_i32 s29, s65, s12
	v_lshl_add_u64 v[210:211], s[88:89], 0, v[132:133]
	s_mov_b32 m0, s29
	ds_read_b128 v[176:179], v143 offset:16384
	ds_read_b128 v[180:183], v143 offset:17408
	ds_read_b128 v[194:197], v143 offset:18432
	ds_read_b128 v[198:201], v143 offset:19456
	ds_read_b128 v[202:205], v143 offset:20480
	ds_read_b128 v[206:209], v143 offset:21504
	ds_read_b128 v[220:223], v143 offset:22528
	ds_read_b128 v[224:227], v143 offset:23552
	global_load_lds_dwordx4 v[210:211], off
	s_add_i32 m0, s29, 0x2000
	v_lshl_add_u64 v[228:229], s[88:89], 0, v[136:137]
	s_add_u32 s88, s88, s36
	s_addc_u32 s89, s89, s37
	s_add_i32 s28, s28, s12
	global_load_lds_dwordx4 v[228:229], off
	v_lshl_add_u64 v[230:231], s[88:89], 0, v[132:133]
	s_mov_b32 m0, s28
	v_lshl_add_u64 v[232:233], s[88:89], 0, v[136:137]
	global_load_lds_dwordx4 v[230:231], off
	s_add_i32 m0, s28, 0x2000
	v_lshl_add_u64 v[234:235], s[50:51], 0, v[0:1]
	global_load_lds_dwordx4 v[232:233], off
	s_mov_b32 m0, s15
	v_lshl_add_u64 v[236:237], s[50:51], 0, v[134:135]
	global_load_lds_dwordx4 v[234:235], off
	s_mov_b32 m0, s19
	s_nop 0
	global_load_lds_dwordx4 v[236:237], off
	s_waitcnt vmcnt(8)
	s_waitcnt lgkmcnt(0)
	s_barrier
; #define PG8_STAGE(bufoff, gbase, voff) do { _Pragma("unroll") for (int _i = 0; _i < 2; ++_i) \
;         __builtin_amdgcn_global_load_lds((const unsigned*)((const char*)(gbase) + (voff)[_i]), (PG8_LAS unsigned*)(lds + (bufoff) + ldsw + _i * 8192), 16, 0, 0); } while (0)
; #define PG8_LDA(dst, b, h) do { _Pragma("unroll") for (int m = 0; m < 4; ++m) _Pragma("unroll") for (int k = 0; k < 2; ++k) dst[m][k] = *(const PG8_LAS bf16x8*)(lds + PG8_SA(b, h) + aoff + m * 2048 + k * 1024); } while (0)
; #define PG8_LDB(dst, b, h) do { _Pragma("unroll") for (int n = 0; n < 2; ++n) _Pragma("unroll") for (int k = 0; k < 2; ++k) dst[n][k] = *(const PG8_LAS bf16x8*)(lds + PG8_SB(b, h) + boff + n * 2048 + k * 1024); } while (0)
; #define PG8_MMA(ai, bj, At, Bt) do { __builtin_amdgcn_s_setprio(1); _Pragma("unroll") for (int m = 0; m < 4; ++m) _Pragma("unroll") for (int n = 0; n < 2; ++n) _Pragma("unroll") for (int k = 0; k < 2; ++k) \
;         acc[ai][bj][m][n] = __builtin_amdgcn_mfma_f32_16x16x32_bf16(Bt[n][k], At[m][k], acc[ai][bj][m][n], 0, 0, 0); __builtin_amdgcn_s_setprio(0); } while (0)
; #define PG8_WAIT_V(n) asm volatile("s_waitcnt vmcnt(" #n ")" ::: "memory")
; #define PG8_WAIT_L(n) asm volatile("s_waitcnt lgkmcnt(" #n ")" ::: "memory")
; #define PG8_BAR __builtin_amdgcn_s_barrier()
; #define PG8_SCHED __builtin_amdgcn_sched_barrier(0)
; template <class Epi, class Sched, bool ALIGN_EPI = false, bool SP2 = false>
; __device__ __forceinline__ void gemm_phase(PG8_LAS unsigned char* lds, const Gemm g, const Sched& S, const Epi& E) {
;     ...
;             PG8_WAIT_V(8); PG8_WAIT_L(0); PG8_BAR; PG8_MMA(1, 0, At, B0); PG8_MMA(1, 1, At, B1); PG8_BAR; PG8_SCHED;
;             PG8_LDB(B0, 1, 0); PG8_LDB(B1, 1, 1); PG8_SCHED; PG8_LDA(At, 1, 0); PG8_STAGE(PG8_SA(0, 1), a2 + hstep, voffA);
;             PG8_WAIT_V(8); PG8_WAIT_L(0); PG8_BAR; PG8_MMA(0, 0, At, B0); PG8_MMA(0, 1, At, B1); PG8_BAR; PG8_SCHED;
	s_setprio 1
	s_waitcnt lgkmcnt(0)
	v_mfma_f32_16x16x32_bf16 v[64:67], v[144:147], v[176:179], v[64:67]
	v_mfma_f32_16x16x32_bf16 v[60:63], v[152:155], v[176:179], v[60:63]
	v_mfma_f32_16x16x32_bf16 v[48:51], v[144:147], v[194:197], v[48:51]
	v_mfma_f32_16x16x32_bf16 v[44:47], v[152:155], v[194:197], v[44:47]
	v_mfma_f32_16x16x32_bf16 v[32:35], v[144:147], v[202:205], v[32:35]
	v_mfma_f32_16x16x32_bf16 v[28:31], v[152:155], v[202:205], v[28:31]
	v_mfma_f32_16x16x32_bf16 v[16:19], v[144:147], v[220:223], v[16:19]
	v_mfma_f32_16x16x32_bf16 v[12:15], v[152:155], v[220:223], v[12:15]
	v_mfma_f32_16x16x32_bf16 v[64:67], v[148:151], v[180:183], v[64:67]
	v_mfma_f32_16x16x32_bf16 v[60:63], v[156:159], v[180:183], v[60:63]
	v_mfma_f32_16x16x32_bf16 v[48:51], v[148:151], v[198:201], v[48:51]
	v_mfma_f32_16x16x32_bf16 v[44:47], v[156:159], v[198:201], v[44:47]
	v_mfma_f32_16x16x32_bf16 v[32:35], v[148:151], v[206:209], v[32:35]
	v_mfma_f32_16x16x32_bf16 v[28:31], v[156:159], v[206:209], v[28:31]
	v_mfma_f32_16x16x32_bf16 v[16:19], v[148:151], v[224:227], v[16:19]
	v_mfma_f32_16x16x32_bf16 v[12:15], v[156:159], v[224:227], v[12:15]
	s_setprio 0
	s_setprio 1
	v_mfma_f32_16x16x32_bf16 v[56:59], v[160:163], v[176:179], v[56:59]
	v_mfma_f32_16x16x32_bf16 v[52:55], v[168:171], v[176:179], v[52:55]
	v_mfma_f32_16x16x32_bf16 v[40:43], v[160:163], v[194:197], v[40:43]
	v_mfma_f32_16x16x32_bf16 v[36:39], v[168:171], v[194:197], v[36:39]
	v_mfma_f32_16x16x32_bf16 v[24:27], v[160:163], v[202:205], v[24:27]
	v_mfma_f32_16x16x32_bf16 v[20:23], v[168:171], v[202:205], v[20:23]
	v_mfma_f32_16x16x32_bf16 v[8:11], v[160:163], v[220:223], v[8:11]
	v_mfma_f32_16x16x32_bf16 v[4:7], v[168:171], v[220:223], v[4:7]
	v_mfma_f32_16x16x32_bf16 v[56:59], v[164:167], v[180:183], v[56:59]
	v_mfma_f32_16x16x32_bf16 v[52:55], v[172:175], v[180:183], v[52:55]
	v_mfma_f32_16x16x32_bf16 v[40:43], v[164:167], v[198:201], v[40:43]
	v_mfma_f32_16x16x32_bf16 v[36:39], v[172:175], v[198:201], v[36:39]
	v_mfma_f32_16x16x32_bf16 v[24:27], v[164:167], v[206:209], v[24:27]
	v_mfma_f32_16x16x32_bf16 v[20:23], v[172:175], v[206:209], v[20:23]
	v_mfma_f32_16x16x32_bf16 v[8:11], v[164:167], v[224:227], v[8:11]
	v_mfma_f32_16x16x32_bf16 v[4:7], v[172:175], v[224:227], v[4:7]
	s_setprio 0
	s_barrier
	s_add_i32 s28, s82, 0x100
	v_add_u32_e32 v2, s28, v142
	s_add_i32 s29, s78, 0x100
	ds_read_b128 v[144:147], v2
	ds_read_b128 v[148:151], v2 offset:1024
	ds_read_b128 v[152:155], v2 offset:2048
	ds_read_b128 v[156:159], v2 offset:3072
	v_add_u32_e32 v2, s29, v142
	ds_read_b128 v[160:163], v2
	ds_read_b128 v[164:167], v2 offset:1024
	ds_read_b128 v[168:171], v2 offset:2048
	ds_read_b128 v[172:175], v2 offset:3072
	s_add_u32 s50, s50, s36
	s_addc_u32 s51, s51, s37
	s_mov_b32 m0, s23
	v_lshl_add_u64 v[238:239], s[50:51], 0, v[0:1]
	ds_read_b128 v[176:179], v143 offset:32768
	ds_read_b128 v[180:183], v143 offset:33792
	ds_read_b128 v[194:197], v143 offset:34816
	ds_read_b128 v[198:201], v143 offset:35840
	ds_read_b128 v[202:205], v143 offset:36864
	ds_read_b128 v[206:209], v143 offset:37888
	ds_read_b128 v[220:223], v143 offset:38912
	ds_read_b128 v[224:227], v143 offset:39936
	global_load_lds_dwordx4 v[238:239], off
	v_lshl_add_u64 v[238:239], s[50:51], 0, v[134:135]
	s_mov_b32 m0, s25
	s_nop 0
	global_load_lds_dwordx4 v[238:239], off
	s_waitcnt vmcnt(8)
	s_waitcnt lgkmcnt(0)
	s_barrier
	s_setprio 1
	s_waitcnt lgkmcnt(0)
	v_mfma_f32_16x16x32_bf16 v[124:127], v[144:147], v[176:179], v[124:127]
	v_mfma_f32_16x16x32_bf16 v[128:131], v[152:155], v[176:179], v[128:131]
	v_mfma_f32_16x16x32_bf16 v[112:115], v[144:147], v[194:197], v[112:115]
	v_mfma_f32_16x16x32_bf16 v[108:111], v[152:155], v[194:197], v[108:111]
	v_mfma_f32_16x16x32_bf16 v[96:99], v[144:147], v[202:205], v[96:99]
	v_mfma_f32_16x16x32_bf16 v[92:95], v[152:155], v[202:205], v[92:95]
	v_mfma_f32_16x16x32_bf16 v[80:83], v[144:147], v[220:223], v[80:83]
	v_mfma_f32_16x16x32_bf16 v[76:79], v[152:155], v[220:223], v[76:79]
	v_mfma_f32_16x16x32_bf16 v[124:127], v[148:151], v[180:183], v[124:127]
	v_mfma_f32_16x16x32_bf16 v[128:131], v[156:159], v[180:183], v[128:131]
	v_mfma_f32_16x16x32_bf16 v[112:115], v[148:151], v[198:201], v[112:115]
	v_mfma_f32_16x16x32_bf16 v[108:111], v[156:159], v[198:201], v[108:111]
	v_mfma_f32_16x16x32_bf16 v[96:99], v[148:151], v[206:209], v[96:99]
	v_mfma_f32_16x16x32_bf16 v[92:95], v[156:159], v[206:209], v[92:95]
	v_mfma_f32_16x16x32_bf16 v[80:83], v[148:151], v[224:227], v[80:83]
	v_mfma_f32_16x16x32_bf16 v[76:79], v[156:159], v[224:227], v[76:79]
	s_setprio 0
	s_setprio 1
	v_mfma_f32_16x16x32_bf16 v[120:123], v[160:163], v[176:179], v[120:123]
	v_mfma_f32_16x16x32_bf16 v[116:119], v[168:171], v[176:179], v[116:119]
	v_mfma_f32_16x16x32_bf16 v[104:107], v[160:163], v[194:197], v[104:107]
	v_mfma_f32_16x16x32_bf16 v[100:103], v[168:171], v[194:197], v[100:103]
	v_mfma_f32_16x16x32_bf16 v[88:91], v[160:163], v[202:205], v[88:91]
	v_mfma_f32_16x16x32_bf16 v[84:87], v[168:171], v[202:205], v[84:87]
	v_mfma_f32_16x16x32_bf16 v[72:75], v[160:163], v[220:223], v[72:75]
	v_mfma_f32_16x16x32_bf16 v[68:71], v[168:171], v[220:223], v[68:71]
	v_mfma_f32_16x16x32_bf16 v[120:123], v[164:167], v[180:183], v[120:123]
	v_mfma_f32_16x16x32_bf16 v[116:119], v[172:175], v[180:183], v[116:119]
	v_mfma_f32_16x16x32_bf16 v[104:107], v[164:167], v[198:201], v[104:107]
	v_mfma_f32_16x16x32_bf16 v[100:103], v[172:175], v[198:201], v[100:103]
	v_mfma_f32_16x16x32_bf16 v[88:91], v[164:167], v[206:209], v[88:91]
	v_mfma_f32_16x16x32_bf16 v[84:87], v[172:175], v[206:209], v[84:87]
	v_mfma_f32_16x16x32_bf16 v[72:75], v[164:167], v[224:227], v[72:75]
	v_mfma_f32_16x16x32_bf16 v[68:71], v[172:175], v[224:227], v[68:71]
	s_setprio 0
	s_barrier
; #define PG8_STAGE(bufoff, gbase, voff) do { _Pragma("unroll") for (int _i = 0; _i < 2; ++_i) \
;         __builtin_amdgcn_global_load_lds((const unsigned*)((const char*)(gbase) + (voff)[_i]), (PG8_LAS unsigned*)(lds + (bufoff) + ldsw + _i * 8192), 16, 0, 0); } while (0)
; #define PG8_LDA(dst, b, h) do { _Pragma("unroll") for (int m = 0; m < 4; ++m) _Pragma("unroll") for (int k = 0; k < 2; ++k) dst[m][k] = *(const PG8_LAS bf16x8*)(lds + PG8_SA(b, h) + aoff + m * 2048 + k * 1024); } while (0)
; #define PG8_MMA(ai, bj, At, Bt) do { __builtin_amdgcn_s_setprio(1); _Pragma("unroll") for (int m = 0; m < 4; ++m) _Pragma("unroll") for (int n = 0; n < 2; ++n) _Pragma("unroll") for (int k = 0; k < 2; ++k) \
;         acc[ai][bj][m][n] = __builtin_amdgcn_mfma_f32_16x16x32_bf16(Bt[n][k], At[m][k], acc[ai][bj][m][n], 0, 0, 0); __builtin_amdgcn_s_setprio(0); } while (0)
; #define PG8_WAIT_V(n) asm volatile("s_waitcnt vmcnt(" #n ")" ::: "memory")
; #define PG8_WAIT_L(n) asm volatile("s_waitcnt lgkmcnt(" #n ")" ::: "memory")
; #define PG8_BAR __builtin_amdgcn_s_barrier()
; #define PG8_SCHED __builtin_amdgcn_sched_barrier(0)
; template <class Epi, class Sched, bool ALIGN_EPI = false, bool SP2 = false>
; __device__ __forceinline__ void gemm_phase(PG8_LAS unsigned char* lds, const Gemm g, const Sched& S, const Epi& E) {
;     ...
;         for (int t = 0; t < nt; t += 2) {
;     ...
;             PG8_LDA(At, 1, 1); PG8_STAGE(PG8_SB(1, 0), b3, voffB); PG8_STAGE(PG8_SB(1, 1), b3 + hstep, voffB); PG8_STAGE(PG8_SA(1, 0), a3, voffA);
;             PG8_WAIT_V(8); PG8_WAIT_L(0); PG8_BAR; PG8_MMA(1, 0, At, B0); PG8_MMA(1, 1, At, B1); PG8_BAR; PG8_SCHED;
	s_add_i32 s28, s28, s12
	v_lshl_add_u64 v[210:211], v[210:211], 0, s[8:9]
	s_mov_b32 m0, s28
	ds_read_b128 v[176:179], v143 offset:49152
	ds_read_b128 v[180:183], v143 offset:50176
	ds_read_b128 v[194:197], v143 offset:51200
	ds_read_b128 v[198:201], v143 offset:52224
	ds_read_b128 v[202:205], v143 offset:53248
	ds_read_b128 v[206:209], v143 offset:54272
	ds_read_b128 v[220:223], v143 offset:55296
	ds_read_b128 v[224:227], v143 offset:56320
	global_load_lds_dwordx4 v[210:211], off
	v_lshl_add_u64 v[210:211], v[228:229], 0, s[8:9]
	s_add_i32 m0, s28, 0x2000
	s_add_i32 s28, s29, s12
	global_load_lds_dwordx4 v[210:211], off
	v_lshl_add_u64 v[210:211], v[230:231], 0, s[8:9]
	s_mov_b32 m0, s28
	s_nop 0
	global_load_lds_dwordx4 v[210:211], off
	v_lshl_add_u64 v[210:211], v[232:233], 0, s[8:9]
	s_add_i32 m0, s28, 0x2000
	s_nop 0
	global_load_lds_dwordx4 v[210:211], off
	v_lshl_add_u64 v[210:211], v[234:235], 0, s[8:9]
	s_mov_b32 m0, s26
	s_nop 0
	global_load_lds_dwordx4 v[210:211], off
	v_lshl_add_u64 v[210:211], v[236:237], 0, s[8:9]
	s_mov_b32 m0, s27
	s_nop 0
	global_load_lds_dwordx4 v[210:211], off
	s_waitcnt vmcnt(8)
	s_waitcnt lgkmcnt(0)
	s_barrier
	s_setprio 1
	s_waitcnt lgkmcnt(0)
	v_mfma_f32_16x16x32_bf16 v[64:67], v[144:147], v[176:179], v[64:67]
	v_mfma_f32_16x16x32_bf16 v[60:63], v[152:155], v[176:179], v[60:63]
	v_mfma_f32_16x16x32_bf16 v[48:51], v[144:147], v[194:197], v[48:51]
	v_mfma_f32_16x16x32_bf16 v[44:47], v[152:155], v[194:197], v[44:47]
	v_mfma_f32_16x16x32_bf16 v[32:35], v[144:147], v[202:205], v[32:35]
	v_mfma_f32_16x16x32_bf16 v[28:31], v[152:155], v[202:205], v[28:31]
	v_mfma_f32_16x16x32_bf16 v[16:19], v[144:147], v[220:223], v[16:19]
	v_mfma_f32_16x16x32_bf16 v[12:15], v[152:155], v[220:223], v[12:15]
	v_mfma_f32_16x16x32_bf16 v[64:67], v[148:151], v[180:183], v[64:67]
	v_mfma_f32_16x16x32_bf16 v[60:63], v[156:159], v[180:183], v[60:63]
	v_mfma_f32_16x16x32_bf16 v[48:51], v[148:151], v[198:201], v[48:51]
	v_mfma_f32_16x16x32_bf16 v[44:47], v[156:159], v[198:201], v[44:47]
	v_mfma_f32_16x16x32_bf16 v[32:35], v[148:151], v[206:209], v[32:35]
	v_mfma_f32_16x16x32_bf16 v[28:31], v[156:159], v[206:209], v[28:31]
	v_mfma_f32_16x16x32_bf16 v[16:19], v[148:151], v[224:227], v[16:19]
	v_mfma_f32_16x16x32_bf16 v[12:15], v[156:159], v[224:227], v[12:15]
	s_setprio 0
	s_setprio 1
	v_mfma_f32_16x16x32_bf16 v[56:59], v[160:163], v[176:179], v[56:59]
	v_mfma_f32_16x16x32_bf16 v[52:55], v[168:171], v[176:179], v[52:55]
	v_mfma_f32_16x16x32_bf16 v[40:43], v[160:163], v[194:197], v[40:43]
	v_mfma_f32_16x16x32_bf16 v[36:39], v[168:171], v[194:197], v[36:39]
	v_mfma_f32_16x16x32_bf16 v[24:27], v[160:163], v[202:205], v[24:27]
	v_mfma_f32_16x16x32_bf16 v[20:23], v[168:171], v[202:205], v[20:23]
	v_mfma_f32_16x16x32_bf16 v[8:11], v[160:163], v[220:223], v[8:11]
	v_mfma_f32_16x16x32_bf16 v[4:7], v[168:171], v[220:223], v[4:7]
	v_mfma_f32_16x16x32_bf16 v[56:59], v[164:167], v[180:183], v[56:59]
	v_mfma_f32_16x16x32_bf16 v[52:55], v[172:175], v[180:183], v[52:55]
	v_mfma_f32_16x16x32_bf16 v[40:43], v[164:167], v[198:201], v[40:43]
	v_mfma_f32_16x16x32_bf16 v[36:39], v[172:175], v[198:201], v[36:39]
	v_mfma_f32_16x16x32_bf16 v[24:27], v[164:167], v[206:209], v[24:27]
	v_mfma_f32_16x16x32_bf16 v[20:23], v[172:175], v[206:209], v[20:23]
	v_mfma_f32_16x16x32_bf16 v[8:11], v[164:167], v[224:227], v[8:11]
	v_mfma_f32_16x16x32_bf16 v[4:7], v[172:175], v[224:227], v[4:7]
	s_add_u32 s20, s20, 0x100
	s_addc_u32 s53, s53, 0
	s_add_u32 s42, s42, 0x100
	s_addc_u32 s43, s43, 0
	s_cmp_ge_i32 s64, s30
	s_mov_b32 s50, s64
	s_setprio 0
	s_barrier
	s_cbranch_scc0 .LBB0_355

; #define PG8_STAGE(bufoff, gbase, voff) do { _Pragma("unroll") for (int _i = 0; _i < 2; ++_i) \
;         __builtin_amdgcn_global_load_lds((const unsigned*)((const char*)(gbase) + (voff)[_i]), (PG8_LAS unsigned*)(lds + (bufoff) + ldsw + _i * 8192), 16, 0, 0); } while (0)
; #define PG8_LDA(dst, b, h) do { _Pragma("unroll") for (int m = 0; m < 4; ++m) _Pragma("unroll") for (int k = 0; k < 2; ++k) dst[m][k] = *(const PG8_LAS bf16x8*)(lds + PG8_SA(b, h) + aoff + m * 2048 + k * 1024); } while (0)
; #define PG8_LDB(dst, b, h) do { _Pragma("unroll") for (int n = 0; n < 2; ++n) _Pragma("unroll") for (int k = 0; k < 2; ++k) dst[n][k] = *(const PG8_LAS bf16x8*)(lds + PG8_SB(b, h) + boff + n * 2048 + k * 1024); } while (0)
; #define PG8_MMA(ai, bj, At, Bt) do { __builtin_amdgcn_s_setprio(1); _Pragma("unroll") for (int m = 0; m < 4; ++m) _Pragma("unroll") for (int n = 0; n < 2; ++n) _Pragma("unroll") for (int k = 0; k < 2; ++k) \
;         acc[ai][bj][m][n] = __builtin_amdgcn_mfma_f32_16x16x32_bf16(Bt[n][k], At[m][k], acc[ai][bj][m][n], 0, 0, 0); __builtin_amdgcn_s_setprio(0); } while (0)
; #define PG8_WAIT_V(n) asm volatile("s_waitcnt vmcnt(" #n ")" ::: "memory")
; #define PG8_BAR __builtin_amdgcn_s_barrier()
; template <class Epi, class Sched, bool ALIGN_EPI = false, bool SP2 = false>
; __device__ __forceinline__ void gemm_phase(PG8_LAS unsigned char* lds, const Gemm g, const Sched& S, const Epi& E) {
;     ...
;         for (int t = 0; t < nt; t += 2) {
;             const bool last = (t == nt - 2);
;             const char* a1 = cA + (size_t)(t + 1) * kstep;
;             const char* a2 = last ? nA : cA + (size_t)(t + 2) * kstep; const char* b2 = last ? nB : cB + (size_t)(t + 2) * kstep;
;             const char* a3 = a2 + kstep; const char* b3 = b2 + kstep;
;             if (last && has_next) S.a_ready(nxt);
;             if constexpr (SP2) {
;             PG8_LDB(B0, 0, 0); PG8_LDB(B1, 0, 1); PG8_SCHED; PG8_LDA(At, 0, 0); PG8_STAGE(PG8_SA(1, 1), a1 + hstep, voffA);
;             PG8_WAIT_V(8); PG8_WAIT_L(0); PG8_BAR; PG8_MMA(0, 0, At, B0); PG8_MMA(0, 1, At, B1); PG8_BAR; PG8_SCHED;
;             PG8_LDA(At, 0, 1); PG8_STAGE(PG8_SB(0, 0), b2, voffB); PG8_STAGE(PG8_SB(0, 1), b2 + hstep, voffB); PG8_STAGE(PG8_SA(0, 0), a2, voffA);
;             PG8_WAIT_V(8); PG8_WAIT_L(0); PG8_BAR; PG8_MMA(1, 0, At, B0); PG8_MMA(1, 1, At, B1); PG8_BAR; PG8_SCHED;
.LBB0_448:
	ds_read_b128 v[176:179], v175
	ds_read_b128 v[180:183], v175 offset:1024
	ds_read_b128 v[194:197], v175 offset:2048
	ds_read_b128 v[198:201], v175 offset:3072
	ds_read_b128 v[202:205], v175 offset:4096
	ds_read_b128 v[206:209], v175 offset:5120
	ds_read_b128 v[220:223], v175 offset:6144
	ds_read_b128 v[224:227], v175 offset:7168
	s_add_i32 s63, s33, 0x100
	v_add_u32_e32 v2, s63, v174
	ds_read_b128 v[132:135], v2
	ds_read_b128 v[136:139], v2 offset:1024
	ds_read_b128 v[140:143], v2 offset:2048
	ds_read_b128 v[144:147], v2 offset:3072
	s_add_i32 s62, s52, 2
	s_add_u32 s28, s60, 0x80
	s_addc_u32 s29, s61, 0
	s_cmp_eq_u32 s66, s52
	s_cselect_b32 s53, s43, s29
	s_cselect_b32 s52, s42, s28
	s_cselect_b32 s89, s51, s80
	s_cselect_b32 s88, s50, s77
	s_add_i32 s28, s21, 0x100
	v_add_u32_e32 v2, s28, v174
	ds_read_b128 v[148:151], v2
	ds_read_b128 v[152:155], v2 offset:1024
	ds_read_b128 v[156:159], v2 offset:2048
	ds_read_b128 v[160:163], v2 offset:3072
	v_lshl_add_u64 v[210:211], s[60:61], 0, v[172:173]
	s_add_i32 m0, s19, 0xc000
	global_load_lds_dwordx4 v[210:211], off
	v_lshl_add_u64 v[210:211], s[60:61], 0, v[170:171]
	s_add_i32 m0, s19, 0xe000
	s_nop 0
	global_load_lds_dwordx4 v[210:211], off
	s_waitcnt vmcnt(8)
	s_waitcnt lgkmcnt(0)
	s_barrier
	s_setprio 1
	s_waitcnt lgkmcnt(0)
	v_mfma_f32_16x16x32_bf16 v[128:131], v[132:135], v[176:179], v[128:131]
	v_mfma_f32_16x16x32_bf16 v[124:127], v[140:143], v[176:179], v[124:127]
	v_mfma_f32_16x16x32_bf16 v[112:115], v[132:135], v[194:197], v[112:115]
	v_mfma_f32_16x16x32_bf16 v[108:111], v[140:143], v[194:197], v[108:111]
	v_mfma_f32_16x16x32_bf16 v[96:99], v[132:135], v[202:205], v[96:99]
	v_mfma_f32_16x16x32_bf16 v[92:95], v[140:143], v[202:205], v[92:95]
	v_mfma_f32_16x16x32_bf16 v[80:83], v[132:135], v[220:223], v[80:83]
	v_mfma_f32_16x16x32_bf16 v[76:79], v[140:143], v[220:223], v[76:79]
	v_mfma_f32_16x16x32_bf16 v[128:131], v[136:139], v[180:183], v[128:131]
	v_mfma_f32_16x16x32_bf16 v[124:127], v[144:147], v[180:183], v[124:127]
	v_mfma_f32_16x16x32_bf16 v[112:115], v[136:139], v[198:201], v[112:115]
	v_mfma_f32_16x16x32_bf16 v[108:111], v[144:147], v[198:201], v[108:111]
	v_mfma_f32_16x16x32_bf16 v[96:99], v[136:139], v[206:209], v[96:99]
	v_mfma_f32_16x16x32_bf16 v[92:95], v[144:147], v[206:209], v[92:95]
	v_mfma_f32_16x16x32_bf16 v[80:83], v[136:139], v[224:227], v[80:83]
	v_mfma_f32_16x16x32_bf16 v[76:79], v[144:147], v[224:227], v[76:79]
	s_setprio 0
	s_setprio 1
	v_mfma_f32_16x16x32_bf16 v[120:123], v[148:151], v[176:179], v[120:123]
	v_mfma_f32_16x16x32_bf16 v[116:119], v[156:159], v[176:179], v[116:119]
	v_mfma_f32_16x16x32_bf16 v[104:107], v[148:151], v[194:197], v[104:107]
	v_mfma_f32_16x16x32_bf16 v[100:103], v[156:159], v[194:197], v[100:103]
	v_mfma_f32_16x16x32_bf16 v[88:91], v[148:151], v[202:205], v[88:91]
	v_mfma_f32_16x16x32_bf16 v[84:87], v[156:159], v[202:205], v[84:87]
	v_mfma_f32_16x16x32_bf16 v[72:75], v[148:151], v[220:223], v[72:75]
	v_mfma_f32_16x16x32_bf16 v[68:71], v[156:159], v[220:223], v[68:71]
	v_mfma_f32_16x16x32_bf16 v[120:123], v[152:155], v[180:183], v[120:123]
	v_mfma_f32_16x16x32_bf16 v[116:119], v[160:163], v[180:183], v[116:119]
	v_mfma_f32_16x16x32_bf16 v[104:107], v[152:155], v[198:201], v[104:107]
	v_mfma_f32_16x16x32_bf16 v[100:103], v[160:163], v[198:201], v[100:103]
	v_mfma_f32_16x16x32_bf16 v[88:91], v[152:155], v[206:209], v[88:91]
	v_mfma_f32_16x16x32_bf16 v[84:87], v[160:163], v[206:209], v[84:87]
	v_mfma_f32_16x16x32_bf16 v[72:75], v[152:155], v[224:227], v[72:75]
	v_mfma_f32_16x16x32_bf16 v[68:71], v[160:163], v[224:227], v[68:71]
	s_setprio 0
	s_barrier
	s_add_i32 s29, s63, s18
	v_lshl_add_u64 v[210:211], s[88:89], 0, v[164:165]
	s_mov_b32 m0, s29
	ds_read_b128 v[176:179], v175 offset:16384
	ds_read_b128 v[180:183], v175 offset:17408
	ds_read_b128 v[194:197], v175 offset:18432
	ds_read_b128 v[198:201], v175 offset:19456
	ds_read_b128 v[202:205], v175 offset:20480
	ds_read_b128 v[206:209], v175 offset:21504
	ds_read_b128 v[220:223], v175 offset:22528
	ds_read_b128 v[224:227], v175 offset:23552
	global_load_lds_dwordx4 v[210:211], off
	s_add_i32 m0, s29, 0x2000
	v_lshl_add_u64 v[228:229], s[88:89], 0, v[168:169]
	s_add_u32 s88, s88, s36
	s_addc_u32 s89, s89, s37
	s_add_i32 s28, s28, s18
	global_load_lds_dwordx4 v[228:229], off
	v_lshl_add_u64 v[230:231], s[88:89], 0, v[164:165]
	s_mov_b32 m0, s28
	v_lshl_add_u64 v[232:233], s[88:89], 0, v[168:169]
	global_load_lds_dwordx4 v[230:231], off
	s_add_i32 m0, s28, 0x2000
	v_lshl_add_u64 v[234:235], s[52:53], 0, v[0:1]
	global_load_lds_dwordx4 v[232:233], off
	s_mov_b32 m0, s19
	v_lshl_add_u64 v[236:237], s[52:53], 0, v[166:167]
	global_load_lds_dwordx4 v[234:235], off
	s_mov_b32 m0, s23
	s_nop 0
	global_load_lds_dwordx4 v[236:237], off
	s_waitcnt vmcnt(8)
	s_waitcnt lgkmcnt(0)
	s_barrier
; #define PG8_STAGE(bufoff, gbase, voff) do { _Pragma("unroll") for (int _i = 0; _i < 2; ++_i) \
;         __builtin_amdgcn_global_load_lds((const unsigned*)((const char*)(gbase) + (voff)[_i]), (PG8_LAS unsigned*)(lds + (bufoff) + ldsw + _i * 8192), 16, 0, 0); } while (0)
; #define PG8_LDA(dst, b, h) do { _Pragma("unroll") for (int m = 0; m < 4; ++m) _Pragma("unroll") for (int k = 0; k < 2; ++k) dst[m][k] = *(const PG8_LAS bf16x8*)(lds + PG8_SA(b, h) + aoff + m * 2048 + k * 1024); } while (0)
; #define PG8_LDB(dst, b, h) do { _Pragma("unroll") for (int n = 0; n < 2; ++n) _Pragma("unroll") for (int k = 0; k < 2; ++k) dst[n][k] = *(const PG8_LAS bf16x8*)(lds + PG8_SB(b, h) + boff + n * 2048 + k * 1024); } while (0)
; #define PG8_MMA(ai, bj, At, Bt) do { __builtin_amdgcn_s_setprio(1); _Pragma("unroll") for (int m = 0; m < 4; ++m) _Pragma("unroll") for (int n = 0; n < 2; ++n) _Pragma("unroll") for (int k = 0; k < 2; ++k) \
;         acc[ai][bj][m][n] = __builtin_amdgcn_mfma_f32_16x16x32_bf16(Bt[n][k], At[m][k], acc[ai][bj][m][n], 0, 0, 0); __builtin_amdgcn_s_setprio(0); } while (0)
; #define PG8_WAIT_V(n) asm volatile("s_waitcnt vmcnt(" #n ")" ::: "memory")
; #define PG8_WAIT_L(n) asm volatile("s_waitcnt lgkmcnt(" #n ")" ::: "memory")
; #define PG8_BAR __builtin_amdgcn_s_barrier()
; #define PG8_SCHED __builtin_amdgcn_sched_barrier(0)
; template <class Epi, class Sched, bool ALIGN_EPI = false, bool SP2 = false>
; __device__ __forceinline__ void gemm_phase(PG8_LAS unsigned char* lds, const Gemm g, const Sched& S, const Epi& E) {
;     ...
;             PG8_WAIT_V(8); PG8_WAIT_L(0); PG8_BAR; PG8_MMA(1, 0, At, B0); PG8_MMA(1, 1, At, B1); PG8_BAR; PG8_SCHED;
;             PG8_LDB(B0, 1, 0); PG8_LDB(B1, 1, 1); PG8_SCHED; PG8_LDA(At, 1, 0); PG8_STAGE(PG8_SA(0, 1), a2 + hstep, voffA);
;             PG8_WAIT_V(8); PG8_WAIT_L(0); PG8_BAR; PG8_MMA(0, 0, At, B0); PG8_MMA(0, 1, At, B1); PG8_BAR; PG8_SCHED;
	s_setprio 1
	s_waitcnt lgkmcnt(0)
	v_mfma_f32_16x16x32_bf16 v[64:67], v[132:135], v[176:179], v[64:67]
	v_mfma_f32_16x16x32_bf16 v[60:63], v[140:143], v[176:179], v[60:63]
	v_mfma_f32_16x16x32_bf16 v[48:51], v[132:135], v[194:197], v[48:51]
	v_mfma_f32_16x16x32_bf16 v[44:47], v[140:143], v[194:197], v[44:47]
	v_mfma_f32_16x16x32_bf16 v[32:35], v[132:135], v[202:205], v[32:35]
	v_mfma_f32_16x16x32_bf16 v[28:31], v[140:143], v[202:205], v[28:31]
	v_mfma_f32_16x16x32_bf16 v[16:19], v[132:135], v[220:223], v[16:19]
	v_mfma_f32_16x16x32_bf16 v[12:15], v[140:143], v[220:223], v[12:15]
	v_mfma_f32_16x16x32_bf16 v[64:67], v[136:139], v[180:183], v[64:67]
	v_mfma_f32_16x16x32_bf16 v[60:63], v[144:147], v[180:183], v[60:63]
	v_mfma_f32_16x16x32_bf16 v[48:51], v[136:139], v[198:201], v[48:51]
	v_mfma_f32_16x16x32_bf16 v[44:47], v[144:147], v[198:201], v[44:47]
	v_mfma_f32_16x16x32_bf16 v[32:35], v[136:139], v[206:209], v[32:35]
	v_mfma_f32_16x16x32_bf16 v[28:31], v[144:147], v[206:209], v[28:31]
	v_mfma_f32_16x16x32_bf16 v[16:19], v[136:139], v[224:227], v[16:19]
	v_mfma_f32_16x16x32_bf16 v[12:15], v[144:147], v[224:227], v[12:15]
	s_setprio 0
	s_setprio 1
	v_mfma_f32_16x16x32_bf16 v[56:59], v[148:151], v[176:179], v[56:59]
	v_mfma_f32_16x16x32_bf16 v[52:55], v[156:159], v[176:179], v[52:55]
	v_mfma_f32_16x16x32_bf16 v[40:43], v[148:151], v[194:197], v[40:43]
	v_mfma_f32_16x16x32_bf16 v[36:39], v[156:159], v[194:197], v[36:39]
	v_mfma_f32_16x16x32_bf16 v[24:27], v[148:151], v[202:205], v[24:27]
	v_mfma_f32_16x16x32_bf16 v[20:23], v[156:159], v[202:205], v[20:23]
	v_mfma_f32_16x16x32_bf16 v[8:11], v[148:151], v[220:223], v[8:11]
	v_mfma_f32_16x16x32_bf16 v[4:7], v[156:159], v[220:223], v[4:7]
	v_mfma_f32_16x16x32_bf16 v[56:59], v[152:155], v[180:183], v[56:59]
	v_mfma_f32_16x16x32_bf16 v[52:55], v[160:163], v[180:183], v[52:55]
	v_mfma_f32_16x16x32_bf16 v[40:43], v[152:155], v[198:201], v[40:43]
	v_mfma_f32_16x16x32_bf16 v[36:39], v[160:163], v[198:201], v[36:39]
	v_mfma_f32_16x16x32_bf16 v[24:27], v[152:155], v[206:209], v[24:27]
	v_mfma_f32_16x16x32_bf16 v[20:23], v[160:163], v[206:209], v[20:23]
	v_mfma_f32_16x16x32_bf16 v[8:11], v[152:155], v[224:227], v[8:11]
	v_mfma_f32_16x16x32_bf16 v[4:7], v[160:163], v[224:227], v[4:7]
	s_setprio 0
	s_barrier
	s_add_i32 s28, s82, 0x100
	v_add_u32_e32 v2, s28, v174
	s_add_i32 s29, s78, 0x100
	ds_read_b128 v[132:135], v2
	ds_read_b128 v[136:139], v2 offset:1024
	ds_read_b128 v[140:143], v2 offset:2048
	ds_read_b128 v[144:147], v2 offset:3072
	v_add_u32_e32 v2, s29, v174
	ds_read_b128 v[148:151], v2
	ds_read_b128 v[152:155], v2 offset:1024
	ds_read_b128 v[156:159], v2 offset:2048
	ds_read_b128 v[160:163], v2 offset:3072
	s_add_u32 s52, s52, s36
	s_addc_u32 s53, s53, s37
	s_mov_b32 m0, s25
	v_lshl_add_u64 v[238:239], s[52:53], 0, v[0:1]
	ds_read_b128 v[176:179], v175 offset:32768
	ds_read_b128 v[180:183], v175 offset:33792
	ds_read_b128 v[194:197], v175 offset:34816
	ds_read_b128 v[198:201], v175 offset:35840
	ds_read_b128 v[202:205], v175 offset:36864
	ds_read_b128 v[206:209], v175 offset:37888
	ds_read_b128 v[220:223], v175 offset:38912
	ds_read_b128 v[224:227], v175 offset:39936
	global_load_lds_dwordx4 v[238:239], off
	v_lshl_add_u64 v[238:239], s[52:53], 0, v[166:167]
	s_mov_b32 m0, s26
	s_nop 0
	global_load_lds_dwordx4 v[238:239], off
	s_waitcnt vmcnt(8)
	s_waitcnt lgkmcnt(0)
	s_barrier
	s_setprio 1
	s_waitcnt lgkmcnt(0)
	v_mfma_f32_16x16x32_bf16 v[128:131], v[132:135], v[176:179], v[128:131]
	v_mfma_f32_16x16x32_bf16 v[124:127], v[140:143], v[176:179], v[124:127]
	v_mfma_f32_16x16x32_bf16 v[112:115], v[132:135], v[194:197], v[112:115]
	v_mfma_f32_16x16x32_bf16 v[108:111], v[140:143], v[194:197], v[108:111]
	v_mfma_f32_16x16x32_bf16 v[96:99], v[132:135], v[202:205], v[96:99]
	v_mfma_f32_16x16x32_bf16 v[92:95], v[140:143], v[202:205], v[92:95]
	v_mfma_f32_16x16x32_bf16 v[80:83], v[132:135], v[220:223], v[80:83]
	v_mfma_f32_16x16x32_bf16 v[76:79], v[140:143], v[220:223], v[76:79]
	v_mfma_f32_16x16x32_bf16 v[128:131], v[136:139], v[180:183], v[128:131]
	v_mfma_f32_16x16x32_bf16 v[124:127], v[144:147], v[180:183], v[124:127]
	v_mfma_f32_16x16x32_bf16 v[112:115], v[136:139], v[198:201], v[112:115]
	v_mfma_f32_16x16x32_bf16 v[108:111], v[144:147], v[198:201], v[108:111]
	v_mfma_f32_16x16x32_bf16 v[96:99], v[136:139], v[206:209], v[96:99]
	v_mfma_f32_16x16x32_bf16 v[92:95], v[144:147], v[206:209], v[92:95]
	v_mfma_f32_16x16x32_bf16 v[80:83], v[136:139], v[224:227], v[80:83]
	v_mfma_f32_16x16x32_bf16 v[76:79], v[144:147], v[224:227], v[76:79]
	s_setprio 0
	s_setprio 1
	v_mfma_f32_16x16x32_bf16 v[120:123], v[148:151], v[176:179], v[120:123]
	v_mfma_f32_16x16x32_bf16 v[116:119], v[156:159], v[176:179], v[116:119]
	v_mfma_f32_16x16x32_bf16 v[104:107], v[148:151], v[194:197], v[104:107]
	v_mfma_f32_16x16x32_bf16 v[100:103], v[156:159], v[194:197], v[100:103]
	v_mfma_f32_16x16x32_bf16 v[88:91], v[148:151], v[202:205], v[88:91]
	v_mfma_f32_16x16x32_bf16 v[84:87], v[156:159], v[202:205], v[84:87]
	v_mfma_f32_16x16x32_bf16 v[72:75], v[148:151], v[220:223], v[72:75]
	v_mfma_f32_16x16x32_bf16 v[68:71], v[156:159], v[220:223], v[68:71]
	v_mfma_f32_16x16x32_bf16 v[120:123], v[152:155], v[180:183], v[120:123]
	v_mfma_f32_16x16x32_bf16 v[116:119], v[160:163], v[180:183], v[116:119]
	v_mfma_f32_16x16x32_bf16 v[104:107], v[152:155], v[198:201], v[104:107]
	v_mfma_f32_16x16x32_bf16 v[100:103], v[160:163], v[198:201], v[100:103]
	v_mfma_f32_16x16x32_bf16 v[88:91], v[152:155], v[206:209], v[88:91]
	v_mfma_f32_16x16x32_bf16 v[84:87], v[160:163], v[206:209], v[84:87]
	v_mfma_f32_16x16x32_bf16 v[72:75], v[152:155], v[224:227], v[72:75]
	v_mfma_f32_16x16x32_bf16 v[68:71], v[160:163], v[224:227], v[68:71]
	s_setprio 0
	s_barrier
; #define PG8_STAGE(bufoff, gbase, voff) do { _Pragma("unroll") for (int _i = 0; _i < 2; ++_i) \
;         __builtin_amdgcn_global_load_lds((const unsigned*)((const char*)(gbase) + (voff)[_i]), (PG8_LAS unsigned*)(lds + (bufoff) + ldsw + _i * 8192), 16, 0, 0); } while (0)
; #define PG8_LDA(dst, b, h) do { _Pragma("unroll") for (int m = 0; m < 4; ++m) _Pragma("unroll") for (int k = 0; k < 2; ++k) dst[m][k] = *(const PG8_LAS bf16x8*)(lds + PG8_SA(b, h) + aoff + m * 2048 + k * 1024); } while (0)
; #define PG8_MMA(ai, bj, At, Bt) do { __builtin_amdgcn_s_setprio(1); _Pragma("unroll") for (int m = 0; m < 4; ++m) _Pragma("unroll") for (int n = 0; n < 2; ++n) _Pragma("unroll") for (int k = 0; k < 2; ++k) \
;         acc[ai][bj][m][n] = __builtin_amdgcn_mfma_f32_16x16x32_bf16(Bt[n][k], At[m][k], acc[ai][bj][m][n], 0, 0, 0); __builtin_amdgcn_s_setprio(0); } while (0)
; #define PG8_WAIT_V(n) asm volatile("s_waitcnt vmcnt(" #n ")" ::: "memory")
; #define PG8_WAIT_L(n) asm volatile("s_waitcnt lgkmcnt(" #n ")" ::: "memory")
; #define PG8_BAR __builtin_amdgcn_s_barrier()
; #define PG8_SCHED __builtin_amdgcn_sched_barrier(0)
; template <class Epi, class Sched, bool ALIGN_EPI = false, bool SP2 = false>
; __device__ __forceinline__ void gemm_phase(PG8_LAS unsigned char* lds, const Gemm g, const Sched& S, const Epi& E) {
;     ...
;         for (int t = 0; t < nt; t += 2) {
;     ...
;             PG8_LDA(At, 1, 1); PG8_STAGE(PG8_SB(1, 0), b3, voffB); PG8_STAGE(PG8_SB(1, 1), b3 + hstep, voffB); PG8_STAGE(PG8_SA(1, 0), a3, voffA);
;             PG8_WAIT_V(8); PG8_WAIT_L(0); PG8_BAR; PG8_MMA(1, 0, At, B0); PG8_MMA(1, 1, At, B1); PG8_BAR; PG8_SCHED;
	s_add_i32 s28, s28, s18
	v_lshl_add_u64 v[210:211], v[210:211], 0, s[8:9]
	s_mov_b32 m0, s28
	ds_read_b128 v[176:179], v175 offset:49152
	ds_read_b128 v[180:183], v175 offset:50176
	ds_read_b128 v[194:197], v175 offset:51200
	ds_read_b128 v[198:201], v175 offset:52224
	ds_read_b128 v[202:205], v175 offset:53248
	ds_read_b128 v[206:209], v175 offset:54272
	ds_read_b128 v[220:223], v175 offset:55296
	ds_read_b128 v[224:227], v175 offset:56320
	global_load_lds_dwordx4 v[210:211], off
	v_lshl_add_u64 v[210:211], v[228:229], 0, s[8:9]
	s_add_i32 m0, s28, 0x2000
	s_add_i32 s28, s29, s18
	global_load_lds_dwordx4 v[210:211], off
	v_lshl_add_u64 v[210:211], v[230:231], 0, s[8:9]
	s_mov_b32 m0, s28
	s_nop 0
	global_load_lds_dwordx4 v[210:211], off
	v_lshl_add_u64 v[210:211], v[232:233], 0, s[8:9]
	s_add_i32 m0, s28, 0x2000
	s_nop 0
	global_load_lds_dwordx4 v[210:211], off
	v_lshl_add_u64 v[210:211], v[234:235], 0, s[8:9]
	s_mov_b32 m0, s64
	s_nop 0
	global_load_lds_dwordx4 v[210:211], off
	v_lshl_add_u64 v[210:211], v[236:237], 0, s[8:9]
	s_mov_b32 m0, s65
	s_nop 0
	global_load_lds_dwordx4 v[210:211], off
	s_waitcnt vmcnt(8)
	s_waitcnt lgkmcnt(0)
	s_barrier
	s_setprio 1
	s_waitcnt lgkmcnt(0)
	v_mfma_f32_16x16x32_bf16 v[64:67], v[132:135], v[176:179], v[64:67]
	v_mfma_f32_16x16x32_bf16 v[60:63], v[140:143], v[176:179], v[60:63]
	v_mfma_f32_16x16x32_bf16 v[48:51], v[132:135], v[194:197], v[48:51]
	v_mfma_f32_16x16x32_bf16 v[44:47], v[140:143], v[194:197], v[44:47]
	v_mfma_f32_16x16x32_bf16 v[32:35], v[132:135], v[202:205], v[32:35]
	v_mfma_f32_16x16x32_bf16 v[28:31], v[140:143], v[202:205], v[28:31]
	v_mfma_f32_16x16x32_bf16 v[16:19], v[132:135], v[220:223], v[16:19]
	v_mfma_f32_16x16x32_bf16 v[12:15], v[140:143], v[220:223], v[12:15]
	v_mfma_f32_16x16x32_bf16 v[64:67], v[136:139], v[180:183], v[64:67]
	v_mfma_f32_16x16x32_bf16 v[60:63], v[144:147], v[180:183], v[60:63]
	v_mfma_f32_16x16x32_bf16 v[48:51], v[136:139], v[198:201], v[48:51]
	v_mfma_f32_16x16x32_bf16 v[44:47], v[144:147], v[198:201], v[44:47]
	v_mfma_f32_16x16x32_bf16 v[32:35], v[136:139], v[206:209], v[32:35]
	v_mfma_f32_16x16x32_bf16 v[28:31], v[144:147], v[206:209], v[28:31]
	v_mfma_f32_16x16x32_bf16 v[16:19], v[136:139], v[224:227], v[16:19]
	v_mfma_f32_16x16x32_bf16 v[12:15], v[144:147], v[224:227], v[12:15]
	s_setprio 0
	s_setprio 1
	v_mfma_f32_16x16x32_bf16 v[56:59], v[148:151], v[176:179], v[56:59]
	v_mfma_f32_16x16x32_bf16 v[52:55], v[156:159], v[176:179], v[52:55]
	v_mfma_f32_16x16x32_bf16 v[40:43], v[148:151], v[194:197], v[40:43]
	v_mfma_f32_16x16x32_bf16 v[36:39], v[156:159], v[194:197], v[36:39]
	v_mfma_f32_16x16x32_bf16 v[24:27], v[148:151], v[202:205], v[24:27]
	v_mfma_f32_16x16x32_bf16 v[20:23], v[156:159], v[202:205], v[20:23]
	v_mfma_f32_16x16x32_bf16 v[8:11], v[148:151], v[220:223], v[8:11]
	v_mfma_f32_16x16x32_bf16 v[4:7], v[156:159], v[220:223], v[4:7]
	v_mfma_f32_16x16x32_bf16 v[56:59], v[152:155], v[180:183], v[56:59]
	v_mfma_f32_16x16x32_bf16 v[52:55], v[160:163], v[180:183], v[52:55]
	v_mfma_f32_16x16x32_bf16 v[40:43], v[152:155], v[198:201], v[40:43]
	v_mfma_f32_16x16x32_bf16 v[36:39], v[160:163], v[198:201], v[36:39]
	v_mfma_f32_16x16x32_bf16 v[24:27], v[152:155], v[206:209], v[24:27]
	v_mfma_f32_16x16x32_bf16 v[20:23], v[160:163], v[206:209], v[20:23]
	v_mfma_f32_16x16x32_bf16 v[8:11], v[152:155], v[224:227], v[8:11]
	v_mfma_f32_16x16x32_bf16 v[4:7], v[160:163], v[224:227], v[4:7]
	s_add_u32 s77, s77, 0x100
	s_addc_u32 s80, s80, 0
	s_add_u32 s60, s60, 0x100
	s_addc_u32 s61, s61, 0
	s_cmp_ge_i32 s62, s6
	s_mov_b32 s52, s62
	s_setprio 0
	s_barrier
	s_cbranch_scc0 .LBB0_448

; #define PG8_STAGE(bufoff, gbase, voff) do { _Pragma("unroll") for (int _i = 0; _i < 2; ++_i) \
;         __builtin_amdgcn_global_load_lds((const unsigned*)((const char*)(gbase) + (voff)[_i]), (PG8_LAS unsigned*)(lds + (bufoff) + ldsw + _i * 8192), 16, 0, 0); } while (0)
; #define PG8_LDA(dst, b, h) do { _Pragma("unroll") for (int m = 0; m < 4; ++m) _Pragma("unroll") for (int k = 0; k < 2; ++k) dst[m][k] = *(const PG8_LAS bf16x8*)(lds + PG8_SA(b, h) + aoff + m * 2048 + k * 1024); } while (0)
; #define PG8_LDB(dst, b, h) do { _Pragma("unroll") for (int n = 0; n < 2; ++n) _Pragma("unroll") for (int k = 0; k < 2; ++k) dst[n][k] = *(const PG8_LAS bf16x8*)(lds + PG8_SB(b, h) + boff + n * 2048 + k * 1024); } while (0)
; #define PG8_MMA(ai, bj, At, Bt) do { __builtin_amdgcn_s_setprio(1); _Pragma("unroll") for (int m = 0; m < 4; ++m) _Pragma("unroll") for (int n = 0; n < 2; ++n) _Pragma("unroll") for (int k = 0; k < 2; ++k) \
;         acc[ai][bj][m][n] = __builtin_amdgcn_mfma_f32_16x16x32_bf16(Bt[n][k], At[m][k], acc[ai][bj][m][n], 0, 0, 0); __builtin_amdgcn_s_setprio(0); } while (0)
; #define PG8_WAIT_V(n) asm volatile("s_waitcnt vmcnt(" #n ")" ::: "memory")
; #define PG8_BAR __builtin_amdgcn_s_barrier()
; template <class Epi, class Sched, bool ALIGN_EPI = false, bool SP2 = false>
; __device__ __forceinline__ void gemm_phase(PG8_LAS unsigned char* lds, const Gemm g, const Sched& S, const Epi& E) {
;     ...
;         for (int t = 0; t < nt; t += 2) {
;             const bool last = (t == nt - 2);
;             const char* a1 = cA + (size_t)(t + 1) * kstep;
;             const char* a2 = last ? nA : cA + (size_t)(t + 2) * kstep; const char* b2 = last ? nB : cB + (size_t)(t + 2) * kstep;
;             const char* a3 = a2 + kstep; const char* b3 = b2 + kstep;
;             if (last && has_next) S.a_ready(nxt);
;             if constexpr (SP2) {
;             PG8_LDB(B0, 0, 0); PG8_LDB(B1, 0, 1); PG8_SCHED; PG8_LDA(At, 0, 0); PG8_STAGE(PG8_SA(1, 1), a1 + hstep, voffA);
;             PG8_WAIT_V(8); PG8_WAIT_L(0); PG8_BAR; PG8_MMA(0, 0, At, B0); PG8_MMA(0, 1, At, B1); PG8_BAR; PG8_SCHED;
;             PG8_LDA(At, 0, 1); PG8_STAGE(PG8_SB(0, 0), b2, voffB); PG8_STAGE(PG8_SB(0, 1), b2 + hstep, voffB); PG8_STAGE(PG8_SA(0, 0), a2, voffA);
;             PG8_WAIT_V(8); PG8_WAIT_L(0); PG8_BAR; PG8_MMA(1, 0, At, B0); PG8_MMA(1, 1, At, B1); PG8_BAR; PG8_SCHED;
.LBB0_489:
	ds_read_b128 v[194:197], v152
	ds_read_b128 v[198:201], v152 offset:1024
	ds_read_b128 v[202:205], v152 offset:2048
	ds_read_b128 v[206:209], v152 offset:3072
	ds_read_b128 v[220:223], v152 offset:4096
	ds_read_b128 v[224:227], v152 offset:5120
	ds_read_b128 v[228:231], v152 offset:6144
	ds_read_b128 v[232:235], v152 offset:7168
	s_add_i32 s66, s33, 0x100
	v_add_u32_e32 v2, s66, v149
	ds_read_b128 v[142:145], v2
	ds_read_b128 v[154:157], v2 offset:1024
	ds_read_b128 v[158:161], v2 offset:2048
	ds_read_b128 v[162:165], v2 offset:3072
	s_add_i32 s27, s26, 2
	s_add_u32 s28, s38, 0x80
	s_addc_u32 s29, s39, 0
	s_cmp_eq_u32 s95, s26
	s_cselect_b32 s51, s43, s29
	s_cselect_b32 s50, s42, s28
	s_cselect_b32 s53, s65, s20
	s_cselect_b32 s52, s64, s4
	s_add_i32 s26, s21, 0x100
	v_add_u32_e32 v2, s26, v149
	ds_read_b128 v[166:169], v2
	ds_read_b128 v[170:173], v2 offset:1024
	ds_read_b128 v[174:177], v2 offset:2048
	ds_read_b128 v[178:181], v2 offset:3072
	v_lshl_add_u64 v[146:147], s[38:39], 0, v[140:141]
	s_add_i32 m0, s87, 0xc000
	global_load_lds_dwordx4 v[146:147], off
	v_lshl_add_u64 v[146:147], s[38:39], 0, v[138:139]
	s_add_i32 m0, s87, 0xe000
	s_nop 0
	global_load_lds_dwordx4 v[146:147], off
	s_waitcnt vmcnt(8)
	s_waitcnt lgkmcnt(0)
	s_barrier
	s_setprio 1
	s_waitcnt lgkmcnt(0)
	v_mfma_f32_16x16x32_bf16 v[128:131], v[142:145], v[194:197], v[128:131]
	v_mfma_f32_16x16x32_bf16 v[124:127], v[158:161], v[194:197], v[124:127]
	v_mfma_f32_16x16x32_bf16 v[112:115], v[142:145], v[202:205], v[112:115]
	v_mfma_f32_16x16x32_bf16 v[108:111], v[158:161], v[202:205], v[108:111]
	v_mfma_f32_16x16x32_bf16 v[96:99], v[142:145], v[220:223], v[96:99]
	v_mfma_f32_16x16x32_bf16 v[92:95], v[158:161], v[220:223], v[92:95]
	v_mfma_f32_16x16x32_bf16 v[80:83], v[142:145], v[228:231], v[80:83]
	v_mfma_f32_16x16x32_bf16 v[76:79], v[158:161], v[228:231], v[76:79]
	v_mfma_f32_16x16x32_bf16 v[128:131], v[154:157], v[198:201], v[128:131]
	v_mfma_f32_16x16x32_bf16 v[124:127], v[162:165], v[198:201], v[124:127]
	v_mfma_f32_16x16x32_bf16 v[112:115], v[154:157], v[206:209], v[112:115]
	v_mfma_f32_16x16x32_bf16 v[108:111], v[162:165], v[206:209], v[108:111]
	v_mfma_f32_16x16x32_bf16 v[96:99], v[154:157], v[224:227], v[96:99]
	v_mfma_f32_16x16x32_bf16 v[92:95], v[162:165], v[224:227], v[92:95]
	v_mfma_f32_16x16x32_bf16 v[80:83], v[154:157], v[232:235], v[80:83]
	v_mfma_f32_16x16x32_bf16 v[76:79], v[162:165], v[232:235], v[76:79]
	s_setprio 0
	s_setprio 1
	v_mfma_f32_16x16x32_bf16 v[120:123], v[166:169], v[194:197], v[120:123]
	v_mfma_f32_16x16x32_bf16 v[116:119], v[174:177], v[194:197], v[116:119]
	v_mfma_f32_16x16x32_bf16 v[104:107], v[166:169], v[202:205], v[104:107]
	v_mfma_f32_16x16x32_bf16 v[100:103], v[174:177], v[202:205], v[100:103]
	v_mfma_f32_16x16x32_bf16 v[88:91], v[166:169], v[220:223], v[88:91]
	v_mfma_f32_16x16x32_bf16 v[84:87], v[174:177], v[220:223], v[84:87]
	v_mfma_f32_16x16x32_bf16 v[72:75], v[166:169], v[228:231], v[72:75]
	v_mfma_f32_16x16x32_bf16 v[68:71], v[174:177], v[228:231], v[68:71]
	v_mfma_f32_16x16x32_bf16 v[120:123], v[170:173], v[198:201], v[120:123]
	v_mfma_f32_16x16x32_bf16 v[116:119], v[178:181], v[198:201], v[116:119]
	v_mfma_f32_16x16x32_bf16 v[104:107], v[170:173], v[206:209], v[104:107]
	v_mfma_f32_16x16x32_bf16 v[100:103], v[178:181], v[206:209], v[100:103]
	v_mfma_f32_16x16x32_bf16 v[88:91], v[170:173], v[224:227], v[88:91]
	v_mfma_f32_16x16x32_bf16 v[84:87], v[178:181], v[224:227], v[84:87]
	v_mfma_f32_16x16x32_bf16 v[72:75], v[170:173], v[232:235], v[72:75]
	v_mfma_f32_16x16x32_bf16 v[68:71], v[178:181], v[232:235], v[68:71]
	s_setprio 0
	s_barrier
	s_add_i32 s28, s66, s25
	v_lshl_add_u64 v[146:147], s[52:53], 0, v[134:135]
	s_mov_b32 m0, s28
	ds_read_b128 v[194:197], v152 offset:16384
	ds_read_b128 v[198:201], v152 offset:17408
	ds_read_b128 v[202:205], v152 offset:18432
	ds_read_b128 v[206:209], v152 offset:19456
	ds_read_b128 v[220:223], v152 offset:20480
	ds_read_b128 v[224:227], v152 offset:21504
	ds_read_b128 v[228:231], v152 offset:22528
	ds_read_b128 v[232:235], v152 offset:23552
	global_load_lds_dwordx4 v[146:147], off
	s_add_i32 m0, s28, 0x2000
	v_lshl_add_u64 v[150:151], s[52:53], 0, v[0:1]
	s_add_u32 s52, s52, s36
	s_addc_u32 s53, s53, s37
	s_add_i32 s26, s26, s25
	global_load_lds_dwordx4 v[150:151], off
	v_lshl_add_u64 v[182:183], s[52:53], 0, v[134:135]
	s_mov_b32 m0, s26
	v_lshl_add_u64 v[210:211], s[52:53], 0, v[0:1]
	global_load_lds_dwordx4 v[182:183], off
	s_add_i32 m0, s26, 0x2000
	v_lshl_add_u64 v[236:237], s[50:51], 0, v[136:137]
	global_load_lds_dwordx4 v[210:211], off
	s_mov_b32 m0, s87
	v_lshl_add_u64 v[238:239], s[50:51], 0, v[132:133]
	global_load_lds_dwordx4 v[236:237], off
	s_mov_b32 m0, s88
	s_nop 0
	global_load_lds_dwordx4 v[238:239], off
	s_waitcnt vmcnt(8)
	s_waitcnt lgkmcnt(0)
	s_barrier
; #define PG8_STAGE(bufoff, gbase, voff) do { _Pragma("unroll") for (int _i = 0; _i < 2; ++_i) \
;         __builtin_amdgcn_global_load_lds((const unsigned*)((const char*)(gbase) + (voff)[_i]), (PG8_LAS unsigned*)(lds + (bufoff) + ldsw + _i * 8192), 16, 0, 0); } while (0)
; #define PG8_LDA(dst, b, h) do { _Pragma("unroll") for (int m = 0; m < 4; ++m) _Pragma("unroll") for (int k = 0; k < 2; ++k) dst[m][k] = *(const PG8_LAS bf16x8*)(lds + PG8_SA(b, h) + aoff + m * 2048 + k * 1024); } while (0)
; #define PG8_LDB(dst, b, h) do { _Pragma("unroll") for (int n = 0; n < 2; ++n) _Pragma("unroll") for (int k = 0; k < 2; ++k) dst[n][k] = *(const PG8_LAS bf16x8*)(lds + PG8_SB(b, h) + boff + n * 2048 + k * 1024); } while (0)
; #define PG8_MMA(ai, bj, At, Bt) do { __builtin_amdgcn_s_setprio(1); _Pragma("unroll") for (int m = 0; m < 4; ++m) _Pragma("unroll") for (int n = 0; n < 2; ++n) _Pragma("unroll") for (int k = 0; k < 2; ++k) \
;         acc[ai][bj][m][n] = __builtin_amdgcn_mfma_f32_16x16x32_bf16(Bt[n][k], At[m][k], acc[ai][bj][m][n], 0, 0, 0); __builtin_amdgcn_s_setprio(0); } while (0)
; #define PG8_WAIT_V(n) asm volatile("s_waitcnt vmcnt(" #n ")" ::: "memory")
; #define PG8_WAIT_L(n) asm volatile("s_waitcnt lgkmcnt(" #n ")" ::: "memory")
; #define PG8_BAR __builtin_amdgcn_s_barrier()
; #define PG8_SCHED __builtin_amdgcn_sched_barrier(0)
; template <class Epi, class Sched, bool ALIGN_EPI = false, bool SP2 = false>
; __device__ __forceinline__ void gemm_phase(PG8_LAS unsigned char* lds, const Gemm g, const Sched& S, const Epi& E) {
;     ...
;             PG8_WAIT_V(8); PG8_WAIT_L(0); PG8_BAR; PG8_MMA(1, 0, At, B0); PG8_MMA(1, 1, At, B1); PG8_BAR; PG8_SCHED;
;             PG8_LDB(B0, 1, 0); PG8_LDB(B1, 1, 1); PG8_SCHED; PG8_LDA(At, 1, 0); PG8_STAGE(PG8_SA(0, 1), a2 + hstep, voffA);
;             PG8_WAIT_V(8); PG8_WAIT_L(0); PG8_BAR; PG8_MMA(0, 0, At, B0); PG8_MMA(0, 1, At, B1); PG8_BAR; PG8_SCHED;
	s_setprio 1
	s_waitcnt lgkmcnt(0)
	v_mfma_f32_16x16x32_bf16 v[64:67], v[142:145], v[194:197], v[64:67]
	v_mfma_f32_16x16x32_bf16 v[60:63], v[158:161], v[194:197], v[60:63]
	v_mfma_f32_16x16x32_bf16 v[48:51], v[142:145], v[202:205], v[48:51]
	v_mfma_f32_16x16x32_bf16 v[44:47], v[158:161], v[202:205], v[44:47]
	v_mfma_f32_16x16x32_bf16 v[32:35], v[142:145], v[220:223], v[32:35]
	v_mfma_f32_16x16x32_bf16 v[28:31], v[158:161], v[220:223], v[28:31]
	v_mfma_f32_16x16x32_bf16 v[16:19], v[142:145], v[228:231], v[16:19]
	v_mfma_f32_16x16x32_bf16 v[12:15], v[158:161], v[228:231], v[12:15]
	v_mfma_f32_16x16x32_bf16 v[64:67], v[154:157], v[198:201], v[64:67]
	v_mfma_f32_16x16x32_bf16 v[60:63], v[162:165], v[198:201], v[60:63]
	v_mfma_f32_16x16x32_bf16 v[48:51], v[154:157], v[206:209], v[48:51]
	v_mfma_f32_16x16x32_bf16 v[44:47], v[162:165], v[206:209], v[44:47]
	v_mfma_f32_16x16x32_bf16 v[32:35], v[154:157], v[224:227], v[32:35]
	v_mfma_f32_16x16x32_bf16 v[28:31], v[162:165], v[224:227], v[28:31]
	v_mfma_f32_16x16x32_bf16 v[16:19], v[154:157], v[232:235], v[16:19]
	v_mfma_f32_16x16x32_bf16 v[12:15], v[162:165], v[232:235], v[12:15]
	s_setprio 0
	s_setprio 1
	v_mfma_f32_16x16x32_bf16 v[56:59], v[166:169], v[194:197], v[56:59]
	v_mfma_f32_16x16x32_bf16 v[52:55], v[174:177], v[194:197], v[52:55]
	v_mfma_f32_16x16x32_bf16 v[40:43], v[166:169], v[202:205], v[40:43]
	v_mfma_f32_16x16x32_bf16 v[36:39], v[174:177], v[202:205], v[36:39]
	v_mfma_f32_16x16x32_bf16 v[24:27], v[166:169], v[220:223], v[24:27]
	v_mfma_f32_16x16x32_bf16 v[20:23], v[174:177], v[220:223], v[20:23]
	v_mfma_f32_16x16x32_bf16 v[8:11], v[166:169], v[228:231], v[8:11]
	v_mfma_f32_16x16x32_bf16 v[4:7], v[174:177], v[228:231], v[4:7]
	v_mfma_f32_16x16x32_bf16 v[56:59], v[170:173], v[198:201], v[56:59]
	v_mfma_f32_16x16x32_bf16 v[52:55], v[178:181], v[198:201], v[52:55]
	v_mfma_f32_16x16x32_bf16 v[40:43], v[170:173], v[206:209], v[40:43]
	v_mfma_f32_16x16x32_bf16 v[36:39], v[178:181], v[206:209], v[36:39]
	v_mfma_f32_16x16x32_bf16 v[24:27], v[170:173], v[224:227], v[24:27]
	v_mfma_f32_16x16x32_bf16 v[20:23], v[178:181], v[224:227], v[20:23]
	v_mfma_f32_16x16x32_bf16 v[8:11], v[170:173], v[232:235], v[8:11]
	v_mfma_f32_16x16x32_bf16 v[4:7], v[178:181], v[232:235], v[4:7]
	s_setprio 0
	s_barrier
	s_add_i32 s26, s82, 0x100
	v_add_u32_e32 v2, s26, v149
	s_add_i32 s28, s78, 0x100
	ds_read_b128 v[142:145], v2
	ds_read_b128 v[154:157], v2 offset:1024
	ds_read_b128 v[158:161], v2 offset:2048
	ds_read_b128 v[162:165], v2 offset:3072
	v_add_u32_e32 v2, s28, v149
	ds_read_b128 v[166:169], v2
	ds_read_b128 v[170:173], v2 offset:1024
	ds_read_b128 v[174:177], v2 offset:2048
	ds_read_b128 v[178:181], v2 offset:3072
	s_add_u32 s50, s50, s36
	s_addc_u32 s51, s51, s37
	s_mov_b32 m0, s89
	v_lshl_add_u64 v[244:245], s[50:51], 0, v[136:137]
	ds_read_b128 v[194:197], v152 offset:32768
	ds_read_b128 v[198:201], v152 offset:33792
	ds_read_b128 v[202:205], v152 offset:34816
	ds_read_b128 v[206:209], v152 offset:35840
	ds_read_b128 v[220:223], v152 offset:36864
	ds_read_b128 v[224:227], v152 offset:37888
	ds_read_b128 v[228:231], v152 offset:38912
	ds_read_b128 v[232:235], v152 offset:39936
	global_load_lds_dwordx4 v[244:245], off
	v_lshl_add_u64 v[244:245], s[50:51], 0, v[132:133]
	s_mov_b32 m0, s90
	s_nop 0
	global_load_lds_dwordx4 v[244:245], off
	s_waitcnt vmcnt(8)
	s_waitcnt lgkmcnt(0)
	s_barrier
	s_setprio 1
	s_waitcnt lgkmcnt(0)
	v_mfma_f32_16x16x32_bf16 v[128:131], v[142:145], v[194:197], v[128:131]
	v_mfma_f32_16x16x32_bf16 v[124:127], v[158:161], v[194:197], v[124:127]
	v_mfma_f32_16x16x32_bf16 v[112:115], v[142:145], v[202:205], v[112:115]
	v_mfma_f32_16x16x32_bf16 v[108:111], v[158:161], v[202:205], v[108:111]
	v_mfma_f32_16x16x32_bf16 v[96:99], v[142:145], v[220:223], v[96:99]
	v_mfma_f32_16x16x32_bf16 v[92:95], v[158:161], v[220:223], v[92:95]
	v_mfma_f32_16x16x32_bf16 v[80:83], v[142:145], v[228:231], v[80:83]
	v_mfma_f32_16x16x32_bf16 v[76:79], v[158:161], v[228:231], v[76:79]
	v_mfma_f32_16x16x32_bf16 v[128:131], v[154:157], v[198:201], v[128:131]
	v_mfma_f32_16x16x32_bf16 v[124:127], v[162:165], v[198:201], v[124:127]
	v_mfma_f32_16x16x32_bf16 v[112:115], v[154:157], v[206:209], v[112:115]
	v_mfma_f32_16x16x32_bf16 v[108:111], v[162:165], v[206:209], v[108:111]
	v_mfma_f32_16x16x32_bf16 v[96:99], v[154:157], v[224:227], v[96:99]
	v_mfma_f32_16x16x32_bf16 v[92:95], v[162:165], v[224:227], v[92:95]
	v_mfma_f32_16x16x32_bf16 v[80:83], v[154:157], v[232:235], v[80:83]
	v_mfma_f32_16x16x32_bf16 v[76:79], v[162:165], v[232:235], v[76:79]
	s_setprio 0
	s_setprio 1
	v_mfma_f32_16x16x32_bf16 v[120:123], v[166:169], v[194:197], v[120:123]
	v_mfma_f32_16x16x32_bf16 v[116:119], v[174:177], v[194:197], v[116:119]
	v_mfma_f32_16x16x32_bf16 v[104:107], v[166:169], v[202:205], v[104:107]
	v_mfma_f32_16x16x32_bf16 v[100:103], v[174:177], v[202:205], v[100:103]
	v_mfma_f32_16x16x32_bf16 v[88:91], v[166:169], v[220:223], v[88:91]
	v_mfma_f32_16x16x32_bf16 v[84:87], v[174:177], v[220:223], v[84:87]
	v_mfma_f32_16x16x32_bf16 v[72:75], v[166:169], v[228:231], v[72:75]
	v_mfma_f32_16x16x32_bf16 v[68:71], v[174:177], v[228:231], v[68:71]
	v_mfma_f32_16x16x32_bf16 v[120:123], v[170:173], v[198:201], v[120:123]
	v_mfma_f32_16x16x32_bf16 v[116:119], v[178:181], v[198:201], v[116:119]
	v_mfma_f32_16x16x32_bf16 v[104:107], v[170:173], v[206:209], v[104:107]
	v_mfma_f32_16x16x32_bf16 v[100:103], v[178:181], v[206:209], v[100:103]
	v_mfma_f32_16x16x32_bf16 v[88:91], v[170:173], v[224:227], v[88:91]
	v_mfma_f32_16x16x32_bf16 v[84:87], v[178:181], v[224:227], v[84:87]
	v_mfma_f32_16x16x32_bf16 v[72:75], v[170:173], v[232:235], v[72:75]
	v_mfma_f32_16x16x32_bf16 v[68:71], v[178:181], v[232:235], v[68:71]
	s_setprio 0
	s_barrier
; #define PG8_STAGE(bufoff, gbase, voff) do { _Pragma("unroll") for (int _i = 0; _i < 2; ++_i) \
;         __builtin_amdgcn_global_load_lds((const unsigned*)((const char*)(gbase) + (voff)[_i]), (PG8_LAS unsigned*)(lds + (bufoff) + ldsw + _i * 8192), 16, 0, 0); } while (0)
; #define PG8_LDA(dst, b, h) do { _Pragma("unroll") for (int m = 0; m < 4; ++m) _Pragma("unroll") for (int k = 0; k < 2; ++k) dst[m][k] = *(const PG8_LAS bf16x8*)(lds + PG8_SA(b, h) + aoff + m * 2048 + k * 1024); } while (0)
; #define PG8_MMA(ai, bj, At, Bt) do { __builtin_amdgcn_s_setprio(1); _Pragma("unroll") for (int m = 0; m < 4; ++m) _Pragma("unroll") for (int n = 0; n < 2; ++n) _Pragma("unroll") for (int k = 0; k < 2; ++k) \
;         acc[ai][bj][m][n] = __builtin_amdgcn_mfma_f32_16x16x32_bf16(Bt[n][k], At[m][k], acc[ai][bj][m][n], 0, 0, 0); __builtin_amdgcn_s_setprio(0); } while (0)
; #define PG8_WAIT_V(n) asm volatile("s_waitcnt vmcnt(" #n ")" ::: "memory")
; #define PG8_WAIT_L(n) asm volatile("s_waitcnt lgkmcnt(" #n ")" ::: "memory")
; #define PG8_BAR __builtin_amdgcn_s_barrier()
; #define PG8_SCHED __builtin_amdgcn_sched_barrier(0)
; template <class Epi, class Sched, bool ALIGN_EPI = false, bool SP2 = false>
; __device__ __forceinline__ void gemm_phase(PG8_LAS unsigned char* lds, const Gemm g, const Sched& S, const Epi& E) {
;     ...
;         for (int t = 0; t < nt; t += 2) {
;     ...
;             PG8_LDA(At, 1, 1); PG8_STAGE(PG8_SB(1, 0), b3, voffB); PG8_STAGE(PG8_SB(1, 1), b3 + hstep, voffB); PG8_STAGE(PG8_SA(1, 0), a3, voffA);
;             PG8_WAIT_V(8); PG8_WAIT_L(0); PG8_BAR; PG8_MMA(1, 0, At, B0); PG8_MMA(1, 1, At, B1); PG8_BAR; PG8_SCHED;
	s_add_i32 s26, s26, s25
	v_lshl_add_u64 v[146:147], v[146:147], 0, s[8:9]
	s_mov_b32 m0, s26
	ds_read_b128 v[194:197], v152 offset:49152
	ds_read_b128 v[198:201], v152 offset:50176
	ds_read_b128 v[202:205], v152 offset:51200
	ds_read_b128 v[206:209], v152 offset:52224
	ds_read_b128 v[220:223], v152 offset:53248
	ds_read_b128 v[224:227], v152 offset:54272
	ds_read_b128 v[228:231], v152 offset:55296
	ds_read_b128 v[232:235], v152 offset:56320
	global_load_lds_dwordx4 v[146:147], off
	v_lshl_add_u64 v[146:147], v[150:151], 0, s[8:9]
	s_add_i32 m0, s26, 0x2000
	s_add_i32 s26, s28, s25
	global_load_lds_dwordx4 v[146:147], off
	v_lshl_add_u64 v[146:147], v[182:183], 0, s[8:9]
	s_mov_b32 m0, s26
	s_nop 0
	global_load_lds_dwordx4 v[146:147], off
	v_lshl_add_u64 v[146:147], v[210:211], 0, s[8:9]
	s_add_i32 m0, s26, 0x2000
	s_nop 0
	global_load_lds_dwordx4 v[146:147], off
	v_lshl_add_u64 v[146:147], v[236:237], 0, s[8:9]
	s_mov_b32 m0, s93
	s_nop 0
	global_load_lds_dwordx4 v[146:147], off
	v_lshl_add_u64 v[146:147], v[238:239], 0, s[8:9]
	s_mov_b32 m0, s94
	s_nop 0
	global_load_lds_dwordx4 v[146:147], off
	s_waitcnt vmcnt(8)
	s_waitcnt lgkmcnt(0)
	s_barrier
	s_setprio 1
	s_waitcnt lgkmcnt(0)
	v_mfma_f32_16x16x32_bf16 v[64:67], v[142:145], v[194:197], v[64:67]
	v_mfma_f32_16x16x32_bf16 v[60:63], v[158:161], v[194:197], v[60:63]
	v_mfma_f32_16x16x32_bf16 v[48:51], v[142:145], v[202:205], v[48:51]
	v_mfma_f32_16x16x32_bf16 v[44:47], v[158:161], v[202:205], v[44:47]
	v_mfma_f32_16x16x32_bf16 v[32:35], v[142:145], v[220:223], v[32:35]
	v_mfma_f32_16x16x32_bf16 v[28:31], v[158:161], v[220:223], v[28:31]
	v_mfma_f32_16x16x32_bf16 v[16:19], v[142:145], v[228:231], v[16:19]
	v_mfma_f32_16x16x32_bf16 v[12:15], v[158:161], v[228:231], v[12:15]
	v_mfma_f32_16x16x32_bf16 v[64:67], v[154:157], v[198:201], v[64:67]
	v_mfma_f32_16x16x32_bf16 v[60:63], v[162:165], v[198:201], v[60:63]
	v_mfma_f32_16x16x32_bf16 v[48:51], v[154:157], v[206:209], v[48:51]
	v_mfma_f32_16x16x32_bf16 v[44:47], v[162:165], v[206:209], v[44:47]
	v_mfma_f32_16x16x32_bf16 v[32:35], v[154:157], v[224:227], v[32:35]
	v_mfma_f32_16x16x32_bf16 v[28:31], v[162:165], v[224:227], v[28:31]
	v_mfma_f32_16x16x32_bf16 v[16:19], v[154:157], v[232:235], v[16:19]
	v_mfma_f32_16x16x32_bf16 v[12:15], v[162:165], v[232:235], v[12:15]
	s_setprio 0
	s_setprio 1
	v_mfma_f32_16x16x32_bf16 v[56:59], v[166:169], v[194:197], v[56:59]
	v_mfma_f32_16x16x32_bf16 v[52:55], v[174:177], v[194:197], v[52:55]
	v_mfma_f32_16x16x32_bf16 v[40:43], v[166:169], v[202:205], v[40:43]
	v_mfma_f32_16x16x32_bf16 v[36:39], v[174:177], v[202:205], v[36:39]
	v_mfma_f32_16x16x32_bf16 v[24:27], v[166:169], v[220:223], v[24:27]
	v_mfma_f32_16x16x32_bf16 v[20:23], v[174:177], v[220:223], v[20:23]
	v_mfma_f32_16x16x32_bf16 v[8:11], v[166:169], v[228:231], v[8:11]
	v_mfma_f32_16x16x32_bf16 v[4:7], v[174:177], v[228:231], v[4:7]
	v_mfma_f32_16x16x32_bf16 v[56:59], v[170:173], v[198:201], v[56:59]
	v_mfma_f32_16x16x32_bf16 v[52:55], v[178:181], v[198:201], v[52:55]
	v_mfma_f32_16x16x32_bf16 v[40:43], v[170:173], v[206:209], v[40:43]
	v_mfma_f32_16x16x32_bf16 v[36:39], v[178:181], v[206:209], v[36:39]
	v_mfma_f32_16x16x32_bf16 v[24:27], v[170:173], v[224:227], v[24:27]
	v_mfma_f32_16x16x32_bf16 v[20:23], v[178:181], v[224:227], v[20:23]
	v_mfma_f32_16x16x32_bf16 v[8:11], v[170:173], v[232:235], v[8:11]
	v_mfma_f32_16x16x32_bf16 v[4:7], v[178:181], v[232:235], v[4:7]
	s_add_u32 s4, s4, 0x100
	s_addc_u32 s20, s20, 0
	s_add_u32 s38, s38, 0x100
	s_addc_u32 s39, s39, 0
	s_cmp_ge_i32 s27, s6
	s_mov_b32 s26, s27
	s_setprio 0
	s_barrier
	s_cbranch_scc0 .LBB0_489

; #define PG8_STAGE(bufoff, gbase, voff) do { _Pragma("unroll") for (int _i = 0; _i < 2; ++_i) \
;         __builtin_amdgcn_global_load_lds((const unsigned*)((const char*)(gbase) + (voff)[_i]), (PG8_LAS unsigned*)(lds + (bufoff) + ldsw + _i * 8192), 16, 0, 0); } while (0)
; #define PG8_LDA(dst, b, h) do { _Pragma("unroll") for (int m = 0; m < 4; ++m) _Pragma("unroll") for (int k = 0; k < 2; ++k) dst[m][k] = *(const PG8_LAS bf16x8*)(lds + PG8_SA(b, h) + aoff + m * 2048 + k * 1024); } while (0)
; #define PG8_LDB(dst, b, h) do { _Pragma("unroll") for (int n = 0; n < 2; ++n) _Pragma("unroll") for (int k = 0; k < 2; ++k) dst[n][k] = *(const PG8_LAS bf16x8*)(lds + PG8_SB(b, h) + boff + n * 2048 + k * 1024); } while (0)
; #define PG8_MMA(ai, bj, At, Bt) do { __builtin_amdgcn_s_setprio(1); _Pragma("unroll") for (int m = 0; m < 4; ++m) _Pragma("unroll") for (int n = 0; n < 2; ++n) _Pragma("unroll") for (int k = 0; k < 2; ++k) \
;         acc[ai][bj][m][n] = __builtin_amdgcn_mfma_f32_16x16x32_bf16(Bt[n][k], At[m][k], acc[ai][bj][m][n], 0, 0, 0); __builtin_amdgcn_s_setprio(0); } while (0)
; #define PG8_WAIT_V(n) asm volatile("s_waitcnt vmcnt(" #n ")" ::: "memory")
; #define PG8_BAR __builtin_amdgcn_s_barrier()
; template <class Epi, class Sched, bool ALIGN_EPI = false, bool SP2 = false>
; __device__ __forceinline__ void gemm_phase(PG8_LAS unsigned char* lds, const Gemm g, const Sched& S, const Epi& E) {
;     ...
;         for (int t = 0; t < nt; t += 2) {
;             const bool last = (t == nt - 2);
;             const char* a1 = cA + (size_t)(t + 1) * kstep;
;             const char* a2 = last ? nA : cA + (size_t)(t + 2) * kstep; const char* b2 = last ? nB : cB + (size_t)(t + 2) * kstep;
;             const char* a3 = a2 + kstep; const char* b3 = b2 + kstep;
;             if (last && has_next) S.a_ready(nxt);
;             if constexpr (SP2) {
;             PG8_LDB(B0, 0, 0); PG8_LDB(B1, 0, 1); PG8_SCHED; PG8_LDA(At, 0, 0); PG8_STAGE(PG8_SA(1, 1), a1 + hstep, voffA);
;             PG8_WAIT_V(8); PG8_WAIT_L(0); PG8_BAR; PG8_MMA(0, 0, At, B0); PG8_MMA(0, 1, At, B1); PG8_BAR; PG8_SCHED;
;             PG8_LDA(At, 0, 1); PG8_STAGE(PG8_SB(0, 0), b2, voffB); PG8_STAGE(PG8_SB(0, 1), b2 + hstep, voffB); PG8_STAGE(PG8_SA(0, 0), a2, voffA);
;             PG8_WAIT_V(8); PG8_WAIT_L(0); PG8_BAR; PG8_MMA(1, 0, At, B0); PG8_MMA(1, 1, At, B1); PG8_BAR; PG8_SCHED;
.LBB0_530:
	ds_read_b128 v[178:181], v145
	ds_read_b128 v[194:197], v145 offset:1024
	ds_read_b128 v[198:201], v145 offset:2048
	ds_read_b128 v[202:205], v145 offset:3072
	ds_read_b128 v[206:209], v145 offset:4096
	ds_read_b128 v[220:223], v145 offset:5120
	ds_read_b128 v[224:227], v145 offset:6144
	ds_read_b128 v[228:231], v145 offset:7168
	s_add_i32 s59, s33, 0x100
	v_add_u32_e32 v2, s59, v144
	ds_read_b128 v[146:149], v2
	ds_read_b128 v[150:153], v2 offset:1024
	ds_read_b128 v[154:157], v2 offset:2048
	ds_read_b128 v[158:161], v2 offset:3072
	s_add_i32 s58, s27, 2
	s_add_u32 s28, s38, 0x80
	s_addc_u32 s29, s39, 0
	s_cmp_eq_u32 s80, s27
	s_cselect_b32 s51, s43, s29
	s_cselect_b32 s50, s42, s28
	s_cselect_b32 s61, s57, s26
	s_cselect_b32 s60, s56, s20
	s_add_i32 s27, s21, 0x100
	v_add_u32_e32 v2, s27, v144
	ds_read_b128 v[162:165], v2
	ds_read_b128 v[166:169], v2 offset:1024
	ds_read_b128 v[170:173], v2 offset:2048
	ds_read_b128 v[174:177], v2 offset:3072
	v_lshl_add_u64 v[142:143], s[38:39], 0, v[140:141]
	s_add_i32 m0, s23, 0xc000
	global_load_lds_dwordx4 v[142:143], off
	v_lshl_add_u64 v[142:143], s[38:39], 0, v[138:139]
	s_add_i32 m0, s23, 0xe000
	s_nop 0
	global_load_lds_dwordx4 v[142:143], off
	s_waitcnt vmcnt(8)
	s_waitcnt lgkmcnt(0)
	s_barrier
	s_setprio 1
	s_waitcnt lgkmcnt(0)
	v_mfma_f32_16x16x32_bf16 v[124:127], v[146:149], v[178:181], v[124:127]
	v_mfma_f32_16x16x32_bf16 v[128:131], v[154:157], v[178:181], v[128:131]
	v_mfma_f32_16x16x32_bf16 v[112:115], v[146:149], v[198:201], v[112:115]
	v_mfma_f32_16x16x32_bf16 v[108:111], v[154:157], v[198:201], v[108:111]
	v_mfma_f32_16x16x32_bf16 v[96:99], v[146:149], v[206:209], v[96:99]
	v_mfma_f32_16x16x32_bf16 v[92:95], v[154:157], v[206:209], v[92:95]
	v_mfma_f32_16x16x32_bf16 v[80:83], v[146:149], v[224:227], v[80:83]
	v_mfma_f32_16x16x32_bf16 v[76:79], v[154:157], v[224:227], v[76:79]
	v_mfma_f32_16x16x32_bf16 v[124:127], v[150:153], v[194:197], v[124:127]
	v_mfma_f32_16x16x32_bf16 v[128:131], v[158:161], v[194:197], v[128:131]
	v_mfma_f32_16x16x32_bf16 v[112:115], v[150:153], v[202:205], v[112:115]
	v_mfma_f32_16x16x32_bf16 v[108:111], v[158:161], v[202:205], v[108:111]
	v_mfma_f32_16x16x32_bf16 v[96:99], v[150:153], v[220:223], v[96:99]
	v_mfma_f32_16x16x32_bf16 v[92:95], v[158:161], v[220:223], v[92:95]
	v_mfma_f32_16x16x32_bf16 v[80:83], v[150:153], v[228:231], v[80:83]
	v_mfma_f32_16x16x32_bf16 v[76:79], v[158:161], v[228:231], v[76:79]
	s_setprio 0
	s_setprio 1
	v_mfma_f32_16x16x32_bf16 v[120:123], v[162:165], v[178:181], v[120:123]
	v_mfma_f32_16x16x32_bf16 v[116:119], v[170:173], v[178:181], v[116:119]
	v_mfma_f32_16x16x32_bf16 v[104:107], v[162:165], v[198:201], v[104:107]
	v_mfma_f32_16x16x32_bf16 v[100:103], v[170:173], v[198:201], v[100:103]
	v_mfma_f32_16x16x32_bf16 v[88:91], v[162:165], v[206:209], v[88:91]
	v_mfma_f32_16x16x32_bf16 v[84:87], v[170:173], v[206:209], v[84:87]
	v_mfma_f32_16x16x32_bf16 v[72:75], v[162:165], v[224:227], v[72:75]
	v_mfma_f32_16x16x32_bf16 v[68:71], v[170:173], v[224:227], v[68:71]
	v_mfma_f32_16x16x32_bf16 v[120:123], v[166:169], v[194:197], v[120:123]
	v_mfma_f32_16x16x32_bf16 v[116:119], v[174:177], v[194:197], v[116:119]
	v_mfma_f32_16x16x32_bf16 v[104:107], v[166:169], v[202:205], v[104:107]
	v_mfma_f32_16x16x32_bf16 v[100:103], v[174:177], v[202:205], v[100:103]
	v_mfma_f32_16x16x32_bf16 v[88:91], v[166:169], v[220:223], v[88:91]
	v_mfma_f32_16x16x32_bf16 v[84:87], v[174:177], v[220:223], v[84:87]
	v_mfma_f32_16x16x32_bf16 v[72:75], v[166:169], v[228:231], v[72:75]
	v_mfma_f32_16x16x32_bf16 v[68:71], v[174:177], v[228:231], v[68:71]
	s_setprio 0
	s_barrier
	s_add_i32 s28, s59, s11
	v_lshl_add_u64 v[142:143], s[60:61], 0, v[132:133]
	s_mov_b32 m0, s28
	ds_read_b128 v[178:181], v145 offset:16384
	ds_read_b128 v[194:197], v145 offset:17408
	ds_read_b128 v[198:201], v145 offset:18432
	ds_read_b128 v[202:205], v145 offset:19456
	ds_read_b128 v[206:209], v145 offset:20480
	ds_read_b128 v[220:223], v145 offset:21504
	ds_read_b128 v[224:227], v145 offset:22528
	ds_read_b128 v[228:231], v145 offset:23552
	global_load_lds_dwordx4 v[142:143], off
	s_add_i32 m0, s28, 0x2000
	v_lshl_add_u64 v[182:183], s[60:61], 0, v[136:137]
	s_add_u32 s60, s60, s36
	s_addc_u32 s61, s61, s37
	s_add_i32 s27, s27, s11
	global_load_lds_dwordx4 v[182:183], off
	v_lshl_add_u64 v[210:211], s[60:61], 0, v[132:133]
	s_mov_b32 m0, s27
	v_lshl_add_u64 v[232:233], s[60:61], 0, v[136:137]
	global_load_lds_dwordx4 v[210:211], off
	s_add_i32 m0, s27, 0x2000
	v_lshl_add_u64 v[234:235], s[50:51], 0, v[0:1]
	global_load_lds_dwordx4 v[232:233], off
	s_mov_b32 m0, s23
	v_lshl_add_u64 v[236:237], s[50:51], 0, v[134:135]
	global_load_lds_dwordx4 v[234:235], off
	s_mov_b32 m0, s25
	s_nop 0
	global_load_lds_dwordx4 v[236:237], off
	s_waitcnt vmcnt(8)
	s_waitcnt lgkmcnt(0)
	s_barrier
; #define PG8_STAGE(bufoff, gbase, voff) do { _Pragma("unroll") for (int _i = 0; _i < 2; ++_i) \
;         __builtin_amdgcn_global_load_lds((const unsigned*)((const char*)(gbase) + (voff)[_i]), (PG8_LAS unsigned*)(lds + (bufoff) + ldsw + _i * 8192), 16, 0, 0); } while (0)
; #define PG8_LDA(dst, b, h) do { _Pragma("unroll") for (int m = 0; m < 4; ++m) _Pragma("unroll") for (int k = 0; k < 2; ++k) dst[m][k] = *(const PG8_LAS bf16x8*)(lds + PG8_SA(b, h) + aoff + m * 2048 + k * 1024); } while (0)
; #define PG8_LDB(dst, b, h) do { _Pragma("unroll") for (int n = 0; n < 2; ++n) _Pragma("unroll") for (int k = 0; k < 2; ++k) dst[n][k] = *(const PG8_LAS bf16x8*)(lds + PG8_SB(b, h) + boff + n * 2048 + k * 1024); } while (0)
; #define PG8_MMA(ai, bj, At, Bt) do { __builtin_amdgcn_s_setprio(1); _Pragma("unroll") for (int m = 0; m < 4; ++m) _Pragma("unroll") for (int n = 0; n < 2; ++n) _Pragma("unroll") for (int k = 0; k < 2; ++k) \
;         acc[ai][bj][m][n] = __builtin_amdgcn_mfma_f32_16x16x32_bf16(Bt[n][k], At[m][k], acc[ai][bj][m][n], 0, 0, 0); __builtin_amdgcn_s_setprio(0); } while (0)
; #define PG8_WAIT_V(n) asm volatile("s_waitcnt vmcnt(" #n ")" ::: "memory")
; #define PG8_WAIT_L(n) asm volatile("s_waitcnt lgkmcnt(" #n ")" ::: "memory")
; #define PG8_BAR __builtin_amdgcn_s_barrier()
; #define PG8_SCHED __builtin_amdgcn_sched_barrier(0)
; template <class Epi, class Sched, bool ALIGN_EPI = false, bool SP2 = false>
; __device__ __forceinline__ void gemm_phase(PG8_LAS unsigned char* lds, const Gemm g, const Sched& S, const Epi& E) {
;     ...
;             PG8_WAIT_V(8); PG8_WAIT_L(0); PG8_BAR; PG8_MMA(1, 0, At, B0); PG8_MMA(1, 1, At, B1); PG8_BAR; PG8_SCHED;
;             PG8_LDB(B0, 1, 0); PG8_LDB(B1, 1, 1); PG8_SCHED; PG8_LDA(At, 1, 0); PG8_STAGE(PG8_SA(0, 1), a2 + hstep, voffA);
;             PG8_WAIT_V(8); PG8_WAIT_L(0); PG8_BAR; PG8_MMA(0, 0, At, B0); PG8_MMA(0, 1, At, B1); PG8_BAR; PG8_SCHED;
	s_setprio 1
	s_waitcnt lgkmcnt(0)
	v_mfma_f32_16x16x32_bf16 v[64:67], v[146:149], v[178:181], v[64:67]
	v_mfma_f32_16x16x32_bf16 v[60:63], v[154:157], v[178:181], v[60:63]
	v_mfma_f32_16x16x32_bf16 v[48:51], v[146:149], v[198:201], v[48:51]
	v_mfma_f32_16x16x32_bf16 v[44:47], v[154:157], v[198:201], v[44:47]
	v_mfma_f32_16x16x32_bf16 v[32:35], v[146:149], v[206:209], v[32:35]
	v_mfma_f32_16x16x32_bf16 v[28:31], v[154:157], v[206:209], v[28:31]
	v_mfma_f32_16x16x32_bf16 v[16:19], v[146:149], v[224:227], v[16:19]
	v_mfma_f32_16x16x32_bf16 v[12:15], v[154:157], v[224:227], v[12:15]
	v_mfma_f32_16x16x32_bf16 v[64:67], v[150:153], v[194:197], v[64:67]
	v_mfma_f32_16x16x32_bf16 v[60:63], v[158:161], v[194:197], v[60:63]
	v_mfma_f32_16x16x32_bf16 v[48:51], v[150:153], v[202:205], v[48:51]
	v_mfma_f32_16x16x32_bf16 v[44:47], v[158:161], v[202:205], v[44:47]
	v_mfma_f32_16x16x32_bf16 v[32:35], v[150:153], v[220:223], v[32:35]
	v_mfma_f32_16x16x32_bf16 v[28:31], v[158:161], v[220:223], v[28:31]
	v_mfma_f32_16x16x32_bf16 v[16:19], v[150:153], v[228:231], v[16:19]
	v_mfma_f32_16x16x32_bf16 v[12:15], v[158:161], v[228:231], v[12:15]
	s_setprio 0
	s_setprio 1
	v_mfma_f32_16x16x32_bf16 v[56:59], v[162:165], v[178:181], v[56:59]
	v_mfma_f32_16x16x32_bf16 v[52:55], v[170:173], v[178:181], v[52:55]
	v_mfma_f32_16x16x32_bf16 v[40:43], v[162:165], v[198:201], v[40:43]
	v_mfma_f32_16x16x32_bf16 v[36:39], v[170:173], v[198:201], v[36:39]
	v_mfma_f32_16x16x32_bf16 v[24:27], v[162:165], v[206:209], v[24:27]
	v_mfma_f32_16x16x32_bf16 v[20:23], v[170:173], v[206:209], v[20:23]
	v_mfma_f32_16x16x32_bf16 v[8:11], v[162:165], v[224:227], v[8:11]
	v_mfma_f32_16x16x32_bf16 v[4:7], v[170:173], v[224:227], v[4:7]
	v_mfma_f32_16x16x32_bf16 v[56:59], v[166:169], v[194:197], v[56:59]
	v_mfma_f32_16x16x32_bf16 v[52:55], v[174:177], v[194:197], v[52:55]
	v_mfma_f32_16x16x32_bf16 v[40:43], v[166:169], v[202:205], v[40:43]
	v_mfma_f32_16x16x32_bf16 v[36:39], v[174:177], v[202:205], v[36:39]
	v_mfma_f32_16x16x32_bf16 v[24:27], v[166:169], v[220:223], v[24:27]
	v_mfma_f32_16x16x32_bf16 v[20:23], v[174:177], v[220:223], v[20:23]
	v_mfma_f32_16x16x32_bf16 v[8:11], v[166:169], v[228:231], v[8:11]
	v_mfma_f32_16x16x32_bf16 v[4:7], v[174:177], v[228:231], v[4:7]
	s_setprio 0
	s_barrier
	s_add_i32 s27, s82, 0x100
	v_add_u32_e32 v2, s27, v144
	s_add_i32 s28, s78, 0x100
	ds_read_b128 v[146:149], v2
	ds_read_b128 v[150:153], v2 offset:1024
	ds_read_b128 v[154:157], v2 offset:2048
	ds_read_b128 v[158:161], v2 offset:3072
	v_add_u32_e32 v2, s28, v144
	ds_read_b128 v[162:165], v2
	ds_read_b128 v[166:169], v2 offset:1024
	ds_read_b128 v[170:173], v2 offset:2048
	ds_read_b128 v[174:177], v2 offset:3072
	s_add_u32 s50, s50, s36
	s_addc_u32 s51, s51, s37
	s_mov_b32 m0, s30
	v_lshl_add_u64 v[238:239], s[50:51], 0, v[0:1]
	ds_read_b128 v[178:181], v145 offset:32768
	ds_read_b128 v[194:197], v145 offset:33792
	ds_read_b128 v[198:201], v145 offset:34816
	ds_read_b128 v[202:205], v145 offset:35840
	ds_read_b128 v[206:209], v145 offset:36864
	ds_read_b128 v[220:223], v145 offset:37888
	ds_read_b128 v[224:227], v145 offset:38912
	ds_read_b128 v[228:231], v145 offset:39936
	global_load_lds_dwordx4 v[238:239], off
	v_lshl_add_u64 v[238:239], s[50:51], 0, v[134:135]
	s_mov_b32 m0, s64
	s_nop 0
	global_load_lds_dwordx4 v[238:239], off
	s_waitcnt vmcnt(8)
	s_waitcnt lgkmcnt(0)
	s_barrier
	s_setprio 1
	s_waitcnt lgkmcnt(0)
	v_mfma_f32_16x16x32_bf16 v[124:127], v[146:149], v[178:181], v[124:127]
	v_mfma_f32_16x16x32_bf16 v[128:131], v[154:157], v[178:181], v[128:131]
	v_mfma_f32_16x16x32_bf16 v[112:115], v[146:149], v[198:201], v[112:115]
	v_mfma_f32_16x16x32_bf16 v[108:111], v[154:157], v[198:201], v[108:111]
	v_mfma_f32_16x16x32_bf16 v[96:99], v[146:149], v[206:209], v[96:99]
	v_mfma_f32_16x16x32_bf16 v[92:95], v[154:157], v[206:209], v[92:95]
	v_mfma_f32_16x16x32_bf16 v[80:83], v[146:149], v[224:227], v[80:83]
	v_mfma_f32_16x16x32_bf16 v[76:79], v[154:157], v[224:227], v[76:79]
	v_mfma_f32_16x16x32_bf16 v[124:127], v[150:153], v[194:197], v[124:127]
	v_mfma_f32_16x16x32_bf16 v[128:131], v[158:161], v[194:197], v[128:131]
	v_mfma_f32_16x16x32_bf16 v[112:115], v[150:153], v[202:205], v[112:115]
	v_mfma_f32_16x16x32_bf16 v[108:111], v[158:161], v[202:205], v[108:111]
	v_mfma_f32_16x16x32_bf16 v[96:99], v[150:153], v[220:223], v[96:99]
	v_mfma_f32_16x16x32_bf16 v[92:95], v[158:161], v[220:223], v[92:95]
	v_mfma_f32_16x16x32_bf16 v[80:83], v[150:153], v[228:231], v[80:83]
	v_mfma_f32_16x16x32_bf16 v[76:79], v[158:161], v[228:231], v[76:79]
	s_setprio 0
	s_setprio 1
	v_mfma_f32_16x16x32_bf16 v[120:123], v[162:165], v[178:181], v[120:123]
	v_mfma_f32_16x16x32_bf16 v[116:119], v[170:173], v[178:181], v[116:119]
	v_mfma_f32_16x16x32_bf16 v[104:107], v[162:165], v[198:201], v[104:107]
	v_mfma_f32_16x16x32_bf16 v[100:103], v[170:173], v[198:201], v[100:103]
	v_mfma_f32_16x16x32_bf16 v[88:91], v[162:165], v[206:209], v[88:91]
	v_mfma_f32_16x16x32_bf16 v[84:87], v[170:173], v[206:209], v[84:87]
	v_mfma_f32_16x16x32_bf16 v[72:75], v[162:165], v[224:227], v[72:75]
	v_mfma_f32_16x16x32_bf16 v[68:71], v[170:173], v[224:227], v[68:71]
	v_mfma_f32_16x16x32_bf16 v[120:123], v[166:169], v[194:197], v[120:123]
	v_mfma_f32_16x16x32_bf16 v[116:119], v[174:177], v[194:197], v[116:119]
	v_mfma_f32_16x16x32_bf16 v[104:107], v[166:169], v[202:205], v[104:107]
	v_mfma_f32_16x16x32_bf16 v[100:103], v[174:177], v[202:205], v[100:103]
	v_mfma_f32_16x16x32_bf16 v[88:91], v[166:169], v[220:223], v[88:91]
	v_mfma_f32_16x16x32_bf16 v[84:87], v[174:177], v[220:223], v[84:87]
	v_mfma_f32_16x16x32_bf16 v[72:75], v[166:169], v[228:231], v[72:75]
	v_mfma_f32_16x16x32_bf16 v[68:71], v[174:177], v[228:231], v[68:71]
	s_setprio 0
	s_barrier
; #define PG8_STAGE(bufoff, gbase, voff) do { _Pragma("unroll") for (int _i = 0; _i < 2; ++_i) \
;         __builtin_amdgcn_global_load_lds((const unsigned*)((const char*)(gbase) + (voff)[_i]), (PG8_LAS unsigned*)(lds + (bufoff) + ldsw + _i * 8192), 16, 0, 0); } while (0)
; #define PG8_LDA(dst, b, h) do { _Pragma("unroll") for (int m = 0; m < 4; ++m) _Pragma("unroll") for (int k = 0; k < 2; ++k) dst[m][k] = *(const PG8_LAS bf16x8*)(lds + PG8_SA(b, h) + aoff + m * 2048 + k * 1024); } while (0)
; #define PG8_MMA(ai, bj, At, Bt) do { __builtin_amdgcn_s_setprio(1); _Pragma("unroll") for (int m = 0; m < 4; ++m) _Pragma("unroll") for (int n = 0; n < 2; ++n) _Pragma("unroll") for (int k = 0; k < 2; ++k) \
;         acc[ai][bj][m][n] = __builtin_amdgcn_mfma_f32_16x16x32_bf16(Bt[n][k], At[m][k], acc[ai][bj][m][n], 0, 0, 0); __builtin_amdgcn_s_setprio(0); } while (0)
; #define PG8_WAIT_V(n) asm volatile("s_waitcnt vmcnt(" #n ")" ::: "memory")
; #define PG8_WAIT_L(n) asm volatile("s_waitcnt lgkmcnt(" #n ")" ::: "memory")
; #define PG8_BAR __builtin_amdgcn_s_barrier()
; #define PG8_SCHED __builtin_amdgcn_sched_barrier(0)
; template <class Epi, class Sched, bool ALIGN_EPI = false, bool SP2 = false>
; __device__ __forceinline__ void gemm_phase(PG8_LAS unsigned char* lds, const Gemm g, const Sched& S, const Epi& E) {
;     ...
;         for (int t = 0; t < nt; t += 2) {
;             const bool last = (t == nt - 2);
;     ...
;             PG8_LDA(At, 1, 1); PG8_STAGE(PG8_SB(1, 0), b3, voffB); PG8_STAGE(PG8_SB(1, 1), b3 + hstep, voffB); PG8_STAGE(PG8_SA(1, 0), a3, voffA);
;             PG8_WAIT_V(8); PG8_WAIT_L(0); PG8_BAR; PG8_MMA(1, 0, At, B0); PG8_MMA(1, 1, At, B1); PG8_BAR; PG8_SCHED;
	s_add_i32 s27, s27, s11
	v_lshl_add_u64 v[142:143], v[142:143], 0, s[8:9]
	s_mov_b32 m0, s27
	ds_read_b128 v[178:181], v145 offset:49152
	ds_read_b128 v[194:197], v145 offset:50176
	ds_read_b128 v[198:201], v145 offset:51200
	ds_read_b128 v[202:205], v145 offset:52224
	ds_read_b128 v[206:209], v145 offset:53248
	ds_read_b128 v[220:223], v145 offset:54272
	ds_read_b128 v[224:227], v145 offset:55296
	ds_read_b128 v[228:231], v145 offset:56320
	global_load_lds_dwordx4 v[142:143], off
	v_lshl_add_u64 v[142:143], v[182:183], 0, s[8:9]
	s_add_i32 m0, s27, 0x2000
	s_add_i32 s27, s28, s11
	global_load_lds_dwordx4 v[142:143], off
	v_lshl_add_u64 v[142:143], v[210:211], 0, s[8:9]
	s_mov_b32 m0, s27
	s_nop 0
	global_load_lds_dwordx4 v[142:143], off
	v_lshl_add_u64 v[142:143], v[232:233], 0, s[8:9]
	s_add_i32 m0, s27, 0x2000
	s_nop 0
	global_load_lds_dwordx4 v[142:143], off
	v_lshl_add_u64 v[142:143], v[234:235], 0, s[8:9]
	s_mov_b32 m0, s65
	s_nop 0
	global_load_lds_dwordx4 v[142:143], off
	v_lshl_add_u64 v[142:143], v[236:237], 0, s[8:9]
	s_mov_b32 m0, s66
	s_nop 0
	global_load_lds_dwordx4 v[142:143], off
	s_waitcnt vmcnt(8)
	s_waitcnt lgkmcnt(0)
	s_barrier
	s_setprio 1
	s_waitcnt lgkmcnt(0)
	v_mfma_f32_16x16x32_bf16 v[64:67], v[146:149], v[178:181], v[64:67]
	v_mfma_f32_16x16x32_bf16 v[60:63], v[154:157], v[178:181], v[60:63]
	v_mfma_f32_16x16x32_bf16 v[48:51], v[146:149], v[198:201], v[48:51]
	v_mfma_f32_16x16x32_bf16 v[44:47], v[154:157], v[198:201], v[44:47]
	v_mfma_f32_16x16x32_bf16 v[32:35], v[146:149], v[206:209], v[32:35]
	v_mfma_f32_16x16x32_bf16 v[28:31], v[154:157], v[206:209], v[28:31]
	v_mfma_f32_16x16x32_bf16 v[16:19], v[146:149], v[224:227], v[16:19]
	v_mfma_f32_16x16x32_bf16 v[12:15], v[154:157], v[224:227], v[12:15]
	v_mfma_f32_16x16x32_bf16 v[64:67], v[150:153], v[194:197], v[64:67]
	v_mfma_f32_16x16x32_bf16 v[60:63], v[158:161], v[194:197], v[60:63]
	v_mfma_f32_16x16x32_bf16 v[48:51], v[150:153], v[202:205], v[48:51]
	v_mfma_f32_16x16x32_bf16 v[44:47], v[158:161], v[202:205], v[44:47]
	v_mfma_f32_16x16x32_bf16 v[32:35], v[150:153], v[220:223], v[32:35]
	v_mfma_f32_16x16x32_bf16 v[28:31], v[158:161], v[220:223], v[28:31]
	v_mfma_f32_16x16x32_bf16 v[16:19], v[150:153], v[228:231], v[16:19]
	v_mfma_f32_16x16x32_bf16 v[12:15], v[158:161], v[228:231], v[12:15]
	s_setprio 0
	s_setprio 1
	v_mfma_f32_16x16x32_bf16 v[56:59], v[162:165], v[178:181], v[56:59]
	v_mfma_f32_16x16x32_bf16 v[52:55], v[170:173], v[178:181], v[52:55]
	v_mfma_f32_16x16x32_bf16 v[40:43], v[162:165], v[198:201], v[40:43]
	v_mfma_f32_16x16x32_bf16 v[36:39], v[170:173], v[198:201], v[36:39]
	v_mfma_f32_16x16x32_bf16 v[24:27], v[162:165], v[206:209], v[24:27]
	v_mfma_f32_16x16x32_bf16 v[20:23], v[170:173], v[206:209], v[20:23]
	v_mfma_f32_16x16x32_bf16 v[8:11], v[162:165], v[224:227], v[8:11]
	v_mfma_f32_16x16x32_bf16 v[4:7], v[170:173], v[224:227], v[4:7]
	v_mfma_f32_16x16x32_bf16 v[56:59], v[166:169], v[194:197], v[56:59]
	v_mfma_f32_16x16x32_bf16 v[52:55], v[174:177], v[194:197], v[52:55]
	v_mfma_f32_16x16x32_bf16 v[40:43], v[166:169], v[202:205], v[40:43]
	v_mfma_f32_16x16x32_bf16 v[36:39], v[174:177], v[202:205], v[36:39]
	v_mfma_f32_16x16x32_bf16 v[24:27], v[166:169], v[220:223], v[24:27]
	v_mfma_f32_16x16x32_bf16 v[20:23], v[174:177], v[220:223], v[20:23]
	v_mfma_f32_16x16x32_bf16 v[8:11], v[166:169], v[228:231], v[8:11]
	v_mfma_f32_16x16x32_bf16 v[4:7], v[174:177], v[228:231], v[4:7]
	s_add_u32 s20, s20, 0x100
	s_addc_u32 s26, s26, 0
	s_add_u32 s38, s38, 0x100
	s_addc_u32 s39, s39, 0
	s_cmp_ge_i32 s58, s69
	s_mov_b32 s27, s58
	s_setprio 0
	s_barrier
	s_cbranch_scc0 .LBB0_530
